# gMLP tiles: the two 256-thread halves of a workgroup (same 128-token chunk) split the LayerNorm-statistics pass and exchange partial sums through LDS (one extra barrier per tile)
# speedup vs baseline: 1.0564x; 1.0038x over previous
.LBB0_618:
	s_andn2_b64 vcc, exec, s[0:1]
	s_cbranch_vccnz .LBB0_639
	s_cmpk_gt_i32 s10, 0x7f
	s_cbranch_scc0 .LBB0_625
	s_add_i32 s38, s10, 0xffffff80
	s_lshl_b32 s0, s38, 5
	v_mov_b32_e32 v50, v194
	v_readlane_b32 s40, v251, 54
	s_and_b32 s4, s0, 0x7fffff80
	v_readlane_b32 s46, v251, 60
	v_bfe_u32 v31, v50, 1, 7
	v_readlane_b32 s47, v251, 61
	v_and_b32_e32 v18, 1, v50
	v_or_b32_e32 v0, s4, v31
	v_mov_b64_e32 v[2:3], s[46:47]
	v_mad_u64_u32 v[10:11], s[0:1], v0, s3, v[2:3]
	v_lshlrev_b32_e32 v0, 9, v18
	v_mov_b32_e32 v14, 0
	v_lshrrev_b32_e32 v30, 1, v50
	v_lshl_add_u64 v[12:13], v[10:11], 0, v[0:1]
	v_readfirstlane_b32 s64, v194
	s_lshr_b32 s64, s64, 8
	s_lshl_b32 s0, s64, 8
	s_mov_b32 s1, 0
	s_add_i32 s65, s0, 0x100
	v_mov_b32_e32 v15, v14
	v_readlane_b32 s41, v251, 55
	v_readlane_b32 s42, v251, 56
	v_readlane_b32 s43, v251, 57
	v_readlane_b32 s44, v251, 58
	v_readlane_b32 s45, v251, 59
	v_readlane_b32 s48, v251, 62
	v_readlane_b32 s49, v251, 63
	v_readlane_b32 s50, v252, 0
	v_readlane_b32 s51, v252, 1
	v_readlane_b32 s52, v252, 2
	v_readlane_b32 s53, v252, 3
	v_readlane_b32 s54, v252, 4
	v_readlane_b32 s55, v252, 5
.LBB0_621:
	v_lshl_add_u64 v[16:17], v[12:13], 0, s[0:1]
	global_load_dwordx4 v[2:5], v[16:17], off offset:1072
	global_load_dwordx4 v[6:9], v[16:17], off offset:1056
	global_load_dwordx4 v[20:23], v[16:17], off offset:1040
	global_load_dwordx4 v[24:27], v[16:17], off offset:1024
	s_add_u32 s0, s0, 0x80
	s_addc_u32 s1, s1, 0
	s_cmp_lg_u32 s0, s65
	s_waitcnt vmcnt(0)
	v_lshlrev_b32_e32 v0, 16, v24
	v_mul_f32_e32 v19, v0, v0
	v_fmamk_f32 v19, v19, 0xbdd2d3e7, v129
	v_mul_f32_e32 v19, v19, v0
	v_exp_f32_e32 v19, v19
	v_and_b32_e32 v40, 0xffff0000, v27
	v_add_f32_e32 v19, 1.0, v19
	v_rcp_f32_e32 v19, v19
	s_nop 0
	v_mul_f32_e32 v29, v19, v0
	v_and_b32_e32 v0, 0xffff0000, v24
	v_mul_f32_e32 v19, v0, v0
	v_fmamk_f32 v19, v19, 0xbdd2d3e7, v129
	v_mul_f32_e32 v19, v19, v0
	v_exp_f32_e32 v19, v19
	v_mul_f32_e32 v28, v29, v29
	v_add_f32_e32 v19, 1.0, v19
	v_rcp_f32_e32 v19, v19
	s_nop 0
	v_mul_f32_e32 v33, v19, v0
	v_lshlrev_b32_e32 v0, 16, v25
	v_mul_f32_e32 v19, v0, v0
	v_fmamk_f32 v19, v19, 0xbdd2d3e7, v129
	v_mul_f32_e32 v19, v19, v0
	v_exp_f32_e32 v19, v19
	v_mul_f32_e32 v32, v33, v33
	v_add_f32_e32 v19, 1.0, v19
	v_rcp_f32_e32 v19, v19
	s_nop 0
	v_mul_f32_e32 v35, v19, v0
	v_and_b32_e32 v0, 0xffff0000, v25
	v_mul_f32_e32 v19, v0, v0
	v_fmamk_f32 v19, v19, 0xbdd2d3e7, v129
	v_mul_f32_e32 v19, v19, v0
	v_exp_f32_e32 v19, v19
	v_mul_f32_e32 v34, v35, v35
	v_add_f32_e32 v19, 1.0, v19
	v_rcp_f32_e32 v19, v19
	s_nop 0
	v_mul_f32_e32 v25, v19, v0
	v_lshlrev_b32_e32 v0, 16, v26
	v_mul_f32_e32 v19, v0, v0
	v_fmamk_f32 v19, v19, 0xbdd2d3e7, v129
	v_mul_f32_e32 v19, v19, v0
	v_exp_f32_e32 v19, v19
	v_mul_f32_e32 v24, v25, v25
	v_pk_add_f32 v[24:25], v[34:35], v[24:25]
	v_add_f32_e32 v19, 1.0, v19
	v_rcp_f32_e32 v19, v19
	s_nop 0
	v_mul_f32_e32 v37, v19, v0
	v_and_b32_e32 v0, 0xffff0000, v26
	v_mul_f32_e32 v19, v0, v0
	v_fmamk_f32 v19, v19, 0xbdd2d3e7, v129
	v_mul_f32_e32 v19, v19, v0
	v_exp_f32_e32 v19, v19
	v_mul_f32_e32 v26, v40, v40
	v_fmamk_f32 v26, v26, 0xbdd2d3e7, v129
	v_mul_f32_e32 v26, v26, v40
	v_add_f32_e32 v19, 1.0, v19
	v_rcp_f32_e32 v19, v19
	v_exp_f32_e32 v26, v26
	v_mul_f32_e32 v39, v19, v0
	v_lshlrev_b32_e32 v0, 16, v27
	v_mul_f32_e32 v19, v0, v0
	v_fmamk_f32 v19, v19, 0xbdd2d3e7, v129
	v_mul_f32_e32 v19, v19, v0
	v_exp_f32_e32 v19, v19
	v_add_f32_e32 v26, 1.0, v26
	v_rcp_f32_e32 v41, v26
	v_pk_add_f32 v[26:27], v[28:29], v[32:33]
	v_add_f32_e32 v19, 1.0, v19
	v_rcp_f32_e32 v19, v19
	v_mul_f32_e32 v36, v37, v37
	v_mul_f32_e32 v38, v39, v39
	v_pk_add_f32 v[14:15], v[14:15], v[26:27]
	v_mul_f32_e32 v27, v41, v40
	v_pk_add_f32 v[14:15], v[14:15], v[24:25]
	v_pk_add_f32 v[24:25], v[36:37], v[38:39]
	v_mul_f32_e32 v26, v27, v27
	v_pk_add_f32 v[14:15], v[14:15], v[24:25]
	v_mul_f32_e32 v25, v19, v0
	v_lshlrev_b32_e32 v0, 16, v20
	v_mul_f32_e32 v19, v0, v0
	v_fmamk_f32 v19, v19, 0xbdd2d3e7, v129
	v_mul_f32_e32 v19, v19, v0
	v_exp_f32_e32 v19, v19
	v_mul_f32_e32 v24, v25, v25
	v_pk_add_f32 v[24:25], v[24:25], v[26:27]
	v_and_b32_e32 v36, 0xffff0000, v23
	v_add_f32_e32 v19, 1.0, v19
	v_rcp_f32_e32 v19, v19
	v_pk_add_f32 v[14:15], v[14:15], v[24:25]
	v_mul_f32_e32 v25, v19, v0
	v_and_b32_e32 v0, 0xffff0000, v20
	v_mul_f32_e32 v19, v0, v0
	v_fmamk_f32 v19, v19, 0xbdd2d3e7, v129
	v_mul_f32_e32 v19, v19, v0
	v_exp_f32_e32 v19, v19
	v_mul_f32_e32 v24, v25, v25
	v_add_f32_e32 v19, 1.0, v19
	v_rcp_f32_e32 v19, v19
	s_nop 0
	v_mul_f32_e32 v27, v19, v0
	v_lshlrev_b32_e32 v0, 16, v21
	v_mul_f32_e32 v19, v0, v0
	v_fmamk_f32 v19, v19, 0xbdd2d3e7, v129
	v_mul_f32_e32 v19, v19, v0
	v_exp_f32_e32 v19, v19
	v_mul_f32_e32 v26, v27, v27
	v_add_f32_e32 v19, 1.0, v19
	v_rcp_f32_e32 v19, v19
	s_nop 0
	v_mul_f32_e32 v29, v19, v0
	v_and_b32_e32 v0, 0xffff0000, v21
	v_mul_f32_e32 v19, v0, v0
	v_fmamk_f32 v19, v19, 0xbdd2d3e7, v129
	v_mul_f32_e32 v19, v19, v0
	v_exp_f32_e32 v19, v19
	v_mul_f32_e32 v28, v29, v29
	v_add_f32_e32 v19, 1.0, v19
	v_rcp_f32_e32 v19, v19
	s_nop 0
	v_mul_f32_e32 v21, v19, v0
	v_lshlrev_b32_e32 v0, 16, v22
	v_mul_f32_e32 v19, v0, v0
	v_fmamk_f32 v19, v19, 0xbdd2d3e7, v129
	v_mul_f32_e32 v19, v19, v0
	v_exp_f32_e32 v19, v19
	v_mul_f32_e32 v20, v21, v21
	v_pk_add_f32 v[20:21], v[28:29], v[20:21]
	v_add_f32_e32 v19, 1.0, v19
	v_rcp_f32_e32 v19, v19
	s_nop 0
	v_mul_f32_e32 v33, v19, v0
	v_and_b32_e32 v0, 0xffff0000, v22
	v_mul_f32_e32 v19, v0, v0
	v_fmamk_f32 v19, v19, 0xbdd2d3e7, v129
	v_mul_f32_e32 v19, v19, v0
	v_exp_f32_e32 v19, v19
	v_mul_f32_e32 v22, v36, v36
	v_fmamk_f32 v22, v22, 0xbdd2d3e7, v129
	v_mul_f32_e32 v22, v22, v36
	v_add_f32_e32 v19, 1.0, v19
	v_rcp_f32_e32 v19, v19
	v_exp_f32_e32 v22, v22
	v_mul_f32_e32 v35, v19, v0
	v_lshlrev_b32_e32 v0, 16, v23
	v_mul_f32_e32 v19, v0, v0
	v_fmamk_f32 v19, v19, 0xbdd2d3e7, v129
	v_mul_f32_e32 v19, v19, v0
	v_exp_f32_e32 v19, v19
	v_add_f32_e32 v22, 1.0, v22
	v_rcp_f32_e32 v37, v22
	v_pk_add_f32 v[22:23], v[24:25], v[26:27]
	v_add_f32_e32 v19, 1.0, v19
	v_rcp_f32_e32 v19, v19
	v_mul_f32_e32 v32, v33, v33
	v_mul_f32_e32 v34, v35, v35
	v_pk_add_f32 v[14:15], v[14:15], v[22:23]
	v_mul_f32_e32 v23, v37, v36
	v_pk_add_f32 v[14:15], v[14:15], v[20:21]
	v_pk_add_f32 v[20:21], v[32:33], v[34:35]
	v_mul_f32_e32 v22, v23, v23
	v_pk_add_f32 v[14:15], v[14:15], v[20:21]
	v_mul_f32_e32 v21, v19, v0
	v_lshlrev_b32_e32 v0, 16, v6
	v_mul_f32_e32 v19, v0, v0
	v_fmamk_f32 v19, v19, 0xbdd2d3e7, v129
	v_mul_f32_e32 v19, v19, v0
	v_exp_f32_e32 v19, v19
	v_mul_f32_e32 v20, v21, v21
	v_pk_add_f32 v[20:21], v[20:21], v[22:23]
	v_and_b32_e32 v32, 0xffff0000, v9
	v_add_f32_e32 v19, 1.0, v19
	v_rcp_f32_e32 v19, v19
	v_pk_add_f32 v[14:15], v[14:15], v[20:21]
	v_mul_f32_e32 v21, v19, v0
	v_and_b32_e32 v0, 0xffff0000, v6
	v_mul_f32_e32 v6, v0, v0
	v_fmamk_f32 v6, v6, 0xbdd2d3e7, v129
	v_mul_f32_e32 v6, v6, v0
	v_exp_f32_e32 v6, v6
	v_mul_f32_e32 v20, v21, v21
	v_add_f32_e32 v6, 1.0, v6
	v_rcp_f32_e32 v6, v6
	s_nop 0
	v_mul_f32_e32 v23, v6, v0
	v_lshlrev_b32_e32 v0, 16, v7
	v_mul_f32_e32 v6, v0, v0
	v_fmamk_f32 v6, v6, 0xbdd2d3e7, v129
	v_mul_f32_e32 v6, v6, v0
	v_exp_f32_e32 v6, v6
	v_mul_f32_e32 v22, v23, v23
	v_add_f32_e32 v6, 1.0, v6
	v_rcp_f32_e32 v6, v6
	s_nop 0
	v_mul_f32_e32 v25, v6, v0
	v_and_b32_e32 v0, 0xffff0000, v7
	v_mul_f32_e32 v6, v0, v0
	v_fmamk_f32 v6, v6, 0xbdd2d3e7, v129
	v_mul_f32_e32 v6, v6, v0
	v_exp_f32_e32 v6, v6
	v_mul_f32_e32 v24, v25, v25
	v_add_f32_e32 v6, 1.0, v6
	v_rcp_f32_e32 v6, v6
	s_nop 0
	v_mul_f32_e32 v7, v6, v0
	v_lshlrev_b32_e32 v0, 16, v8
	v_mul_f32_e32 v19, v0, v0
	v_fmamk_f32 v19, v19, 0xbdd2d3e7, v129
	v_mul_f32_e32 v19, v19, v0
	v_exp_f32_e32 v19, v19
	v_mul_f32_e32 v6, v7, v7
	v_pk_add_f32 v[6:7], v[24:25], v[6:7]
	v_add_f32_e32 v19, 1.0, v19
	v_rcp_f32_e32 v19, v19
	s_nop 0
	v_mul_f32_e32 v27, v19, v0
	v_and_b32_e32 v0, 0xffff0000, v8
	v_mul_f32_e32 v8, v0, v0
	v_fmamk_f32 v8, v8, 0xbdd2d3e7, v129
	v_mul_f32_e32 v8, v8, v0
	v_exp_f32_e32 v8, v8
	v_mul_f32_e32 v26, v27, v27
	v_add_f32_e32 v8, 1.0, v8
	v_rcp_f32_e32 v8, v8
	s_nop 0
	v_mul_f32_e32 v29, v8, v0
	v_lshlrev_b32_e32 v0, 16, v9
	v_mul_f32_e32 v8, v0, v0
	v_fmamk_f32 v8, v8, 0xbdd2d3e7, v129
	v_mul_f32_e32 v8, v8, v0
	v_exp_f32_e32 v8, v8
	v_mul_f32_e32 v28, v29, v29
	v_add_f32_e32 v8, 1.0, v8
	v_rcp_f32_e32 v19, v8
	v_mul_f32_e32 v8, v32, v32
	v_fmamk_f32 v8, v8, 0xbdd2d3e7, v129
	v_mul_f32_e32 v8, v8, v32
	v_exp_f32_e32 v8, v8
	s_nop 0
	v_add_f32_e32 v8, 1.0, v8
	v_rcp_f32_e32 v33, v8
	v_pk_add_f32 v[8:9], v[20:21], v[22:23]
	s_nop 0
	v_pk_add_f32 v[8:9], v[14:15], v[8:9]
	v_mul_f32_e32 v15, v33, v32
	v_pk_add_f32 v[6:7], v[8:9], v[6:7]
	v_pk_add_f32 v[8:9], v[26:27], v[28:29]
	v_mul_f32_e32 v14, v15, v15
	v_pk_add_f32 v[6:7], v[6:7], v[8:9]
	v_mul_f32_e32 v9, v19, v0
	v_mul_f32_e32 v8, v9, v9
	v_pk_add_f32 v[8:9], v[8:9], v[14:15]
	v_lshlrev_b32_e32 v0, 16, v2
	v_pk_add_f32 v[6:7], v[6:7], v[8:9]
	v_mul_f32_e32 v8, v0, v0
	v_fmamk_f32 v8, v8, 0xbdd2d3e7, v129
	v_mul_f32_e32 v8, v8, v0
	v_exp_f32_e32 v8, v8
	v_and_b32_e32 v26, 0xffff0000, v5
	v_add_f32_e32 v8, 1.0, v8
	v_rcp_f32_e32 v8, v8
	s_nop 0
	v_mul_f32_e32 v9, v8, v0
	v_and_b32_e32 v0, 0xffff0000, v2
	v_mul_f32_e32 v2, v0, v0
	v_fmamk_f32 v2, v2, 0xbdd2d3e7, v129
	v_mul_f32_e32 v2, v2, v0
	v_exp_f32_e32 v2, v2
	v_mul_f32_e32 v8, v9, v9
	v_add_f32_e32 v2, 1.0, v2
	v_rcp_f32_e32 v2, v2
	s_nop 0
	v_mul_f32_e32 v15, v2, v0
	v_lshlrev_b32_e32 v0, 16, v3
	v_mul_f32_e32 v2, v0, v0
	v_fmamk_f32 v2, v2, 0xbdd2d3e7, v129
	v_mul_f32_e32 v2, v2, v0
	v_exp_f32_e32 v2, v2
	v_mul_f32_e32 v14, v15, v15
	v_add_f32_e32 v2, 1.0, v2
	v_rcp_f32_e32 v2, v2
	s_nop 0
	v_mul_f32_e32 v21, v2, v0
	v_and_b32_e32 v0, 0xffff0000, v3
	v_mul_f32_e32 v2, v0, v0
	v_fmamk_f32 v2, v2, 0xbdd2d3e7, v129
	v_mul_f32_e32 v2, v2, v0
	v_exp_f32_e32 v2, v2
	v_mul_f32_e32 v20, v21, v21
	v_add_f32_e32 v2, 1.0, v2
	v_rcp_f32_e32 v2, v2
	s_nop 0
	v_mul_f32_e32 v3, v2, v0
	v_lshlrev_b32_e32 v0, 16, v4
	v_mul_f32_e32 v19, v0, v0
	v_fmamk_f32 v19, v19, 0xbdd2d3e7, v129
	v_mul_f32_e32 v19, v19, v0
	v_exp_f32_e32 v19, v19
	v_mul_f32_e32 v2, v3, v3
	v_pk_add_f32 v[2:3], v[20:21], v[2:3]
	v_add_f32_e32 v19, 1.0, v19
	v_rcp_f32_e32 v19, v19
	s_nop 0
	v_mul_f32_e32 v23, v19, v0
	v_and_b32_e32 v0, 0xffff0000, v4
	v_mul_f32_e32 v4, v0, v0
	v_fmamk_f32 v4, v4, 0xbdd2d3e7, v129
	v_mul_f32_e32 v4, v4, v0
	v_exp_f32_e32 v4, v4
	v_mul_f32_e32 v22, v23, v23
	v_add_f32_e32 v4, 1.0, v4
	v_rcp_f32_e32 v4, v4
	s_nop 0
	v_mul_f32_e32 v25, v4, v0
	v_lshlrev_b32_e32 v0, 16, v5
	v_mul_f32_e32 v4, v0, v0
	v_fmamk_f32 v4, v4, 0xbdd2d3e7, v129
	v_mul_f32_e32 v4, v4, v0
	v_exp_f32_e32 v4, v4
	v_mul_f32_e32 v24, v25, v25
	v_add_f32_e32 v4, 1.0, v4
	v_rcp_f32_e32 v19, v4
	v_mul_f32_e32 v4, v26, v26
	v_fmamk_f32 v4, v4, 0xbdd2d3e7, v129
	v_mul_f32_e32 v4, v4, v26
	v_exp_f32_e32 v4, v4
	s_nop 0
	v_add_f32_e32 v4, 1.0, v4
	v_rcp_f32_e32 v27, v4
	v_pk_add_f32 v[4:5], v[8:9], v[14:15]
	s_nop 0
	v_pk_add_f32 v[4:5], v[6:7], v[4:5]
	v_mul_f32_e32 v7, v27, v26
	v_pk_add_f32 v[2:3], v[4:5], v[2:3]
	v_pk_add_f32 v[4:5], v[22:23], v[24:25]
	v_mul_f32_e32 v6, v7, v7
	v_pk_add_f32 v[2:3], v[2:3], v[4:5]
	v_mul_f32_e32 v5, v19, v0
	v_mul_f32_e32 v4, v5, v5
	v_pk_add_f32 v[4:5], v[4:5], v[6:7]
	s_nop 0
	v_pk_add_f32 v[24:25], v[2:3], v[4:5]
	global_load_dwordx4 v[2:5], v[16:17], off offset:1136
	global_load_dwordx4 v[6:9], v[16:17], off offset:1120
	global_load_dwordx4 v[20:23], v[16:17], off offset:1104
	s_nop 0
	global_load_dwordx4 v[14:17], v[16:17], off offset:1088
	s_waitcnt vmcnt(0)
	v_lshlrev_b32_e32 v0, 16, v14
	v_mul_f32_e32 v19, v0, v0
	v_fmamk_f32 v19, v19, 0xbdd2d3e7, v129
	v_mul_f32_e32 v19, v19, v0
	v_exp_f32_e32 v19, v19
	v_and_b32_e32 v38, 0xffff0000, v17
	v_add_f32_e32 v19, 1.0, v19
	v_rcp_f32_e32 v19, v19
	s_nop 0
	v_mul_f32_e32 v27, v19, v0
	v_and_b32_e32 v0, 0xffff0000, v14
	v_mul_f32_e32 v14, v0, v0
	v_fmamk_f32 v14, v14, 0xbdd2d3e7, v129
	v_mul_f32_e32 v14, v14, v0
	v_exp_f32_e32 v14, v14
	v_mul_f32_e32 v26, v27, v27
	v_add_f32_e32 v14, 1.0, v14
	v_rcp_f32_e32 v14, v14
	s_nop 0
	v_mul_f32_e32 v29, v14, v0
	v_lshlrev_b32_e32 v0, 16, v15
	v_mul_f32_e32 v14, v0, v0
	v_fmamk_f32 v14, v14, 0xbdd2d3e7, v129
	v_mul_f32_e32 v14, v14, v0
	v_exp_f32_e32 v14, v14
	v_mul_f32_e32 v28, v29, v29
	v_add_f32_e32 v14, 1.0, v14
	v_rcp_f32_e32 v14, v14
	s_nop 0
	v_mul_f32_e32 v33, v14, v0
	v_and_b32_e32 v0, 0xffff0000, v15
	v_mul_f32_e32 v14, v0, v0
	v_fmamk_f32 v14, v14, 0xbdd2d3e7, v129
	v_mul_f32_e32 v14, v14, v0
	v_exp_f32_e32 v14, v14
	v_mul_f32_e32 v32, v33, v33
	v_add_f32_e32 v14, 1.0, v14
	v_rcp_f32_e32 v14, v14
	s_nop 0
	v_mul_f32_e32 v15, v14, v0
	v_lshlrev_b32_e32 v0, 16, v16
	v_mul_f32_e32 v19, v0, v0
	v_fmamk_f32 v19, v19, 0xbdd2d3e7, v129
	v_mul_f32_e32 v19, v19, v0
	v_exp_f32_e32 v19, v19
	v_mul_f32_e32 v14, v15, v15
	v_pk_add_f32 v[14:15], v[32:33], v[14:15]
	v_add_f32_e32 v19, 1.0, v19
	v_rcp_f32_e32 v19, v19
	s_nop 0
	v_mul_f32_e32 v35, v19, v0
	v_and_b32_e32 v0, 0xffff0000, v16
	v_mul_f32_e32 v16, v0, v0
	v_fmamk_f32 v16, v16, 0xbdd2d3e7, v129
	v_mul_f32_e32 v16, v16, v0
	v_exp_f32_e32 v16, v16
	v_mul_f32_e32 v34, v35, v35
	v_add_f32_e32 v16, 1.0, v16
	v_rcp_f32_e32 v16, v16
	s_nop 0
	v_mul_f32_e32 v37, v16, v0
	v_lshlrev_b32_e32 v0, 16, v17
	v_mul_f32_e32 v16, v0, v0
	v_fmamk_f32 v16, v16, 0xbdd2d3e7, v129
	v_mul_f32_e32 v16, v16, v0
	v_exp_f32_e32 v16, v16
	v_mul_f32_e32 v36, v37, v37
	v_add_f32_e32 v16, 1.0, v16
	v_rcp_f32_e32 v19, v16
	v_mul_f32_e32 v16, v38, v38
	v_fmamk_f32 v16, v16, 0xbdd2d3e7, v129
	v_mul_f32_e32 v16, v16, v38
	v_exp_f32_e32 v16, v16
	s_nop 0
	v_add_f32_e32 v16, 1.0, v16
	v_rcp_f32_e32 v39, v16
	v_pk_add_f32 v[16:17], v[26:27], v[28:29]
	s_nop 0
	v_pk_add_f32 v[16:17], v[24:25], v[16:17]
	v_mul_f32_e32 v25, v39, v38
	v_pk_add_f32 v[14:15], v[16:17], v[14:15]
	v_pk_add_f32 v[16:17], v[34:35], v[36:37]
	v_mul_f32_e32 v24, v25, v25
	v_pk_add_f32 v[14:15], v[14:15], v[16:17]
	v_mul_f32_e32 v17, v19, v0
	v_mul_f32_e32 v16, v17, v17
	v_pk_add_f32 v[16:17], v[16:17], v[24:25]
	v_lshlrev_b32_e32 v0, 16, v20
	v_pk_add_f32 v[14:15], v[14:15], v[16:17]
	v_mul_f32_e32 v16, v0, v0
	v_fmamk_f32 v16, v16, 0xbdd2d3e7, v129
	v_mul_f32_e32 v16, v16, v0
	v_exp_f32_e32 v16, v16
	s_nop 0
	v_add_f32_e32 v16, 1.0, v16
	v_rcp_f32_e32 v16, v16
	s_nop 0
	v_mul_f32_e32 v17, v16, v0
	v_and_b32_e32 v0, 0xffff0000, v20
	v_mul_f32_e32 v16, v0, v0
	v_fmamk_f32 v16, v16, 0xbdd2d3e7, v129
	v_mul_f32_e32 v16, v16, v0
	v_exp_f32_e32 v16, v16
	s_nop 0
	v_add_f32_e32 v16, 1.0, v16
	v_rcp_f32_e32 v16, v16
	s_nop 0
	v_mul_f32_e32 v25, v16, v0
	v_lshlrev_b32_e32 v0, 16, v21
	v_mul_f32_e32 v19, v0, v0
	v_fmamk_f32 v19, v19, 0xbdd2d3e7, v129
	v_mul_f32_e32 v19, v19, v0
	v_exp_f32_e32 v19, v19
	v_mul_f32_e32 v16, v17, v17
	v_mul_f32_e32 v24, v25, v25
	v_pk_add_f32 v[16:17], v[16:17], v[24:25]
	v_add_f32_e32 v19, 1.0, v19
	v_rcp_f32_e32 v19, v19
	v_pk_add_f32 v[14:15], v[14:15], v[16:17]
	v_mul_f32_e32 v27, v19, v0
	v_and_b32_e32 v0, 0xffff0000, v21
	v_mul_f32_e32 v19, v0, v0
	v_fmamk_f32 v19, v19, 0xbdd2d3e7, v129
	v_mul_f32_e32 v19, v19, v0
	v_exp_f32_e32 v19, v19
	v_mul_f32_e32 v26, v27, v27
	v_add_f32_e32 v19, 1.0, v19
	v_rcp_f32_e32 v19, v19
	s_nop 0
	v_mul_f32_e32 v21, v19, v0
	v_lshlrev_b32_e32 v0, 16, v22
	v_mul_f32_e32 v19, v0, v0
	v_fmamk_f32 v19, v19, 0xbdd2d3e7, v129
	v_mul_f32_e32 v19, v19, v0
	v_exp_f32_e32 v19, v19
	v_mul_f32_e32 v20, v21, v21
	v_pk_add_f32 v[16:17], v[26:27], v[20:21]
	v_add_f32_e32 v19, 1.0, v19
	v_rcp_f32_e32 v19, v19
	v_pk_add_f32 v[14:15], v[14:15], v[16:17]
	v_mul_f32_e32 v29, v19, v0
	v_and_b32_e32 v0, 0xffff0000, v22
	v_mul_f32_e32 v19, v0, v0
	v_fmamk_f32 v19, v19, 0xbdd2d3e7, v129
	v_mul_f32_e32 v19, v19, v0
	v_exp_f32_e32 v19, v19
	v_and_b32_e32 v22, 0xffff0000, v23
	v_mul_f32_e32 v28, v29, v29
	v_add_f32_e32 v19, 1.0, v19
	v_rcp_f32_e32 v19, v19
	s_nop 0
	v_mul_f32_e32 v33, v19, v0
	v_lshlrev_b32_e32 v0, 16, v23
	v_mul_f32_e32 v19, v0, v0
	v_mul_f32_e32 v23, v22, v22
	v_fmamk_f32 v19, v19, 0xbdd2d3e7, v129
	v_fmamk_f32 v23, v23, 0xbdd2d3e7, v129
	v_mul_f32_e32 v19, v19, v0
	v_mul_f32_e32 v23, v23, v22
	v_exp_f32_e32 v19, v19
	v_exp_f32_e32 v23, v23
	v_mul_f32_e32 v32, v33, v33
	v_pk_add_f32 v[16:17], v[28:29], v[32:33]
	v_add_f32_e32 v19, 1.0, v19
	v_add_f32_e32 v23, 1.0, v23
	v_rcp_f32_e32 v19, v19
	v_rcp_f32_e32 v23, v23
	v_pk_add_f32 v[14:15], v[14:15], v[16:17]
	v_and_b32_e32 v28, 0xffff0000, v9
	v_mul_f32_e32 v17, v19, v0
	v_mul_f32_e32 v21, v23, v22
	v_mul_f32_e32 v16, v17, v17
	v_mul_f32_e32 v20, v21, v21
	v_pk_add_f32 v[16:17], v[16:17], v[20:21]
	v_lshlrev_b32_e32 v0, 16, v6
	v_pk_add_f32 v[14:15], v[14:15], v[16:17]
	v_mul_f32_e32 v16, v0, v0
	v_fmamk_f32 v16, v16, 0xbdd2d3e7, v129
	v_mul_f32_e32 v16, v16, v0
	v_exp_f32_e32 v16, v16
	s_nop 0
	v_add_f32_e32 v16, 1.0, v16
	v_rcp_f32_e32 v16, v16
	s_nop 0
	v_mul_f32_e32 v17, v16, v0
	v_and_b32_e32 v0, 0xffff0000, v6
	v_mul_f32_e32 v6, v0, v0
	v_fmamk_f32 v6, v6, 0xbdd2d3e7, v129
	v_mul_f32_e32 v6, v6, v0
	v_exp_f32_e32 v6, v6
	v_mul_f32_e32 v16, v17, v17
	v_add_f32_e32 v6, 1.0, v6
	v_rcp_f32_e32 v6, v6
	s_nop 0
	v_mul_f32_e32 v21, v6, v0
	v_lshlrev_b32_e32 v0, 16, v7
	v_mul_f32_e32 v6, v0, v0
	v_fmamk_f32 v6, v6, 0xbdd2d3e7, v129
	v_mul_f32_e32 v6, v6, v0
	v_exp_f32_e32 v6, v6
	v_mul_f32_e32 v20, v21, v21
	v_add_f32_e32 v6, 1.0, v6
	v_rcp_f32_e32 v6, v6
	s_nop 0
	v_mul_f32_e32 v23, v6, v0
	v_and_b32_e32 v0, 0xffff0000, v7
	v_mul_f32_e32 v6, v0, v0
	v_fmamk_f32 v6, v6, 0xbdd2d3e7, v129
	v_mul_f32_e32 v6, v6, v0
	v_exp_f32_e32 v6, v6
	v_mul_f32_e32 v22, v23, v23
	v_add_f32_e32 v6, 1.0, v6
	v_rcp_f32_e32 v6, v6
	s_nop 0
	v_mul_f32_e32 v7, v6, v0
	v_lshlrev_b32_e32 v0, 16, v8
	v_mul_f32_e32 v19, v0, v0
	v_fmamk_f32 v19, v19, 0xbdd2d3e7, v129
	v_mul_f32_e32 v19, v19, v0
	v_exp_f32_e32 v19, v19
	v_mul_f32_e32 v6, v7, v7
	v_pk_add_f32 v[6:7], v[22:23], v[6:7]
	v_add_f32_e32 v19, 1.0, v19
	v_rcp_f32_e32 v19, v19
	s_nop 0
	v_mul_f32_e32 v25, v19, v0
	v_and_b32_e32 v0, 0xffff0000, v8
	v_mul_f32_e32 v8, v0, v0
	v_fmamk_f32 v8, v8, 0xbdd2d3e7, v129
	v_mul_f32_e32 v8, v8, v0
	v_exp_f32_e32 v8, v8
	v_mul_f32_e32 v24, v25, v25
	v_add_f32_e32 v8, 1.0, v8
	v_rcp_f32_e32 v8, v8
	s_nop 0
	v_mul_f32_e32 v27, v8, v0
	v_lshlrev_b32_e32 v0, 16, v9
	v_mul_f32_e32 v8, v0, v0
	v_fmamk_f32 v8, v8, 0xbdd2d3e7, v129
	v_mul_f32_e32 v8, v8, v0
	v_exp_f32_e32 v8, v8
	v_mul_f32_e32 v26, v27, v27
	v_add_f32_e32 v8, 1.0, v8
	v_rcp_f32_e32 v19, v8
	v_mul_f32_e32 v8, v28, v28
	v_fmamk_f32 v8, v8, 0xbdd2d3e7, v129
	v_mul_f32_e32 v8, v8, v28
	v_exp_f32_e32 v8, v8
	s_nop 0
	v_add_f32_e32 v8, 1.0, v8
	v_rcp_f32_e32 v29, v8
	v_pk_add_f32 v[8:9], v[16:17], v[20:21]
	s_nop 0
	v_pk_add_f32 v[8:9], v[14:15], v[8:9]
	v_mul_f32_e32 v15, v29, v28
	v_pk_add_f32 v[6:7], v[8:9], v[6:7]
	v_pk_add_f32 v[8:9], v[24:25], v[26:27]
	v_mul_f32_e32 v14, v15, v15
	v_pk_add_f32 v[6:7], v[6:7], v[8:9]
	v_mul_f32_e32 v9, v19, v0
	v_mul_f32_e32 v8, v9, v9
	v_pk_add_f32 v[8:9], v[8:9], v[14:15]
	v_lshlrev_b32_e32 v0, 16, v2
	v_pk_add_f32 v[6:7], v[6:7], v[8:9]
	v_mul_f32_e32 v8, v0, v0
	v_fmamk_f32 v8, v8, 0xbdd2d3e7, v129
	v_mul_f32_e32 v8, v8, v0
	v_exp_f32_e32 v8, v8
	v_and_b32_e32 v24, 0xffff0000, v5
	v_add_f32_e32 v8, 1.0, v8
	v_rcp_f32_e32 v8, v8
	s_nop 0
	v_mul_f32_e32 v9, v8, v0
	v_and_b32_e32 v0, 0xffff0000, v2
	v_mul_f32_e32 v2, v0, v0
	v_fmamk_f32 v2, v2, 0xbdd2d3e7, v129
	v_mul_f32_e32 v2, v2, v0
	v_exp_f32_e32 v2, v2
	v_mul_f32_e32 v8, v9, v9
	v_add_f32_e32 v2, 1.0, v2
	v_rcp_f32_e32 v2, v2
	s_nop 0
	v_mul_f32_e32 v15, v2, v0
	v_lshlrev_b32_e32 v0, 16, v3
	v_mul_f32_e32 v2, v0, v0
	v_fmamk_f32 v2, v2, 0xbdd2d3e7, v129
	v_mul_f32_e32 v2, v2, v0
	v_exp_f32_e32 v2, v2
	v_mul_f32_e32 v14, v15, v15
	v_add_f32_e32 v2, 1.0, v2
	v_rcp_f32_e32 v2, v2
	s_nop 0
	v_mul_f32_e32 v17, v2, v0
	v_and_b32_e32 v0, 0xffff0000, v3
	v_mul_f32_e32 v2, v0, v0
	v_fmamk_f32 v2, v2, 0xbdd2d3e7, v129
	v_mul_f32_e32 v2, v2, v0
	v_exp_f32_e32 v2, v2
	v_mul_f32_e32 v16, v17, v17
	v_add_f32_e32 v2, 1.0, v2
	v_rcp_f32_e32 v2, v2
	s_nop 0
	v_mul_f32_e32 v3, v2, v0
	v_lshlrev_b32_e32 v0, 16, v4
	v_mul_f32_e32 v19, v0, v0
	v_fmamk_f32 v19, v19, 0xbdd2d3e7, v129
	v_mul_f32_e32 v19, v19, v0
	v_exp_f32_e32 v19, v19
	v_mul_f32_e32 v2, v3, v3
	v_pk_add_f32 v[2:3], v[16:17], v[2:3]
	v_add_f32_e32 v19, 1.0, v19
	v_rcp_f32_e32 v19, v19
	s_nop 0
	v_mul_f32_e32 v21, v19, v0
	v_and_b32_e32 v0, 0xffff0000, v4
	v_mul_f32_e32 v4, v0, v0
	v_fmamk_f32 v4, v4, 0xbdd2d3e7, v129
	v_mul_f32_e32 v4, v4, v0
	v_exp_f32_e32 v4, v4
	v_mul_f32_e32 v20, v21, v21
	v_add_f32_e32 v4, 1.0, v4
	v_rcp_f32_e32 v4, v4
	s_nop 0
	v_mul_f32_e32 v23, v4, v0
	v_lshlrev_b32_e32 v0, 16, v5
	v_mul_f32_e32 v4, v0, v0
	v_fmamk_f32 v4, v4, 0xbdd2d3e7, v129
	v_mul_f32_e32 v4, v4, v0
	v_exp_f32_e32 v4, v4
	v_mul_f32_e32 v22, v23, v23
	v_add_f32_e32 v4, 1.0, v4
	v_rcp_f32_e32 v19, v4
	v_mul_f32_e32 v4, v24, v24
	v_fmamk_f32 v4, v4, 0xbdd2d3e7, v129
	v_mul_f32_e32 v4, v4, v24
	v_exp_f32_e32 v4, v4
	s_nop 0
	v_add_f32_e32 v4, 1.0, v4
	v_rcp_f32_e32 v25, v4
	v_pk_add_f32 v[4:5], v[8:9], v[14:15]
	s_nop 0
	v_pk_add_f32 v[4:5], v[6:7], v[4:5]
	v_mul_f32_e32 v7, v25, v24
	v_pk_add_f32 v[2:3], v[4:5], v[2:3]
	v_pk_add_f32 v[4:5], v[20:21], v[22:23]
	v_mul_f32_e32 v6, v7, v7
	v_pk_add_f32 v[2:3], v[2:3], v[4:5]
	v_mul_f32_e32 v5, v19, v0
	v_mul_f32_e32 v4, v5, v5
	v_pk_add_f32 v[4:5], v[4:5], v[6:7]
	s_nop 0
	v_pk_add_f32 v[14:15], v[2:3], v[4:5]
	s_cbranch_scc1 .LBB0_621
	v_and_b32_e32 v171, 0xff, v194
	v_lshlrev_b32_e32 v171, 3, v171
	s_mul_i32 s66, s64, 0x12000
	s_add_i32 s66, s66, 0x11000
	s_xor_b32 s67, s64, 1
	s_mul_i32 s67, s67, 0x12000
	s_add_i32 s67, s67, 0x11000
	v_add_u32_e32 v172, s66, v171
	v_add_u32_e32 v173, s67, v171
	ds_write_b64 v172, v[14:15]
	s_waitcnt lgkmcnt(0)
	s_barrier
	ds_read_b64 v[174:175], v173
	s_waitcnt lgkmcnt(0)
	v_add_f32_e32 v14, v14, v174
	v_add_f32_e32 v15, v15, v175
	v_readlane_b32 s0, v254, 51
	s_lshl_b32 s88, s0, 9
	v_readlane_b32 s40, v251, 6
	s_lshl_b64 s[6:7], s[88:89], 2
	v_readlane_b32 s52, v251, 18
	v_readlane_b32 s53, v251, 19
	s_add_u32 s1, s52, s6
	s_addc_u32 s2, s53, s7
	s_lshl_b32 s0, s10, 7
	s_and_b32 s0, s0, 0x180
	s_lshl_b32 s5, s0, 2
	s_add_u32 s16, s1, s5
	v_readlane_b32 s54, v251, 20
	s_addc_u32 s17, s2, 0
	v_readlane_b32 s55, v251, 21
	s_add_u32 s1, s54, s6
	s_addc_u32 s2, s55, s7
	s_add_u32 s20, s1, s5
	s_addc_u32 s21, s2, 0
	s_lshl_b32 s8, s0, 1
	s_mov_b32 s9, s89
	v_lshl_add_u64 v[2:3], v[10:11], 0, s[8:9]
	v_lshlrev_b32_e32 v0, 7, v18
	v_lshl_add_u64 v[22:23], v[2:3], 0, v[0:1]
	global_load_dwordx4 v[10:13], v[22:23], off offset:1024
	v_lshlrev_b32_e32 v20, 8, v18
	global_load_dwordx2 v[28:29], v20, s[16:17]
	global_load_dwordx2 v[36:37], v20, s[20:21]
	global_load_dwordx2 v[40:41], v20, s[16:17] offset:16
	global_load_dwordx2 v[42:43], v20, s[16:17] offset:32
	global_load_dwordx2 v[24:25], v20, s[16:17] offset:48
	global_load_dwordx2 v[44:45], v20, s[20:21] offset:16
	global_load_dwordx2 v[46:47], v20, s[20:21] offset:32
	global_load_dwordx2 v[26:27], v20, s[20:21] offset:48
	v_xor_b32_e32 v2, 1, v234
	v_cmp_lt_i32_e32 vcc, v2, v235
	s_mov_b32 s2, 0x3b000000
	v_lshlrev_b32_e32 v34, 6, v18
	v_cndmask_b32_e32 v2, v234, v2, vcc
	v_lshlrev_b32_e32 v80, 2, v2
	ds_bpermute_b32 v3, v80, v15
	ds_bpermute_b32 v2, v80, v14
	v_mul_u32_u24_e32 v4, 0x4400, v18
	v_lshlrev_b32_e32 v33, 1, v31
	s_mov_b32 s11, 0x800000
	v_add3_u32 v38, s15, v4, v33
	s_waitcnt lgkmcnt(0)
	v_pk_add_f32 v[2:3], v[14:15], v[2:3]
	v_or_b32_e32 v4, 1, v34
	v_pk_mul_f32 v[18:19], v[2:3], s[2:3] op_sel_hi:[1,0]
	v_mul_u32_u24_e32 v4, 0x110, v4
	v_fma_f32 v2, -v19, v19, v18
	v_max_f32_e32 v2, 0, v2
	v_add_f32_e32 v2, 0x358637bd, v2
	v_mul_f32_e32 v3, 0x4b800000, v2
	v_cmp_gt_f32_e32 vcc, s11, v2
	v_add3_u32 v35, s15, v4, v33
	v_or_b32_e32 v78, 7, v34
	v_cndmask_b32_e32 v2, v2, v3, vcc
	v_rsq_f32_e32 v18, v2
	global_load_dwordx4 v[14:17], v[22:23], off offset:1040
	global_load_dwordx4 v[2:5], v[22:23], off offset:1072
	global_load_dwordx4 v[6:9], v[22:23], off offset:1056
	v_or_b32_e32 v81, 10, v34
	v_or_b32_e32 v79, 11, v34
	v_mul_f32_e32 v39, 0x45800000, v18
	v_cndmask_b32_e32 v39, v18, v39, vcc
	v_readlane_b32 s41, v251, 7
	v_readlane_b32 s42, v251, 8
	v_readlane_b32 s43, v251, 9
	v_readlane_b32 s44, v251, 10
	v_readlane_b32 s45, v251, 11
	v_readlane_b32 s46, v251, 12
	v_readlane_b32 s47, v251, 13
	v_readlane_b32 s48, v251, 14
	v_readlane_b32 s49, v251, 15
	v_readlane_b32 s50, v251, 16
	v_readlane_b32 s51, v251, 17
	s_or_b32 s88, s0, s88
	v_readlane_b32 s40, v251, 22
	v_readlane_b32 s41, v251, 23
	v_mov_b32_e32 v21, v1
	v_mul_u32_u24_e32 v84, 0x110, v31
	v_add3_u32 v0, s15, v84, v0
	v_or_b32_e32 v101, 31, v34
	v_cmp_gt_u32_e32 vcc, v31, v34
	v_or_b32_e32 v57, 48, v34
	v_and_b32_e32 v32, 15, v50
	v_readlane_b32 s44, v251, 26
	v_readlane_b32 s45, v251, 27
	v_readlane_b32 s46, v251, 28
	v_readlane_b32 s47, v251, 29
	v_readlane_b32 s48, v251, 30
	v_readlane_b32 s49, v251, 31
	v_readlane_b32 s50, v251, 32
	v_readlane_b32 s51, v251, 33
	v_readlane_b32 s52, v251, 34
	v_readlane_b32 s53, v251, 35
	v_readlane_b32 s54, v251, 36
	v_readlane_b32 s55, v251, 37
	v_readlane_b32 s44, v251, 54
	v_readlane_b32 s50, v251, 60
	v_readlane_b32 s51, v251, 61
	s_add_u32 s6, s50, s8
	s_addc_u32 s7, s51, 0
	v_readlane_b32 s42, v251, 24
	v_readlane_b32 s43, v251, 25
	v_readlane_b32 s52, v251, 62
	v_readlane_b32 s53, v251, 63
	v_readlane_b32 s54, v252, 0
	v_readlane_b32 s55, v252, 1
	v_readlane_b32 s45, v251, 55
	s_waitcnt vmcnt(11)
	v_lshlrev_b32_e32 v48, 16, v11
	v_and_b32_e32 v11, 0xffff0000, v11
	v_mul_f32_e32 v54, v11, v11
	v_fmamk_f32 v54, v54, 0xbdd2d3e7, v129
	v_mul_f32_e32 v54, v54, v11
	v_lshlrev_b32_e32 v18, 16, v10
	v_and_b32_e32 v10, 0xffff0000, v10
	v_mul_f32_e32 v51, v18, v18
	v_mul_f32_e32 v52, v10, v10
	v_fmamk_f32 v51, v51, 0xbdd2d3e7, v129
	v_exp_f32_e32 v54, v54
	v_fmamk_f32 v52, v52, 0xbdd2d3e7, v129
	v_mul_f32_e32 v51, v51, v18
	v_mul_f32_e32 v52, v52, v10
	v_exp_f32_e32 v51, v51
	v_add_f32_e32 v54, 1.0, v54
	v_exp_f32_e32 v52, v52
	v_rcp_f32_e32 v54, v54
	v_lshlrev_b32_e32 v49, 16, v12
	v_mul_f32_e32 v55, v49, v49
	v_fmamk_f32 v55, v55, 0xbdd2d3e7, v129
	v_add_f32_e32 v51, 1.0, v51
	v_mul_f32_e32 v55, v55, v49
	v_add_f32_e32 v52, 1.0, v52
	v_rcp_f32_e32 v51, v51
	v_fma_f32 v11, v54, v11, -v19
	v_rcp_f32_e32 v52, v52
	v_mul_f32_e32 v59, v39, v11
	v_and_b32_e32 v11, 0xffff0000, v12
	v_mul_f32_e32 v12, v11, v11
	v_exp_f32_e32 v55, v55
	v_fmamk_f32 v12, v12, 0xbdd2d3e7, v129
	v_fma_f32 v18, v51, v18, -v19
	v_mul_f32_e32 v12, v12, v11
	v_fma_f32 v10, v52, v10, -v19
	v_mul_f32_e32 v18, v39, v18
	v_mul_f32_e32 v10, v39, v10
	s_waitcnt vmcnt(9)
	v_fma_f32 v18, v28, v18, v36
	v_lshlrev_b32_e32 v28, 16, v13
	v_add_f32_e32 v55, 1.0, v55
	v_fmac_f32_e32 v37, v29, v10
	v_exp_f32_e32 v12, v12
	v_mul_f32_e32 v29, v28, v28
	v_rcp_f32_e32 v55, v55
	v_fmamk_f32 v29, v29, 0xbdd2d3e7, v129
	v_mul_f32_e32 v29, v29, v28
	v_cvt_pk_bf16_f32 v10, v18, s0
	v_add_f32_e32 v12, 1.0, v12
	v_cvt_pk_bf16_f32 v18, v37, s0
	ds_write_b16 v38, v10 offset:34816
	ds_write_b16 v35, v18 offset:34816
	v_fma_f32 v10, v55, v49, -v19
	v_rcp_f32_e32 v12, v12
	v_exp_f32_e32 v29, v29
	v_mul_f32_e32 v10, v39, v10
	s_waitcnt vmcnt(5)
	v_fma_f32 v10, v40, v10, v44
	v_cvt_pk_bf16_f32 v10, v10, s0
	ds_write_b16 v35, v10 offset:35632
	v_fma_f32 v10, v12, v11, -v19
	v_add_f32_e32 v11, 1.0, v29
	v_rcp_f32_e32 v11, v11
	v_mul_f32_e32 v10, v39, v10
	v_fmac_f32_e32 v45, v10, v41
	v_cvt_pk_bf16_f32 v10, v45, s0
	ds_write_b16 v35, v10 offset:35904
	v_fma_f32 v10, v11, v28, -v19
	v_and_b32_e32 v11, 0xffff0000, v13
	v_mul_f32_e32 v12, v11, v11
	v_fmamk_f32 v12, v12, 0xbdd2d3e7, v129
	v_mul_f32_e32 v12, v12, v11
	v_exp_f32_e32 v12, v12
	s_waitcnt vmcnt(2)
	v_lshlrev_b32_e32 v13, 16, v14
	v_mul_f32_e32 v28, v13, v13
	v_fmamk_f32 v28, v28, 0xbdd2d3e7, v129
	v_add_f32_e32 v12, 1.0, v12
	v_rcp_f32_e32 v12, v12
	v_mul_f32_e32 v28, v28, v13
	v_fma_f32 v11, v12, v11, -v19
	v_exp_f32_e32 v28, v28
	v_mul_f32_e32 v44, v39, v11
	v_and_b32_e32 v11, 0xffff0000, v14
	v_mul_f32_e32 v12, v11, v11
	v_fmamk_f32 v12, v12, 0xbdd2d3e7, v129
	v_mul_f32_e32 v12, v12, v11
	v_mul_f32_e32 v45, v39, v10
	v_add_f32_e32 v10, 1.0, v28
	v_rcp_f32_e32 v10, v10
	v_exp_f32_e32 v12, v12
	v_lshlrev_b32_e32 v29, 16, v16
	v_fma_f32 v10, v10, v13, -v19
	v_lshlrev_b32_e32 v13, 16, v15
	v_add_f32_e32 v12, 1.0, v12
	v_mul_f32_e32 v14, v13, v13
	v_rcp_f32_e32 v12, v12
	v_fmamk_f32 v14, v14, 0xbdd2d3e7, v129
	v_mul_f32_e32 v10, v39, v10
	v_mul_f32_e32 v14, v14, v13
	v_fma_f32 v10, v42, v10, v46
	v_cvt_pk_bf16_f32 v10, v10, s0
	v_exp_f32_e32 v14, v14
	ds_write_b16 v35, v10 offset:36720
	v_fma_f32 v10, v12, v11, -v19
	v_mul_f32_e32 v10, v39, v10
	v_fmac_f32_e32 v47, v43, v10
	v_cvt_pk_bf16_f32 v10, v47, s0
	v_and_b32_e32 v15, 0xffff0000, v15
	v_add_f32_e32 v11, 1.0, v14
	ds_write_b16 v35, v10 offset:36992
	v_mul_f32_e32 v10, v15, v15
	v_rcp_f32_e32 v11, v11
	v_fmamk_f32 v10, v10, 0xbdd2d3e7, v129
	v_mul_f32_e32 v10, v10, v15
	v_fma_f32 v14, v11, v13, -v19
	v_exp_f32_e32 v28, v10
	global_load_dwordx2 v[10:11], v20, s[16:17] offset:64
	global_load_dwordx2 v[12:13], v20, s[20:21] offset:64
	v_mul_f32_e32 v37, v29, v29
	v_fmamk_f32 v37, v37, 0xbdd2d3e7, v129
	v_add_f32_e32 v28, 1.0, v28
	v_mul_f32_e32 v37, v37, v29
	v_rcp_f32_e32 v28, v28
	v_exp_f32_e32 v37, v37
	v_fma_f32 v15, v28, v15, -v19
	v_mul_f32_e32 v46, v39, v15
	v_and_b32_e32 v15, 0xffff0000, v16
	v_mul_f32_e32 v16, v15, v15
	v_mul_f32_e32 v47, v39, v14
	v_add_f32_e32 v14, 1.0, v37
	v_fmamk_f32 v16, v16, 0xbdd2d3e7, v129
	v_rcp_f32_e32 v14, v14
	v_mul_f32_e32 v16, v16, v15
	v_exp_f32_e32 v16, v16
	v_fma_f32 v14, v14, v29, -v19
	v_mul_f32_e32 v14, v39, v14
	v_fma_f32 v14, v24, v14, v26
	v_lshlrev_b32_e32 v24, 16, v17
	v_add_f32_e32 v16, 1.0, v16
	v_mul_f32_e32 v26, v24, v24
	v_rcp_f32_e32 v16, v16
	v_fmamk_f32 v26, v26, 0xbdd2d3e7, v129
	v_mul_f32_e32 v26, v26, v24
	v_cvt_pk_bf16_f32 v14, v14, s0
	v_exp_f32_e32 v26, v26
	ds_write_b16 v35, v14 offset:37808
	v_fma_f32 v14, v16, v15, -v19
	v_mul_f32_e32 v14, v39, v14
	v_fmac_f32_e32 v27, v14, v25
	v_cvt_pk_bf16_f32 v14, v27, s0
	v_and_b32_e32 v25, 0xffff0000, v17
	v_add_f32_e32 v15, 1.0, v26
	ds_write_b16 v35, v14 offset:38080
	v_mul_f32_e32 v14, v25, v25
	v_rcp_f32_e32 v15, v15
	v_fmamk_f32 v14, v14, 0xbdd2d3e7, v129
	v_mul_f32_e32 v14, v14, v25
	v_fma_f32 v24, v15, v24, -v19
	v_exp_f32_e32 v26, v14
	global_load_dwordx2 v[14:15], v20, s[16:17] offset:80
	global_load_dwordx2 v[16:17], v20, s[20:21] offset:80
	s_waitcnt vmcnt(4)
	v_lshlrev_b32_e32 v27, 16, v6
	v_mul_f32_e32 v28, v27, v27
	v_fmamk_f32 v28, v28, 0xbdd2d3e7, v129
	v_mul_f32_e32 v28, v28, v27
	v_exp_f32_e32 v28, v28
	v_mul_f32_e32 v55, v39, v24
	v_mul_f32_e32 v53, v48, v48
	v_fmamk_f32 v53, v53, 0xbdd2d3e7, v129
	v_add_f32_e32 v24, 1.0, v28
	v_rcp_f32_e32 v24, v24
	v_and_b32_e32 v6, 0xffff0000, v6
	v_mul_f32_e32 v53, v53, v48
	v_fma_f32 v24, v24, v27, -v19
	v_mul_f32_e32 v40, v39, v24
	v_mul_f32_e32 v24, v6, v6
	v_fmamk_f32 v24, v24, 0xbdd2d3e7, v129
	v_mul_f32_e32 v24, v24, v6
	v_exp_f32_e32 v53, v53
	v_exp_f32_e32 v41, v24
	v_add_f32_e32 v53, 1.0, v53
	v_add_f32_e32 v26, 1.0, v26
	v_rcp_f32_e32 v53, v53
	v_rcp_f32_e32 v26, v26
	s_waitcnt vmcnt(2)
	v_fma_f32 v10, v10, v40, v12
	v_lshlrev_b32_e32 v40, 16, v7
	v_add_f32_e32 v12, 1.0, v41
	v_mul_f32_e32 v41, v40, v40
	v_fmamk_f32 v41, v41, 0xbdd2d3e7, v129
	v_mul_f32_e32 v41, v41, v40
	v_fma_f32 v48, v53, v48, -v19
	v_fma_f32 v25, v26, v25, -v19
	v_mul_f32_e32 v65, v39, v48
	v_mul_f32_e32 v54, v39, v25
	global_load_dwordx2 v[24:25], v20, s[16:17] offset:96
	global_load_dwordx2 v[28:29], v20, s[16:17] offset:112
	global_load_dwordx2 v[26:27], v20, s[20:21] offset:96
	global_load_dwordx2 v[48:49], v20, s[20:21] offset:112
	v_exp_f32_e32 v41, v41
	v_rcp_f32_e32 v12, v12
	v_cvt_pk_bf16_f32 v10, v10, s0
	ds_write_b16 v35, v10 offset:38896
	v_add_f32_e32 v10, 1.0, v41
	v_fma_f32 v6, v12, v6, -v19
	v_rcp_f32_e32 v10, v10
	v_mul_f32_e32 v6, v39, v6
	v_fmac_f32_e32 v13, v11, v6
	v_cvt_pk_bf16_f32 v6, v13, s0
	v_and_b32_e32 v7, 0xffff0000, v7
	ds_write_b16 v35, v6 offset:39168
	v_fma_f32 v6, v10, v40, -v19
	v_mul_f32_e32 v10, v7, v7
	v_fmamk_f32 v10, v10, 0xbdd2d3e7, v129
	v_mul_f32_e32 v10, v10, v7
	v_exp_f32_e32 v10, v10
	v_lshlrev_b32_e32 v11, 16, v8
	v_mul_f32_e32 v12, v11, v11
	v_fmamk_f32 v12, v12, 0xbdd2d3e7, v129
	v_mul_f32_e32 v12, v12, v11
	v_add_f32_e32 v10, 1.0, v10
	v_rcp_f32_e32 v10, v10
	v_exp_f32_e32 v12, v12
	v_mul_f32_e32 v53, v39, v6
	v_fma_f32 v7, v10, v7, -v19
	v_mul_f32_e32 v52, v39, v7
	v_and_b32_e32 v7, 0xffff0000, v8
	v_add_f32_e32 v6, 1.0, v12
	v_mul_f32_e32 v8, v7, v7
	v_rcp_f32_e32 v6, v6
	v_fmamk_f32 v8, v8, 0xbdd2d3e7, v129
	v_mul_f32_e32 v8, v8, v7
	v_lshlrev_b32_e32 v10, 16, v9
	v_fma_f32 v6, v6, v11, -v19
	v_exp_f32_e32 v8, v8
	v_mul_f32_e32 v11, v10, v10
	v_fmamk_f32 v11, v11, 0xbdd2d3e7, v129
	v_mul_f32_e32 v11, v11, v10
	v_add_f32_e32 v8, 1.0, v8
	v_rcp_f32_e32 v8, v8
	v_exp_f32_e32 v11, v11
	v_mul_f32_e32 v6, v39, v6
	s_waitcnt vmcnt(4)
	v_fma_f32 v6, v14, v6, v16
	v_cvt_pk_bf16_f32 v6, v6, s0
	ds_write_b16 v35, v6 offset:39984
	v_fma_f32 v6, v8, v7, -v19
	v_add_f32_e32 v7, 1.0, v11
	v_rcp_f32_e32 v7, v7
	v_mul_f32_e32 v6, v39, v6
	v_fmac_f32_e32 v17, v6, v15
	v_cvt_pk_bf16_f32 v6, v17, s0
	ds_write_b16 v35, v6 offset:40256
	v_fma_f32 v6, v7, v10, -v19
	v_and_b32_e32 v7, 0xffff0000, v9
	v_lshlrev_b32_e32 v9, 16, v2
	v_mul_f32_e32 v10, v9, v9
	v_fmamk_f32 v10, v10, 0xbdd2d3e7, v129
	v_mul_f32_e32 v8, v7, v7
	v_mul_f32_e32 v10, v10, v9
	v_fmamk_f32 v8, v8, 0xbdd2d3e7, v129
	v_mul_f32_e32 v8, v8, v7
	v_exp_f32_e32 v10, v10
	v_exp_f32_e32 v8, v8
	v_mul_f32_e32 v58, v39, v6
	v_add_f32_e32 v6, 1.0, v10
	global_load_dwordx4 v[10:13], v[22:23], off offset:1104
	global_load_dwordx4 v[14:17], v[22:23], off offset:1088
	v_add_f32_e32 v8, 1.0, v8
	v_rcp_f32_e32 v8, v8
	v_and_b32_e32 v2, 0xffff0000, v2
	v_rcp_f32_e32 v6, v6
	v_or_b32_e32 v18, 4, v34
	v_fma_f32 v7, v8, v7, -v19
	v_mul_f32_e32 v56, v39, v7
	v_mul_f32_e32 v7, v2, v2
	v_fmamk_f32 v7, v7, 0xbdd2d3e7, v129
	v_mul_f32_e32 v7, v7, v2
	v_exp_f32_e32 v7, v7
	v_lshlrev_b32_e32 v8, 16, v3
	v_fma_f32 v6, v6, v9, -v19
	v_mul_f32_e32 v9, v8, v8
	v_add_f32_e32 v7, 1.0, v7
	v_rcp_f32_e32 v7, v7
	v_fmamk_f32 v9, v9, 0xbdd2d3e7, v129
	v_mul_f32_e32 v9, v9, v8
	v_fma_f32 v2, v7, v2, -v19
	v_mul_f32_e32 v6, v39, v6
	v_mul_f32_e32 v2, v39, v2
	s_waitcnt vmcnt(3)
	v_fma_f32 v6, v24, v6, v26
	v_exp_f32_e32 v9, v9
	v_fmac_f32_e32 v27, v25, v2
	v_cvt_pk_bf16_f32 v6, v6, s0
	v_cvt_pk_bf16_f32 v2, v27, s0
	ds_write_b16 v35, v6 offset:41072
	ds_write_b16 v35, v2 offset:41344
	global_load_dwordx2 v[24:25], v20, s[16:17] offset:128
	global_load_dwordx2 v[26:27], v20, s[20:21] offset:128
	v_add_f32_e32 v6, 1.0, v9
	v_rcp_f32_e32 v6, v6
	v_and_b32_e32 v3, 0xffff0000, v3
	v_lshlrev_b32_e32 v7, 16, v4
	v_or_b32_e32 v36, 8, v34
	v_fma_f32 v2, v6, v8, -v19
	v_mul_f32_e32 v6, v3, v3
	v_fmamk_f32 v6, v6, 0xbdd2d3e7, v129
	v_mul_f32_e32 v6, v6, v3
	v_exp_f32_e32 v6, v6
	v_mul_f32_e32 v8, v7, v7
	v_fmamk_f32 v8, v8, 0xbdd2d3e7, v129
	v_mul_f32_e32 v8, v8, v7
	v_add_f32_e32 v6, 1.0, v6
	v_rcp_f32_e32 v6, v6
	v_exp_f32_e32 v8, v8
	v_mul_f32_e32 v64, v39, v2
	v_fma_f32 v3, v6, v3, -v19
	v_mul_f32_e32 v63, v39, v3
	v_and_b32_e32 v3, 0xffff0000, v4
	v_add_f32_e32 v2, 1.0, v8
	v_mul_f32_e32 v4, v3, v3
	v_rcp_f32_e32 v2, v2
	v_fmamk_f32 v4, v4, 0xbdd2d3e7, v129
	v_mul_f32_e32 v4, v4, v3
	v_fma_f32 v2, v2, v7, -v19
	v_exp_f32_e32 v4, v4
	v_mul_f32_e32 v2, v39, v2
	s_waitcnt vmcnt(4)
	v_fma_f32 v2, v28, v2, v48
	v_cvt_pk_bf16_f32 v2, v2, s0
	ds_write_b16 v35, v2 offset:42160
	v_add_f32_e32 v2, 1.0, v4
	v_lshlrev_b32_e32 v4, 16, v5
	v_mul_f32_e32 v6, v4, v4
	v_fmamk_f32 v6, v6, 0xbdd2d3e7, v129
	v_rcp_f32_e32 v2, v2
	v_mul_f32_e32 v6, v6, v4
	v_exp_f32_e32 v6, v6
	v_fma_f32 v2, v2, v3, -v19
	v_mul_f32_e32 v2, v39, v2
	v_fmac_f32_e32 v49, v2, v29
	v_add_f32_e32 v2, 1.0, v6
	v_cvt_pk_bf16_f32 v6, v49, s0
	ds_write_b16 v35, v6 offset:42432
	global_load_dwordx2 v[60:61], v20, s[16:17] offset:144
	global_load_dwordx2 v[66:67], v20, s[20:21] offset:144
	v_and_b32_e32 v3, 0xffff0000, v5
	v_mul_f32_e32 v5, v3, v3
	v_fmamk_f32 v5, v5, 0xbdd2d3e7, v129
	v_mul_f32_e32 v5, v5, v3
	v_rcp_f32_e32 v2, v2
	v_exp_f32_e32 v5, v5
	s_waitcnt vmcnt(4)
	v_lshlrev_b32_e32 v28, 16, v14
	v_and_b32_e32 v14, 0xffff0000, v14
	v_fma_f32 v2, v2, v4, -v19
	v_add_f32_e32 v4, 1.0, v5
	v_mul_f32_e32 v5, v28, v28
	v_fmamk_f32 v5, v5, 0xbdd2d3e7, v129
	v_mul_f32_e32 v5, v5, v28
	v_rcp_f32_e32 v4, v4
	v_exp_f32_e32 v5, v5
	v_mul_f32_e32 v69, v39, v2
	v_fma_f32 v2, v4, v3, -v19
	v_mul_f32_e32 v68, v39, v2
	v_add_f32_e32 v2, 1.0, v5
	v_rcp_f32_e32 v29, v2
	global_load_dwordx4 v[2:5], v[22:23], off offset:1136
	global_load_dwordx4 v[6:9], v[22:23], off offset:1120
	v_or_b32_e32 v37, 12, v34
	v_or_b32_e32 v38, 16, v34
	v_fma_f32 v22, v29, v28, -v19
	v_mul_f32_e32 v48, v39, v22
	v_mul_f32_e32 v22, v14, v14
	v_fmamk_f32 v22, v22, 0xbdd2d3e7, v129
	v_mul_f32_e32 v22, v22, v14
	v_exp_f32_e32 v49, v22
	global_load_dwordx2 v[74:75], v20, s[16:17] offset:160
	global_load_dwordx2 v[22:23], v20, s[16:17] offset:176
	global_load_dwordx2 v[76:77], v20, s[20:21] offset:160
	global_load_dwordx2 v[28:29], v20, s[20:21] offset:176
	s_waitcnt vmcnt(8)
	v_fma_f32 v24, v24, v48, v26
	v_lshlrev_b32_e32 v48, 16, v15
	v_add_f32_e32 v26, 1.0, v49
	v_mul_f32_e32 v49, v48, v48
	v_fmamk_f32 v49, v49, 0xbdd2d3e7, v129
	v_mul_f32_e32 v49, v49, v48
	v_exp_f32_e32 v49, v49
	v_rcp_f32_e32 v26, v26
	v_cvt_pk_bf16_f32 v24, v24, s0
	ds_write_b16 v35, v24 offset:43248
	v_add_f32_e32 v24, 1.0, v49
	v_fma_f32 v14, v26, v14, -v19
	v_rcp_f32_e32 v24, v24
	v_mul_f32_e32 v14, v39, v14
	v_fmac_f32_e32 v27, v25, v14
	v_cvt_pk_bf16_f32 v14, v27, s0
	v_and_b32_e32 v15, 0xffff0000, v15
	ds_write_b16 v35, v14 offset:43520
	v_fma_f32 v14, v24, v48, -v19
	v_mul_f32_e32 v24, v15, v15
	v_fmamk_f32 v24, v24, 0xbdd2d3e7, v129
	v_mul_f32_e32 v24, v24, v15
	v_exp_f32_e32 v24, v24
	v_lshlrev_b32_e32 v25, 16, v16
	v_mul_f32_e32 v26, v25, v25
	v_fmamk_f32 v26, v26, 0xbdd2d3e7, v129
	v_mul_f32_e32 v26, v26, v25
	v_add_f32_e32 v24, 1.0, v24
	v_rcp_f32_e32 v24, v24
	v_exp_f32_e32 v26, v26
	v_mul_f32_e32 v73, v39, v14
	v_fma_f32 v15, v24, v15, -v19
	v_mul_f32_e32 v72, v39, v15
	v_and_b32_e32 v15, 0xffff0000, v16
	v_add_f32_e32 v14, 1.0, v26
	v_mul_f32_e32 v16, v15, v15
	v_rcp_f32_e32 v14, v14
	v_fmamk_f32 v16, v16, 0xbdd2d3e7, v129
	v_mul_f32_e32 v16, v16, v15
	v_lshlrev_b32_e32 v24, 16, v17
	v_fma_f32 v14, v14, v25, -v19
	v_exp_f32_e32 v16, v16
	v_mul_f32_e32 v25, v24, v24
	v_fmamk_f32 v25, v25, 0xbdd2d3e7, v129
	v_mul_f32_e32 v25, v25, v24
	v_add_f32_e32 v16, 1.0, v16
	v_rcp_f32_e32 v16, v16
	v_exp_f32_e32 v25, v25
	v_mul_f32_e32 v14, v39, v14
	s_waitcnt vmcnt(6)
	v_fma_f32 v14, v60, v14, v66
	v_cvt_pk_bf16_f32 v14, v14, s0
	ds_write_b16 v35, v14 offset:44336
	v_fma_f32 v14, v16, v15, -v19
	v_add_f32_e32 v15, 1.0, v25
	v_rcp_f32_e32 v15, v15
	v_mul_f32_e32 v14, v39, v14
	v_fmac_f32_e32 v67, v14, v61
	v_cvt_pk_bf16_f32 v14, v67, s0
	ds_write_b16 v35, v14 offset:44608
	v_fma_f32 v14, v15, v24, -v19
	v_and_b32_e32 v15, 0xffff0000, v17
	v_mul_f32_e32 v16, v15, v15
	v_fmamk_f32 v16, v16, 0xbdd2d3e7, v129
	v_mul_f32_e32 v16, v16, v15
	v_exp_f32_e32 v16, v16
	v_lshlrev_b32_e32 v17, 16, v10
	v_mul_f32_e32 v24, v17, v17
	v_fmamk_f32 v24, v24, 0xbdd2d3e7, v129
	v_mul_f32_e32 v24, v24, v17
	v_add_f32_e32 v16, 1.0, v16
	v_rcp_f32_e32 v16, v16
	v_exp_f32_e32 v24, v24
	v_and_b32_e32 v10, 0xffff0000, v10
	v_mul_f32_e32 v71, v39, v14
	v_fma_f32 v15, v16, v15, -v19
	v_add_f32_e32 v14, 1.0, v24
	v_mul_f32_e32 v70, v39, v15
	v_mul_f32_e32 v15, v10, v10
	v_rcp_f32_e32 v14, v14
	v_fmamk_f32 v15, v15, 0xbdd2d3e7, v129
	v_mul_f32_e32 v15, v15, v10
	v_fma_f32 v14, v14, v17, -v19
	v_exp_f32_e32 v15, v15
	v_mul_f32_e32 v14, v39, v14
	s_waitcnt vmcnt(1)
	v_fma_f32 v14, v74, v14, v76
	v_cvt_pk_bf16_f32 v14, v14, s0
	ds_write_b16 v35, v14 offset:45424
	v_add_f32_e32 v14, 1.0, v15
	v_lshlrev_b32_e32 v15, 16, v11
	v_rcp_f32_e32 v14, v14
	v_mul_f32_e32 v16, v15, v15
	v_fmamk_f32 v16, v16, 0xbdd2d3e7, v129
	v_mul_f32_e32 v16, v16, v15
	v_and_b32_e32 v11, 0xffff0000, v11
	v_fma_f32 v10, v14, v10, -v19
	v_mul_f32_e32 v14, v11, v11
	v_exp_f32_e32 v16, v16
	v_fmamk_f32 v14, v14, 0xbdd2d3e7, v129
	v_mul_f32_e32 v14, v14, v11
	v_mul_f32_e32 v10, v39, v10
	v_fmac_f32_e32 v77, v75, v10
	v_add_f32_e32 v10, 1.0, v16
	v_exp_f32_e32 v14, v14
	v_rcp_f32_e32 v10, v10
	v_cvt_pk_bf16_f32 v16, v77, s0
	ds_write_b16 v35, v16 offset:45696
	v_add_f32_e32 v14, 1.0, v14
	v_fma_f32 v10, v10, v15, -v19
	v_rcp_f32_e32 v14, v14
	v_lshlrev_b32_e32 v15, 16, v12
	v_mul_f32_e32 v16, v15, v15
	v_fmamk_f32 v16, v16, 0xbdd2d3e7, v129
	v_mul_f32_e32 v16, v16, v15
	v_mul_f32_e32 v67, v39, v10
	v_fma_f32 v10, v14, v11, -v19
	v_and_b32_e32 v11, 0xffff0000, v12
	v_mul_f32_e32 v12, v11, v11
	v_exp_f32_e32 v16, v16
	v_fmamk_f32 v12, v12, 0xbdd2d3e7, v129
	v_mul_f32_e32 v12, v12, v11
	v_mul_f32_e32 v66, v39, v10
	v_add_f32_e32 v10, 1.0, v16
	v_exp_f32_e32 v12, v12
	v_rcp_f32_e32 v10, v10
	v_or_b32_e32 v76, 2, v34
	v_lshlrev_b32_e32 v14, 2, v76
	v_add_f32_e32 v12, 1.0, v12
	v_fma_f32 v10, v10, v15, -v19
	v_rcp_f32_e32 v12, v12
	v_mul_f32_e32 v10, v39, v10
	s_waitcnt vmcnt(0)
	v_fma_f32 v10, v22, v10, v28
	v_cvt_pk_bf16_f32 v10, v10, s0
	ds_write_b16 v35, v10 offset:46512
	v_fma_f32 v10, v12, v11, -v19
	v_lshlrev_b32_e32 v11, 16, v13
	v_mul_f32_e32 v12, v11, v11
	v_fmamk_f32 v12, v12, 0xbdd2d3e7, v129
	v_mul_f32_e32 v12, v12, v11
	v_exp_f32_e32 v12, v12
	v_mul_f32_e32 v10, v39, v10
	v_fmac_f32_e32 v29, v10, v23
	v_cvt_pk_bf16_f32 v10, v29, s0
	global_load_dword v15, v14, s[16:17]
	s_nop 0
	global_load_dword v14, v14, s[20:21]
	ds_write_b16 v35, v10 offset:46784
	v_add_f32_e32 v10, 1.0, v12
	v_rcp_f32_e32 v10, v10
	v_or_b32_e32 v77, 3, v34
	v_lshlrev_b32_e32 v12, 2, v77
	global_load_dword v16, v12, s[16:17]
	global_load_dword v17, v12, s[20:21]
	v_fma_f32 v10, v10, v11, -v19
	v_and_b32_e32 v11, 0xffff0000, v13
	v_mul_f32_e32 v12, v11, v11
	v_fmamk_f32 v12, v12, 0xbdd2d3e7, v129
	v_mul_f32_e32 v12, v12, v11
	v_lshlrev_b32_e32 v13, 16, v6
	v_exp_f32_e32 v12, v12
	v_mul_f32_e32 v22, v13, v13
	v_fmamk_f32 v22, v22, 0xbdd2d3e7, v129
	v_mul_f32_e32 v22, v22, v13
	v_add_f32_e32 v12, 1.0, v12
	v_exp_f32_e32 v22, v22
	v_rcp_f32_e32 v12, v12
	v_mul_f32_e32 v75, v39, v10
	v_and_b32_e32 v6, 0xffff0000, v6
	v_add_f32_e32 v10, 1.0, v22
	v_fma_f32 v11, v12, v11, -v19
	v_rcp_f32_e32 v10, v10
	v_mul_f32_e32 v74, v39, v11
	v_mul_f32_e32 v11, v6, v6
	v_fmamk_f32 v11, v11, 0xbdd2d3e7, v129
	v_mul_f32_e32 v11, v11, v6
	v_fma_f32 v10, v10, v13, -v19
	v_exp_f32_e32 v22, v11
	v_mul_f32_e32 v82, v39, v10
	global_load_dwordx2 v[10:11], v20, s[16:17] offset:192
	global_load_dwordx2 v[12:13], v20, s[20:21] offset:192
	v_lshlrev_b32_e32 v23, 16, v7
	v_mul_f32_e32 v24, v23, v23
	v_and_b32_e32 v7, 0xffff0000, v7
	v_fmamk_f32 v24, v24, 0xbdd2d3e7, v129
	v_mul_f32_e32 v25, v7, v7
	v_mul_f32_e32 v24, v24, v23
	v_fmamk_f32 v25, v25, 0xbdd2d3e7, v129
	v_mul_f32_e32 v25, v25, v7
	v_add_f32_e32 v22, 1.0, v22
	v_rcp_f32_e32 v22, v22
	v_exp_f32_e32 v24, v24
	v_exp_f32_e32 v25, v25
	v_fma_f32 v6, v22, v6, -v19
	v_add_f32_e32 v22, 1.0, v24
	v_rcp_f32_e32 v22, v22
	v_add_f32_e32 v24, 1.0, v25
	v_rcp_f32_e32 v24, v24
	v_mul_f32_e32 v83, v39, v6
	v_fma_f32 v6, v22, v23, -v19
	v_mul_f32_e32 v62, v39, v6
	v_fma_f32 v6, v24, v7, -v19
	v_lshlrev_b32_e32 v91, 16, v8
	v_mul_f32_e32 v61, v39, v6
	v_or_b32_e32 v6, s88, v31
	v_lshlrev_b32_e32 v6, 7, v6
	v_mov_b32_e32 v7, v1
	v_lshl_add_u64 v[6:7], v[6:7], 2, s[40:41]
	v_lshl_add_u64 v[6:7], v[6:7], 0, v[20:21]
	v_and_b32_e32 v8, 0xffff0000, v8
	v_mul_f32_e32 v98, v8, v8
	v_fmamk_f32 v98, v98, 0xbdd2d3e7, v129
	v_mul_f32_e32 v98, v98, v8
	v_exp_f32_e32 v98, v98
	v_and_b32_e32 v99, 0xffff0000, v9
	v_and_b32_e32 v105, 0xffff0000, v5
	s_waitcnt vmcnt(4)
	v_fmac_f32_e32 v14, v15, v65
	v_mul_u32_u24_e32 v15, 0x110, v76
	v_cvt_pk_bf16_f32 v14, v14, s0
	v_add3_u32 v15, s15, v15, v33
	v_or_b32_e32 v65, 6, v34
	ds_write_b16 v15, v14 offset:34816
	v_lshlrev_b32_e32 v14, 2, v65
	global_load_dword v85, v14, s[16:17]
	global_load_dword v86, v14, s[20:21]
	s_waitcnt vmcnt(4)
	v_fmac_f32_e32 v17, v16, v59
	v_lshlrev_b32_e32 v14, 2, v78
	v_mul_u32_u24_e32 v15, 0x110, v77
	global_load_dword v87, v14, s[16:17]
	global_load_dword v88, v14, s[20:21]
	v_cvt_pk_bf16_f32 v14, v17, s0
	v_add3_u32 v15, s15, v15, v33
	ds_write_b16 v15, v14 offset:34816
	v_lshlrev_b32_e32 v14, 2, v81
	global_load_dwordx2 v[22:23], v20, s[16:17] offset:208
	global_load_dwordx2 v[24:25], v20, s[20:21] offset:208
	global_load_dword v89, v14, s[16:17]
	global_load_dword v90, v14, s[20:21]
	v_lshlrev_b32_e32 v14, 2, v79
	global_load_dword v92, v14, s[16:17]
	global_load_dword v93, v14, s[20:21]
	v_mul_f32_e32 v14, v91, v91
	v_fmamk_f32 v14, v14, 0xbdd2d3e7, v129
	v_mul_f32_e32 v14, v14, v91
	v_or_b32_e32 v59, 14, v34
	v_lshlrev_b32_e32 v15, 2, v59
	global_load_dword v94, v15, s[16:17]
	global_load_dword v95, v15, s[20:21]
	v_exp_f32_e32 v96, v14
	global_load_dwordx2 v[14:15], v20, s[16:17] offset:224
	global_load_dwordx2 v[16:17], v20, s[16:17] offset:240
	global_load_dwordx2 v[26:27], v20, s[20:21] offset:224
	s_nop 0
	global_load_dwordx2 v[20:21], v20, s[20:21] offset:240
	v_or_b32_e32 v40, 20, v34
	v_or_b32_e32 v41, 24, v34
	v_or_b32_e32 v42, 28, v34
	v_or_b32_e32 v43, 32, v34
	v_or_b32_e32 v48, 36, v34
	v_or_b32_e32 v49, 40, v34
	v_or_b32_e32 v51, 44, v34
	v_or_b32_e32 v60, 52, v34
	s_waitcnt vmcnt(16)
	v_fma_f32 v10, v10, v82, v12
	v_cvt_pk_bf16_f32 v12, v10, s0
	v_or_b32_e32 v10, 15, v34
	v_add_f32_e32 v82, 1.0, v96
	v_lshlrev_b32_e32 v96, 2, v10
	global_load_dword v97, v96, s[16:17]
	s_nop 0
	global_load_dword v96, v96, s[20:21]
	v_rcp_f32_e32 v82, v82
	ds_write_b16 v35, v12 offset:47600
	v_fmac_f32_e32 v13, v11, v83
	v_cvt_pk_bf16_f32 v11, v13, s0
	v_fma_f32 v12, v82, v91, -v19
	v_lshlrev_b32_e32 v91, 16, v9
	v_add_f32_e32 v82, 1.0, v98
	v_mul_f32_e32 v98, v91, v91
	v_fmamk_f32 v98, v98, 0xbdd2d3e7, v129
	v_mul_f32_e32 v98, v98, v91
	v_rcp_f32_e32 v82, v82
	v_exp_f32_e32 v98, v98
	v_mul_f32_e32 v12, v39, v12
	v_mul_u32_u24_e32 v13, 0x110, v81
	v_fma_f32 v8, v82, v8, -v19
	v_add_f32_e32 v82, 1.0, v98
	v_rcp_f32_e32 v82, v82
	v_mul_f32_e32 v100, v39, v8
	v_add3_u32 v13, s15, v13, v33
	v_mul_f32_e32 v9, v99, v99
	v_fma_f32 v8, v82, v91, -v19
	v_mul_u32_u24_e32 v82, 0x110, v65
	v_add3_u32 v82, s15, v82, v33
	v_fmamk_f32 v9, v9, 0xbdd2d3e7, v129
	v_mul_f32_e32 v9, v9, v99
	v_exp_f32_e32 v9, v9
	v_or_b32_e32 v91, 26, v34
	v_or_b32_e32 v29, 56, v34
	v_or_b32_e32 v28, 60, v34
	v_add_f32_e32 v9, 1.0, v9
	v_rcp_f32_e32 v98, v9
	v_mul_f32_e32 v9, v39, v8
	v_readlane_b32 s46, v251, 56
	v_readlane_b32 s47, v251, 57
	v_fma_f32 v8, v98, v99, -v19
	v_or_b32_e32 v98, 30, v34
	v_mul_f32_e32 v8, v39, v8
	v_readlane_b32 s48, v251, 58
	v_readlane_b32 s49, v251, 59
	s_waitcnt vmcnt(16)
	v_fmac_f32_e32 v86, v45, v85
	v_cvt_pk_bf16_f32 v45, v86, s0
	ds_write_b16 v82, v45 offset:34816
	v_mul_u32_u24_e32 v45, 0x110, v78
	s_waitcnt vmcnt(14)
	v_fmac_f32_e32 v88, v44, v87
	v_cvt_pk_bf16_f32 v44, v88, s0
	v_add3_u32 v45, s15, v45, v33
	ds_write_b16 v45, v44 offset:34816
	ds_write_b16 v35, v11 offset:47872
	s_waitcnt vmcnt(12)
	v_fma_f32 v11, v22, v12, v24
	s_waitcnt vmcnt(10)
	v_fmac_f32_e32 v90, v89, v47
	v_cvt_pk_bf16_f32 v12, v90, s0
	ds_write_b16 v13, v12 offset:34816
	s_waitcnt vmcnt(8)
	v_fmac_f32_e32 v93, v92, v46
	v_mul_u32_u24_e32 v13, 0x110, v79
	v_cvt_pk_bf16_f32 v12, v93, s0
	v_add3_u32 v13, s15, v13, v33
	v_cvt_pk_bf16_f32 v11, v11, s0
	ds_write_b16 v13, v12 offset:34816
	ds_write_b16 v35, v11 offset:48688
	v_lshlrev_b32_e32 v13, 16, v2
	v_mul_f32_e32 v22, v13, v13
	v_fmamk_f32 v22, v22, 0xbdd2d3e7, v129
	v_mul_f32_e32 v22, v22, v13
	v_exp_f32_e32 v22, v22
	v_fmac_f32_e32 v25, v100, v23
	v_cvt_pk_bf16_f32 v11, v25, s0
	s_waitcnt vmcnt(6)
	v_fmac_f32_e32 v95, v55, v94
	v_mul_u32_u24_e32 v12, 0x110, v59
	ds_write_b16 v35, v11 offset:48960
	v_cvt_pk_bf16_f32 v11, v95, s0
	v_add3_u32 v12, s15, v12, v33
	ds_write_b16 v12, v11 offset:34816
	v_add_f32_e32 v12, 1.0, v22
	v_rcp_f32_e32 v12, v12
	s_waitcnt vmcnt(0)
	v_fmac_f32_e32 v96, v54, v97
	v_mul_u32_u24_e32 v22, 0x110, v10
	v_cvt_pk_bf16_f32 v11, v96, s0
	v_add3_u32 v22, s15, v22, v33
	v_and_b32_e32 v2, 0xffff0000, v2
	ds_write_b16 v22, v11 offset:34816
	v_fma_f32 v11, v12, v13, -v19
	v_mul_f32_e32 v12, v2, v2
	v_lshlrev_b32_e32 v13, 16, v3
	v_fmamk_f32 v12, v12, 0xbdd2d3e7, v129
	v_mul_f32_e32 v22, v13, v13
	v_mul_f32_e32 v12, v12, v2
	v_fmamk_f32 v22, v22, 0xbdd2d3e7, v129
	v_mul_f32_e32 v22, v22, v13
	v_exp_f32_e32 v12, v12
	v_exp_f32_e32 v22, v22
	v_mul_f32_e32 v11, v39, v11
	v_add_f32_e32 v12, 1.0, v12
	v_fma_f32 v11, v14, v11, v26
	v_rcp_f32_e32 v12, v12
	v_add_f32_e32 v14, 1.0, v22
	v_rcp_f32_e32 v14, v14
	v_and_b32_e32 v3, 0xffff0000, v3
	v_fma_f32 v2, v12, v2, -v19
	v_mul_f32_e32 v12, v39, v2
	v_fma_f32 v2, v14, v13, -v19
	v_mul_f32_e32 v13, v3, v3
	v_fmamk_f32 v13, v13, 0xbdd2d3e7, v129
	v_mul_f32_e32 v13, v13, v3
	v_or_b32_e32 v86, 18, v34
	v_or_b32_e32 v87, 19, v34
	v_lshlrev_b32_e32 v14, 2, v86
	v_lshlrev_b32_e32 v22, 2, v87
	global_load_dword v26, v14, s[16:17]
	s_nop 0
	global_load_dword v14, v14, s[20:21]
	s_nop 0
	global_load_dword v54, v22, s[16:17]
	global_load_dword v55, v22, s[20:21]
	v_lshlrev_b32_e32 v22, 16, v4
	v_exp_f32_e32 v13, v13
	v_mul_f32_e32 v23, v22, v22
	v_fmamk_f32 v23, v23, 0xbdd2d3e7, v129
	v_mul_f32_e32 v23, v23, v22
	v_add_f32_e32 v13, 1.0, v13
	v_rcp_f32_e32 v13, v13
	v_exp_f32_e32 v23, v23
	v_or_b32_e32 v88, 22, v34
	v_lshlrev_b32_e32 v24, 2, v88
	v_fma_f32 v3, v13, v3, -v19
	v_add_f32_e32 v13, 1.0, v23
	global_load_dword v82, v24, s[16:17]
	global_load_dword v83, v24, s[20:21]
	v_or_b32_e32 v89, 23, v34
	v_rcp_f32_e32 v13, v13
	v_and_b32_e32 v4, 0xffff0000, v4
	v_lshlrev_b32_e32 v24, 2, v89
	v_mul_f32_e32 v23, v4, v4
	global_load_dword v84, v24, s[16:17]
	global_load_dword v85, v24, s[20:21]
	v_fmamk_f32 v23, v23, 0xbdd2d3e7, v129
	v_mul_f32_e32 v23, v23, v4
	v_fma_f32 v13, v13, v22, -v19
	v_lshlrev_b32_e32 v22, 2, v91
	global_load_dword v92, v22, s[16:17]
	global_load_dword v93, v22, s[20:21]
	v_or_b32_e32 v94, 27, v34
	v_exp_f32_e32 v23, v23
	v_lshlrev_b32_e32 v22, 2, v94
	global_load_dword v95, v22, s[16:17]
	global_load_dword v96, v22, s[20:21]
	v_lshlrev_b32_e32 v97, 16, v5
	v_lshlrev_b32_e32 v22, 2, v98
	global_load_dword v99, v22, s[16:17]
	global_load_dword v100, v22, s[20:21]
	v_mul_f32_e32 v22, 0x3d372713, v97
	v_mul_f32_e32 v90, v39, v13
	v_add_f32_e32 v13, 1.0, v23
	v_lshlrev_b32_e32 v23, 2, v101
	v_mul_f32_e32 v22, v22, v97
	global_load_dword v102, v23, s[16:17]
	global_load_dword v103, v23, s[20:21]
	v_fma_f32 v22, v22, v97, v97
	v_mul_f32_e32 v22, 0xbfcc422a, v22
	v_mul_f32_e32 v104, 0x3fb8aa3b, v22
	global_load_dwordx4 v[22:25], v[6:7], off offset:16
	global_load_dwordx4 v[44:47], v[6:7], off
	v_rcp_f32_e32 v13, v13
	v_exp_f32_e32 v104, v104
	v_mul_f32_e32 v5, v105, v105
	v_fmamk_f32 v5, v5, 0xbdd2d3e7, v129
	v_mul_f32_e32 v5, v5, v105
	v_fma_f32 v4, v13, v4, -v19
	v_add_f32_e32 v13, 1.0, v104
	v_rcp_f32_e32 v13, v13
	v_exp_f32_e32 v5, v5
	v_mul_f32_e32 v106, v39, v4
	v_cvt_pk_bf16_f32 v11, v11, s0
	v_fma_f32 v4, v13, v97, -v19
	v_add_f32_e32 v5, 1.0, v5
	v_rcp_f32_e32 v104, v5
	v_fmac_f32_e32 v27, v15, v12
	v_mul_f32_e32 v5, v39, v4
	v_fma_f32 v16, v16, v90, v20
	v_fma_f32 v4, v104, v105, -v19
	v_mul_u32_u24_e32 v19, 0x110, v88
	v_add3_u32 v19, s15, v19, v33
	v_cvt_pk_bf16_f32 v16, v16, s0
	v_fmac_f32_e32 v21, v106, v17
	v_mul_f32_e32 v2, v39, v2
	v_mul_f32_e32 v3, v39, v3
	v_mul_f32_e32 v4, v39, v4
	v_mul_u32_u24_e32 v17, 0x110, v91
	v_add3_u32 v17, s15, v17, v33
	v_readlane_b32 s56, v252, 2
	v_readlane_b32 s57, v252, 3
	v_readlane_b32 s58, v252, 4
	v_readlane_b32 s59, v252, 5
	s_waitcnt vmcnt(16)
	v_fmac_f32_e32 v14, v26, v53
	v_cvt_pk_bf16_f32 v13, v14, s0
	v_mul_u32_u24_e32 v14, 0x110, v86
	v_add3_u32 v14, s15, v14, v33
	ds_write_b16 v14, v13 offset:34816
	s_waitcnt vmcnt(14)
	v_fmac_f32_e32 v55, v54, v52
	v_mul_u32_u24_e32 v14, 0x110, v87
	v_cvt_pk_bf16_f32 v13, v55, s0
	v_add3_u32 v14, s15, v14, v33
	ds_write_b16 v14, v13 offset:34816
	ds_write_b16 v35, v11 offset:49776
	v_cvt_pk_bf16_f32 v11, v27, s0
	ds_write_b16 v35, v11 offset:50048
	global_load_dwordx4 v[12:15], v[6:7], off offset:48
	global_load_dwordx4 v[52:55], v[6:7], off offset:32
	s_waitcnt vmcnt(14)
	v_fmac_f32_e32 v83, v58, v82
	v_cvt_pk_bf16_f32 v11, v83, s0
	ds_write_b16 v19, v11 offset:34816
	v_mul_u32_u24_e32 v19, 0x110, v89
	v_add3_u32 v19, s15, v19, v33
	v_or_b32_e32 v58, 35, v34
	s_waitcnt vmcnt(12)
	v_fmac_f32_e32 v85, v56, v84
	v_cvt_pk_bf16_f32 v11, v85, s0
	v_or_b32_e32 v56, 34, v34
	ds_write_b16 v19, v11 offset:34816
	v_lshlrev_b32_e32 v11, 2, v56
	v_lshlrev_b32_e32 v19, 2, v58
	global_load_dword v39, v11, s[16:17]
	s_nop 0
	global_load_dword v11, v11, s[20:21]
	s_nop 0
	global_load_dword v90, v19, s[16:17]
	global_load_dword v97, v19, s[20:21]
	ds_write_b16 v35, v16 offset:50864
	v_cvt_pk_bf16_f32 v16, v21, s0
	s_waitcnt vmcnt(14)
	v_fmac_f32_e32 v93, v92, v64
	ds_write_b16 v35, v16 offset:51136
	v_cvt_pk_bf16_f32 v16, v93, s0
	ds_write_b16 v17, v16 offset:34816
	s_waitcnt vmcnt(12)
	v_fmac_f32_e32 v96, v95, v63
	v_mul_u32_u24_e32 v17, 0x110, v94
	v_cvt_pk_bf16_f32 v16, v96, s0
	v_add3_u32 v17, s15, v17, v33
	ds_write_b16 v17, v16 offset:34816
	s_waitcnt vmcnt(10)
	v_fmac_f32_e32 v100, v69, v99
	v_mul_u32_u24_e32 v17, 0x110, v98
	v_cvt_pk_bf16_f32 v16, v100, s0
	v_add3_u32 v17, s15, v17, v33
	ds_write_b16 v17, v16 offset:34816
	s_waitcnt vmcnt(8)
	v_fmac_f32_e32 v103, v68, v102
	v_mul_u32_u24_e32 v17, 0x110, v101
	v_cvt_pk_bf16_f32 v16, v103, s0
	v_add3_u32 v17, s15, v17, v33
	ds_write_b16 v17, v16 offset:34816
	s_waitcnt vmcnt(6)
	v_cndmask_b32_e32 v16, 0, v45, vcc
	v_cmp_le_u32_e32 vcc, v34, v31
	v_or_b32_e32 v35, 38, v34
	v_or_b32_e32 v68, 39, v34
	v_cndmask_b32_e32 v17, 0, v44, vcc
	v_cvt_pk_bf16_f32 v16, v17, v16
	v_lshlrev_b32_e32 v17, 2, v35
	global_load_dword v63, v17, s[16:17]
	global_load_dword v64, v17, s[20:21]
	v_lshlrev_b32_e32 v19, 2, v68
	global_load_dword v69, v19, s[16:17]
	global_load_dword v92, v19, s[20:21]
	v_cvt_pk_bf16_f32 v17, v46, v47
	v_cmp_le_u32_e32 vcc, v76, v31
	global_load_dwordx4 v[44:47], v[6:7], off offset:80
	global_load_dwordx4 v[82:85], v[6:7], off offset:64
	v_cndmask_b32_e32 v19, 0, v17, vcc
	v_lshrrev_b32_e32 v17, 16, v17
	v_cmp_le_u32_e32 vcc, v77, v31
	v_or_b32_e32 v77, 47, v34
	s_waitcnt vmcnt(8)
	v_fmac_f32_e32 v11, v39, v73
	v_cndmask_b32_e32 v17, 0, v17, vcc
	v_cmp_gt_u32_e32 vcc, v31, v18
	v_perm_b32 v17, v17, v19, s19
	v_cvt_pk_bf16_f32 v11, v11, s0
	v_cndmask_b32_e32 v19, 0, v23, vcc
	v_cmp_le_u32_e32 vcc, v18, v31
	s_waitcnt vmcnt(6)
	v_fmac_f32_e32 v97, v90, v72
	s_waitcnt vmcnt(4)
	v_fmac_f32_e32 v64, v71, v63
	v_cndmask_b32_e32 v18, 0, v22, vcc
	v_cvt_pk_bf16_f32 v18, v18, v19
	v_cvt_pk_bf16_f32 v19, v24, v25
	v_cmp_le_u32_e32 vcc, v65, v31
	s_waitcnt vmcnt(2)
	v_fmac_f32_e32 v92, v70, v69
	v_cndmask_b32_e32 v20, 0, v19, vcc
	v_lshrrev_b32_e32 v19, 16, v19
	v_cmp_le_u32_e32 vcc, v78, v31
	s_nop 1
	v_cndmask_b32_e32 v19, 0, v19, vcc
	v_perm_b32 v19, v19, v20, s19
	ds_write_b128 v0, v[16:19]
	global_load_dwordx4 v[20:23], v[6:7], off offset:112
	global_load_dwordx4 v[24:27], v[6:7], off offset:96
	v_cmp_gt_u32_e32 vcc, v31, v36
	s_nop 1
	v_cndmask_b32_e32 v16, 0, v53, vcc
	v_cmp_le_u32_e32 vcc, v36, v31
	s_nop 1
	v_cndmask_b32_e32 v17, 0, v52, vcc
	v_cvt_pk_bf16_f32 v16, v17, v16
	v_cvt_pk_bf16_f32 v17, v54, v55
	v_cmp_le_u32_e32 vcc, v81, v31
	v_or_b32_e32 v52, 42, v34
	v_or_b32_e32 v55, 43, v34
	v_cndmask_b32_e32 v18, 0, v17, vcc
	v_lshrrev_b32_e32 v17, 16, v17
	v_cmp_le_u32_e32 vcc, v79, v31
	v_lshlrev_b32_e32 v19, 2, v55
	v_and_or_b32 v81, v30, 64, v32
	v_cndmask_b32_e32 v17, 0, v17, vcc
	v_perm_b32 v17, v17, v18, s19
	v_mul_u32_u24_e32 v18, 0x110, v56
	v_add3_u32 v18, s15, v18, v33
	ds_write_b16 v18, v11 offset:34816
	v_lshlrev_b32_e32 v18, 2, v52
	global_load_dword v53, v18, s[16:17]
	global_load_dword v54, v18, s[20:21]
	v_mul_u32_u24_e32 v18, 0x110, v58
	v_cvt_pk_bf16_f32 v11, v97, s0
	v_add3_u32 v18, s15, v18, v33
	v_cmp_gt_u32_e32 vcc, v31, v37
	global_load_dword v65, v19, s[16:17]
	global_load_dword v72, v19, s[20:21]
	ds_write_b16 v18, v11 offset:34816
	v_cndmask_b32_e32 v11, 0, v13, vcc
	v_cmp_le_u32_e32 vcc, v37, v31
	s_waitcnt vmcnt(2)
	v_fmac_f32_e32 v54, v53, v67
	v_cndmask_b32_e32 v12, 0, v12, vcc
	v_cvt_pk_bf16_f32 v18, v12, v11
	v_cvt_pk_bf16_f32 v11, v14, v15
	v_cmp_le_u32_e32 vcc, v59, v31
	v_or_b32_e32 v59, 46, v34
	s_waitcnt vmcnt(0)
	v_fmac_f32_e32 v72, v65, v66
	v_cndmask_b32_e32 v12, 0, v11, vcc
	v_lshrrev_b32_e32 v11, 16, v11
	v_cmp_le_u32_e32 vcc, v10, v31
	s_nop 1
	v_cndmask_b32_e32 v10, 0, v11, vcc
	v_perm_b32 v19, v10, v12, s19
	v_lshlrev_b32_e32 v10, 2, v59
	global_load_dword v73, v10, s[16:17]
	global_load_dword v76, v10, s[20:21]
	ds_write_b128 v0, v[16:19] offset:16
	v_lshlrev_b32_e32 v10, 2, v77
	v_mul_u32_u24_e32 v11, 0x110, v35
	global_load_dword v78, v10, s[16:17]
	global_load_dword v79, v10, s[20:21]
	v_cvt_pk_bf16_f32 v10, v64, s0
	v_add3_u32 v11, s15, v11, v33
	ds_write_b16 v11, v10 offset:34816
	global_load_dwordx4 v[10:13], v[6:7], off offset:144
	global_load_dwordx4 v[14:17], v[6:7], off offset:128
	v_mul_u32_u24_e32 v19, 0x110, v68
	v_cvt_pk_bf16_f32 v18, v92, s0
	v_add3_u32 v19, s15, v19, v33
	v_cmp_gt_u32_e32 vcc, v31, v38
	ds_write_b16 v19, v18 offset:34816
	s_waitcnt vmcnt(4)
	v_fmac_f32_e32 v76, v75, v73
	v_cndmask_b32_e32 v18, 0, v83, vcc
	v_cmp_le_u32_e32 vcc, v38, v31
	s_waitcnt vmcnt(2)
	v_fmac_f32_e32 v79, v74, v78
	v_cndmask_b32_e32 v19, 0, v82, vcc
	v_cvt_pk_bf16_f32 v36, v19, v18
	v_cvt_pk_bf16_f32 v18, v84, v85
	v_cmp_le_u32_e32 vcc, v86, v31
	v_or_b32_e32 v82, s4, v81
	s_nop 0
	v_cndmask_b32_e32 v19, 0, v18, vcc
	v_lshrrev_b32_e32 v18, 16, v18
	v_cmp_le_u32_e32 vcc, v87, v31
	s_nop 1
	v_cndmask_b32_e32 v18, 0, v18, vcc
	v_cmp_gt_u32_e32 vcc, v31, v40
	v_perm_b32 v37, v18, v19, s19
	s_nop 0
	v_cndmask_b32_e32 v18, 0, v45, vcc
	v_cmp_le_u32_e32 vcc, v40, v31
	s_nop 1
	v_cndmask_b32_e32 v19, 0, v44, vcc
	v_cvt_pk_bf16_f32 v38, v19, v18
	v_cvt_pk_bf16_f32 v18, v46, v47
	v_cmp_le_u32_e32 vcc, v88, v31
	s_nop 1
	v_cndmask_b32_e32 v19, 0, v18, vcc
	v_lshrrev_b32_e32 v18, 16, v18
	v_cmp_le_u32_e32 vcc, v89, v31
	s_nop 1
	v_cndmask_b32_e32 v18, 0, v18, vcc
	v_cmp_gt_u32_e32 vcc, v31, v41
	v_perm_b32 v39, v18, v19, s19
	ds_write_b128 v0, v[36:39] offset:32
	v_cndmask_b32_e32 v18, 0, v25, vcc
	v_cmp_le_u32_e32 vcc, v41, v31
	v_mul_u32_u24_e32 v41, 0x110, v52
	v_add3_u32 v41, s15, v41, v33
	v_cndmask_b32_e32 v19, 0, v24, vcc
	v_cvt_pk_bf16_f32 v18, v19, v18
	v_cvt_pk_bf16_f32 v19, v26, v27
	global_load_dwordx4 v[24:27], v[6:7], off offset:176
	global_load_dwordx4 v[36:39], v[6:7], off offset:160
	v_cmp_le_u32_e32 vcc, v91, v31
	s_nop 1
	v_cndmask_b32_e32 v40, 0, v19, vcc
	v_lshrrev_b32_e32 v19, 16, v19
	v_cmp_le_u32_e32 vcc, v94, v31
	s_nop 1
	v_cndmask_b32_e32 v19, 0, v19, vcc
	v_cmp_gt_u32_e32 vcc, v31, v42
	v_perm_b32 v19, v19, v40, s19
	v_cvt_pk_bf16_f32 v40, v54, s0
	v_cndmask_b32_e32 v21, 0, v21, vcc
	v_cmp_le_u32_e32 vcc, v42, v31
	ds_write_b16 v41, v40 offset:34816
	v_mul_u32_u24_e32 v41, 0x110, v55
	v_cndmask_b32_e32 v20, 0, v20, vcc
	v_cvt_pk_bf16_f32 v20, v20, v21
	v_cvt_pk_bf16_f32 v21, v22, v23
	v_cmp_le_u32_e32 vcc, v98, v31
	v_cvt_pk_bf16_f32 v40, v72, s0
	v_add3_u32 v41, s15, v41, v33
	v_cndmask_b32_e32 v22, 0, v21, vcc
	v_lshrrev_b32_e32 v21, 16, v21
	v_cmp_le_u32_e32 vcc, v101, v31
	ds_write_b16 v41, v40 offset:34816
	v_mul_u32_u24_e32 v23, 0x110, v77
	v_cndmask_b32_e32 v21, 0, v21, vcc
	v_perm_b32 v21, v21, v22, s19
	ds_write_b128 v0, v[18:21] offset:48
	v_mul_u32_u24_e32 v19, 0x110, v59
	v_cvt_pk_bf16_f32 v18, v76, s0
	v_add3_u32 v19, s15, v19, v33
	v_cmp_gt_u32_e32 vcc, v31, v43
	ds_write_b16 v19, v18 offset:34816
	v_cvt_pk_bf16_f32 v22, v79, s0
	v_add3_u32 v23, s15, v23, v33
	s_waitcnt vmcnt(2)
	v_cndmask_b32_e32 v15, 0, v15, vcc
	v_cmp_le_u32_e32 vcc, v43, v31
	global_load_dwordx4 v[18:21], v[6:7], off offset:208
	global_load_dwordx4 v[44:47], v[6:7], off offset:192
	ds_write_b16 v23, v22 offset:34816
	v_cndmask_b32_e32 v14, 0, v14, vcc
	v_or_b32_e32 v23, 50, v34
	v_cvt_pk_bf16_f32 v14, v14, v15
	v_cvt_pk_bf16_f32 v15, v16, v17
	v_or_b32_e32 v22, 51, v34
	v_lshlrev_b32_e32 v17, 2, v23
	v_cmp_le_u32_e32 vcc, v56, v31
	global_load_dword v40, v17, s[16:17]
	global_load_dword v41, v17, s[20:21]
	v_lshlrev_b32_e32 v17, 2, v22
	v_cndmask_b32_e32 v16, 0, v15, vcc
	v_lshrrev_b32_e32 v15, 16, v15
	global_load_dword v42, v17, s[16:17]
	global_load_dword v43, v17, s[20:21]
	v_cmp_le_u32_e32 vcc, v58, v31
	s_waitcnt vmcnt(2)
	v_fmac_f32_e32 v41, v40, v62
	v_cndmask_b32_e32 v15, 0, v15, vcc
	v_cmp_gt_u32_e32 vcc, v31, v48
	v_perm_b32 v15, v15, v16, s19
	s_waitcnt vmcnt(0)
	v_fmac_f32_e32 v43, v42, v61
	v_cndmask_b32_e32 v11, 0, v11, vcc
	v_cmp_le_u32_e32 vcc, v48, v31
	v_or_b32_e32 v48, 54, v34
	s_nop 0
	v_cndmask_b32_e32 v10, 0, v10, vcc
	v_cvt_pk_bf16_f32 v16, v10, v11
	v_cvt_pk_bf16_f32 v10, v12, v13
	v_cmp_le_u32_e32 vcc, v35, v31
	v_or_b32_e32 v35, 55, v34
	s_nop 0
	v_cndmask_b32_e32 v11, 0, v10, vcc
	v_lshrrev_b32_e32 v10, 16, v10
	v_cmp_le_u32_e32 vcc, v68, v31
	s_nop 1
	v_cndmask_b32_e32 v10, 0, v10, vcc
	v_perm_b32 v17, v10, v11, s19
	v_lshlrev_b32_e32 v10, 2, v48
	global_load_dword v53, v10, s[16:17]
	global_load_dword v54, v10, s[20:21]
	v_lshlrev_b32_e32 v10, 2, v35
	global_load_dword v56, v10, s[16:17]
	global_load_dword v58, v10, s[20:21]
	v_cmp_gt_u32_e32 vcc, v31, v49
	ds_write_b128 v0, v[14:17] offset:64
	s_waitcnt vmcnt(2)
	v_fmac_f32_e32 v54, v9, v53
	v_cndmask_b32_e32 v10, 0, v37, vcc
	v_cmp_le_u32_e32 vcc, v49, v31
	v_or_b32_e32 v49, 59, v34
	v_cvt_pk_bf16_f32 v9, v54, s0
	v_cndmask_b32_e32 v11, 0, v36, vcc
	v_cvt_pk_bf16_f32 v10, v11, v10
	v_cvt_pk_bf16_f32 v11, v38, v39
	v_cmp_le_u32_e32 vcc, v52, v31
	global_load_dwordx4 v[14:17], v[6:7], off offset:240
	global_load_dwordx4 v[36:39], v[6:7], off offset:224
	v_cndmask_b32_e32 v12, 0, v11, vcc
	v_lshrrev_b32_e32 v11, 16, v11
	v_cmp_le_u32_e32 vcc, v55, v31
	v_or_b32_e32 v52, 58, v34
	s_waitcnt vmcnt(2)
	v_fmac_f32_e32 v58, v8, v56
	v_cndmask_b32_e32 v6, 0, v11, vcc
	v_perm_b32 v11, v6, v12, s19
	v_lshlrev_b32_e32 v6, 2, v52
	global_load_dword v55, v6, s[16:17]
	global_load_dword v63, v6, s[20:21]
	v_lshlrev_b32_e32 v6, 2, v49
	v_cmp_gt_u32_e32 vcc, v31, v51
	global_load_dword v64, v6, s[16:17]
	global_load_dword v65, v6, s[20:21]
	v_cndmask_b32_e32 v6, 0, v25, vcc
	v_cmp_le_u32_e32 vcc, v51, v31
	s_waitcnt vmcnt(2)
	v_fmac_f32_e32 v63, v55, v2
	v_cndmask_b32_e32 v7, 0, v24, vcc
	v_cvt_pk_bf16_f32 v12, v7, v6
	v_cvt_pk_bf16_f32 v6, v26, v27
	v_cmp_le_u32_e32 vcc, v59, v31
	v_mul_u32_u24_e32 v26, 0x110, v22
	v_cvt_pk_bf16_f32 v27, v41, s0
	v_cndmask_b32_e32 v7, 0, v6, vcc
	v_lshrrev_b32_e32 v6, 16, v6
	v_cmp_le_u32_e32 vcc, v77, v31
	v_add3_u32 v26, s15, v26, v33
	v_cvt_pk_bf16_f32 v2, v63, s0
	v_cndmask_b32_e32 v6, 0, v6, vcc
	v_perm_b32 v13, v6, v7, s19
	ds_write_b128 v0, v[10:13] offset:80
	v_or_b32_e32 v11, 62, v34
	v_or_b32_e32 v10, 63, v34
	v_lshlrev_b32_e32 v7, 2, v11
	global_load_dword v12, v7, s[16:17]
	global_load_dword v13, v7, s[20:21]
	v_lshlrev_b32_e32 v7, 2, v10
	global_load_dword v24, v7, s[16:17]
	global_load_dword v25, v7, s[20:21]
	v_cmp_gt_u32_e32 vcc, v31, v57
	s_waitcnt vmcnt(4)
	v_fmac_f32_e32 v65, v64, v3
	s_waitcnt vmcnt(2)
	v_fmac_f32_e32 v13, v5, v12
	v_cndmask_b32_e32 v6, 0, v45, vcc
	v_cmp_le_u32_e32 vcc, v57, v31
	v_cvt_pk_bf16_f32 v5, v13, s0
	s_waitcnt vmcnt(0)
	v_fmac_f32_e32 v25, v4, v24
	v_cndmask_b32_e32 v7, 0, v44, vcc
	v_cvt_pk_bf16_f32 v6, v7, v6
	v_mul_u32_u24_e32 v7, 0x110, v23
	v_add3_u32 v7, s15, v7, v33
	ds_write_b16 v7, v27 offset:34816
	v_cvt_pk_bf16_f32 v7, v43, s0
	ds_write_b16 v26, v7 offset:34816
	v_cvt_pk_bf16_f32 v7, v46, v47
	v_cmp_le_u32_e32 vcc, v23, v31
	s_nop 1
	v_cndmask_b32_e32 v23, 0, v7, vcc
	v_lshrrev_b32_e32 v7, 16, v7
	v_cmp_le_u32_e32 vcc, v22, v31
	s_nop 1
	v_cndmask_b32_e32 v7, 0, v7, vcc
	v_perm_b32 v7, v7, v23, s19
	v_cmp_gt_u32_e32 vcc, v31, v60
	ds_write_b64 v0, v[6:7] offset:96
	s_nop 0
	v_cndmask_b32_e32 v6, 0, v19, vcc
	v_cmp_le_u32_e32 vcc, v60, v31
	s_nop 1
	v_cndmask_b32_e32 v7, 0, v18, vcc
	v_cvt_pk_bf16_f32 v6, v7, v6
	v_mul_u32_u24_e32 v7, 0x110, v48
	v_add3_u32 v7, s15, v7, v33
	v_mul_u32_u24_e32 v18, 0x110, v35
	v_add3_u32 v18, s15, v18, v33
	ds_write_b16 v7, v9 offset:34816
	v_cvt_pk_bf16_f32 v7, v58, s0
	ds_write_b16 v18, v7 offset:34816
	v_cvt_pk_bf16_f32 v7, v20, v21
	v_cmp_le_u32_e32 vcc, v48, v31
	s_nop 1
	v_cndmask_b32_e32 v8, 0, v7, vcc
	v_lshrrev_b32_e32 v7, 16, v7
	v_cmp_le_u32_e32 vcc, v35, v31
	s_nop 1
	v_cndmask_b32_e32 v7, 0, v7, vcc
	v_perm_b32 v7, v7, v8, s19
	v_cmp_gt_u32_e32 vcc, v31, v29
	ds_write_b64 v0, v[6:7] offset:104
	v_mul_u32_u24_e32 v8, 0x110, v49
	v_cndmask_b32_e32 v6, 0, v37, vcc
	v_cmp_le_u32_e32 vcc, v29, v31
	v_add3_u32 v8, s15, v8, v33
	s_nop 0
	v_cndmask_b32_e32 v7, 0, v36, vcc
	v_cvt_pk_bf16_f32 v6, v7, v6
	v_mul_u32_u24_e32 v7, 0x110, v52
	v_add3_u32 v7, s15, v7, v33
	ds_write_b16 v7, v2 offset:34816
	v_cvt_pk_bf16_f32 v2, v65, s0
	ds_write_b16 v8, v2 offset:34816
	v_cvt_pk_bf16_f32 v2, v38, v39
	v_cmp_le_u32_e32 vcc, v52, v31
	s_nop 1
	v_cndmask_b32_e32 v3, 0, v2, vcc
	v_lshrrev_b32_e32 v2, 16, v2
	v_cmp_le_u32_e32 vcc, v49, v31
	s_nop 1
	v_cndmask_b32_e32 v2, 0, v2, vcc
	v_cmp_gt_u32_e32 vcc, v31, v28
	v_perm_b32 v7, v2, v3, s19
	ds_write_b64 v0, v[6:7] offset:112
	v_cndmask_b32_e32 v2, 0, v15, vcc
	v_cmp_le_u32_e32 vcc, v28, v31
	v_mul_u32_u24_e32 v6, 0x110, v10
	v_add3_u32 v6, s15, v6, v33
	v_cndmask_b32_e32 v3, 0, v14, vcc
	v_cvt_pk_bf16_f32 v2, v3, v2
	v_mul_u32_u24_e32 v3, 0x110, v11
	v_add3_u32 v3, s15, v3, v33
	ds_write_b16 v3, v5 offset:34816
	v_cvt_pk_bf16_f32 v3, v25, s0
	ds_write_b16 v6, v3 offset:34816
	v_cvt_pk_bf16_f32 v3, v16, v17
	v_cmp_le_u32_e32 vcc, v11, v31
	v_mul_u32_u24_e32 v7, 0x88, v81
	v_lshlrev_b32_e32 v81, 2, v81
	v_cndmask_b32_e32 v4, 0, v3, vcc
	v_lshrrev_b32_e32 v3, 16, v3
	v_cmp_le_u32_e32 vcc, v10, v31
	s_nop 1
	v_cndmask_b32_e32 v3, 0, v3, vcc
	v_perm_b32 v3, v3, v4, s19
	ds_write_b64 v0, v[2:3] offset:120
	v_bfe_u32 v0, v50, 4, 2
	v_and_b32_e32 v2, 0x4f, v50
	v_lshl_add_u32 v6, v0, 4, s15
	v_mul_u32_u24_e32 v2, 0x88, v2
	v_lshl_add_u32 v51, v2, 1, v6
	s_waitcnt lgkmcnt(0)
	s_barrier
	ds_read_b128 v[2:5], v51 offset:34816
	ds_read_b128 v[72:75], v51 offset:34880
	ds_read_b128 v[14:17], v51 offset:39168
	ds_read_b128 v[76:79], v51 offset:39232
	ds_read_b128 v[22:25], v51 offset:43520
	ds_read_b128 v[84:87], v51 offset:43584
	ds_read_b128 v[30:33], v51 offset:47872
	ds_read_b128 v[88:91], v51 offset:47936
	v_lshl_add_u32 v83, v7, 1, v6
	ds_read_b128 v[6:9], v83
	ds_read_b128 v[34:37], v83 offset:4352
	ds_read_b128 v[52:55], v83 offset:8704
	ds_read_b128 v[68:71], v83 offset:13056
	s_waitcnt lgkmcnt(3)
	v_mfma_f32_16x16x32_bf16 v[10:13], v[2:5], v[6:9], 0
	ds_read_b128 v[100:103], v51 offset:48000
	v_and_b32_e32 v50, 64, v50
	v_mfma_f32_16x16x32_bf16 v[18:21], v[14:17], v[6:9], 0
	v_mfma_f32_16x16x32_bf16 v[26:29], v[22:25], v[6:9], 0
	v_mfma_f32_16x16x32_bf16 v[6:9], v[30:33], v[6:9], 0
	s_waitcnt lgkmcnt(3)
	v_mfma_f32_16x16x32_bf16 v[38:41], v[2:5], v[34:37], 0
	v_mfma_f32_16x16x32_bf16 v[42:45], v[14:17], v[34:37], 0
	v_mfma_f32_16x16x32_bf16 v[46:49], v[22:25], v[34:37], 0
	v_mfma_f32_16x16x32_bf16 v[34:37], v[30:33], v[34:37], 0
	s_waitcnt lgkmcnt(2)
	v_mfma_f32_16x16x32_bf16 v[56:59], v[2:5], v[52:55], 0
	v_mfma_f32_16x16x32_bf16 v[60:63], v[14:17], v[52:55], 0
	v_mfma_f32_16x16x32_bf16 v[64:67], v[22:25], v[52:55], 0
	v_mfma_f32_16x16x32_bf16 v[52:55], v[30:33], v[52:55], 0
	s_waitcnt lgkmcnt(1)
	v_mfma_f32_16x16x32_bf16 v[2:5], v[2:5], v[68:71], 0
	v_mfma_f32_16x16x32_bf16 v[14:17], v[14:17], v[68:71], 0
	v_mfma_f32_16x16x32_bf16 v[22:25], v[22:25], v[68:71], 0
	v_mfma_f32_16x16x32_bf16 v[30:33], v[30:33], v[68:71], 0
	ds_read_b128 v[68:71], v83 offset:64
	s_waitcnt lgkmcnt(0)
	v_mfma_f32_16x16x32_bf16 v[10:13], v[72:75], v[68:71], v[10:13]
	v_mfma_f32_16x16x32_bf16 v[18:21], v[76:79], v[68:71], v[18:21]
	v_mfma_f32_16x16x32_bf16 v[26:29], v[84:87], v[68:71], v[26:29]
	v_mfma_f32_16x16x32_bf16 v[6:9], v[88:91], v[68:71], v[6:9]
	ds_read_b128 v[68:71], v83 offset:4416
	s_waitcnt lgkmcnt(0)
	v_mfma_f32_16x16x32_bf16 v[38:41], v[72:75], v[68:71], v[38:41]
	v_mfma_f32_16x16x32_bf16 v[42:45], v[76:79], v[68:71], v[42:45]
	v_mfma_f32_16x16x32_bf16 v[46:49], v[84:87], v[68:71], v[46:49]
	v_mfma_f32_16x16x32_bf16 v[34:37], v[88:91], v[68:71], v[34:37]
	ds_read_b128 v[68:71], v83 offset:8768
	s_waitcnt lgkmcnt(0)
	v_mfma_f32_16x16x32_bf16 v[92:95], v[76:79], v[68:71], v[60:63]
	s_nop 2
	ds_read_b128 v[60:63], v83 offset:13120
	v_mfma_f32_16x16x32_bf16 v[56:59], v[72:75], v[68:71], v[56:59]
	v_mfma_f32_16x16x32_bf16 v[96:99], v[84:87], v[68:71], v[64:67]
	v_mfma_f32_16x16x32_bf16 v[52:55], v[88:91], v[68:71], v[52:55]
	s_nop 1
	ds_read_b128 v[66:69], v51 offset:34944
	s_waitcnt lgkmcnt(1)
	v_mfma_f32_16x16x32_bf16 v[2:5], v[72:75], v[60:63], v[2:5]
	v_mfma_f32_16x16x32_bf16 v[70:73], v[88:91], v[60:63], v[30:33]
	s_nop 2
	ds_read_b128 v[30:33], v83 offset:128
	v_mfma_f32_16x16x32_bf16 v[14:17], v[76:79], v[60:63], v[14:17]
	s_waitcnt lgkmcnt(0)
	v_mfma_f32_16x16x32_bf16 v[74:77], v[66:69], v[30:33], v[10:13]
	s_nop 2
	ds_read_b128 v[10:13], v51 offset:39296
	v_mfma_f32_16x16x32_bf16 v[22:25], v[84:87], v[60:63], v[22:25]
	v_mfma_f32_16x16x32_bf16 v[104:107], v[100:103], v[30:33], v[6:9]
	s_nop 2
	ds_read_b128 v[6:9], v83 offset:4480
	s_waitcnt lgkmcnt(1)
	v_mfma_f32_16x16x32_bf16 v[84:87], v[10:13], v[30:33], v[18:21]
	s_nop 2
	ds_read_b128 v[18:21], v51 offset:43648
	s_waitcnt lgkmcnt(1)
	v_mfma_f32_16x16x32_bf16 v[108:111], v[66:69], v[6:9], v[38:41]
	v_mfma_f32_16x16x32_bf16 v[112:115], v[10:13], v[6:9], v[42:45]
	s_waitcnt lgkmcnt(0)
	v_mfma_f32_16x16x32_bf16 v[116:119], v[18:21], v[6:9], v[46:49]
	v_mfma_f32_16x16x32_bf16 v[62:65], v[100:103], v[6:9], v[34:37]
	ds_read_b128 v[6:9], v83 offset:8832
	s_waitcnt lgkmcnt(0)
	v_mfma_f32_16x16x32_bf16 v[42:45], v[100:103], v[6:9], v[52:55]
	s_nop 2
	ds_read_b128 v[52:55], v83 offset:13184
	v_mfma_f32_16x16x32_bf16 v[88:91], v[18:21], v[30:33], v[26:29]
	ds_read_b128 v[30:33], v51 offset:35008
	v_mfma_f32_16x16x32_bf16 v[46:49], v[18:21], v[6:9], v[96:99]
	s_waitcnt lgkmcnt(1)
	v_mfma_f32_16x16x32_bf16 v[26:29], v[66:69], v[52:55], v[2:5]
	v_mfma_f32_16x16x32_bf16 v[2:5], v[18:21], v[52:55], v[22:25]
	ds_read_b128 v[18:21], v51 offset:39360
	v_mfma_f32_16x16x32_bf16 v[38:41], v[66:69], v[6:9], v[56:59]
	v_mfma_f32_16x16x32_bf16 v[34:37], v[10:13], v[6:9], v[92:95]
	v_mfma_f32_16x16x32_bf16 v[6:9], v[10:13], v[52:55], v[14:17]
	v_mfma_f32_16x16x32_bf16 v[10:13], v[100:103], v[52:55], v[70:73]
	ds_read_b128 v[52:55], v83 offset:192
	ds_read_b128 v[22:25], v51 offset:43712
	ds_read_b128 v[14:17], v51 offset:48064
	v_lshlrev_b32_e32 v70, 3, v0
	v_lshlrev_b32_e32 v0, 1, v50
	v_lshl_add_u64 v[50:51], s[6:7], 0, v[0:1]
	v_mov_b32_e32 v71, v1
	s_waitcnt lgkmcnt(2)
	v_mfma_f32_16x16x32_bf16 v[92:95], v[30:33], v[52:55], v[74:77]
	ds_read_b128 v[100:103], v83 offset:4544
	s_nop 1
	v_lshl_add_u64 v[74:75], v[50:51], 0, v[70:71]
	v_mad_u64_u32 v[72:73], s[0:1], v82, s3, v[74:75]
	v_mfma_f32_16x16x32_bf16 v[96:99], v[18:21], v[52:55], v[84:87]
	s_lshl_b64 s[0:1], s[88:89], 2
	s_add_u32 s12, s42, s0
	s_addc_u32 s13, s43, s1
	s_waitcnt lgkmcnt(2)
	v_mfma_f32_16x16x32_bf16 v[86:89], v[22:25], v[52:55], v[88:91]
	global_load_dword v85, v81, s[12:13]
	v_or_b32_e32 v84, 16, v82
	v_mad_u64_u32 v[78:79], s[0:1], v84, s3, v[74:75]
	global_load_dwordx2 v[90:91], v[72:73], off
	s_waitcnt lgkmcnt(1)
	v_mfma_f32_16x16x32_bf16 v[66:69], v[14:17], v[52:55], v[104:107]
	s_cmpk_gt_u32 s10, 0xff
	s_waitcnt vmcnt(1)
	v_add_f32_e32 v87, v87, v85
	global_load_dwordx2 v[104:105], v[72:73], off offset:32
	s_waitcnt lgkmcnt(0)
	v_mfma_f32_16x16x32_bf16 v[58:61], v[30:33], v[100:103], v[108:111]
	global_load_dwordx2 v[106:107], v[72:73], off offset:64
	s_nop 1
	global_load_dwordx2 v[108:109], v[72:73], off offset:96
	s_waitcnt vmcnt(3)
	v_lshlrev_b32_e32 v72, 16, v90
	v_mul_f32_e32 v73, v72, v72
	v_and_b32_e32 v90, 0xffff0000, v90
	v_fmamk_f32 v73, v73, 0xbdd2d3e7, v129
	v_mul_f32_e32 v76, v90, v90
	v_mul_f32_e32 v73, v73, v72
	v_fmamk_f32 v76, v76, 0xbdd2d3e7, v129
	v_mul_f32_e32 v76, v76, v90
	v_exp_f32_e32 v73, v73
	v_exp_f32_e32 v110, v76
	v_add_f32_e32 v86, v86, v85
	v_add_f32_e32 v73, 1.0, v73
	v_rcp_f32_e32 v73, v73
	v_add_f32_e32 v110, 1.0, v110
	v_rcp_f32_e32 v110, v110
	v_add_f32_e32 v88, v88, v85
	v_mul_f32_e32 v72, v73, v72
	v_add_f32_e32 v73, v92, v85
	v_mul_f32_e32 v72, v72, v73
	v_mul_f32_e32 v73, v110, v90
	v_add_f32_e32 v90, v93, v85
	v_lshlrev_b32_e32 v92, 16, v91
	v_mul_f32_e32 v73, v73, v90
	v_mul_f32_e32 v90, v92, v92
	v_and_b32_e32 v91, 0xffff0000, v91
	v_fmamk_f32 v90, v90, 0xbdd2d3e7, v129
	v_mul_f32_e32 v93, v91, v91
	v_mul_f32_e32 v90, v90, v92
	v_fmamk_f32 v93, v93, 0xbdd2d3e7, v129
	v_mul_f32_e32 v93, v93, v91
	v_exp_f32_e32 v90, v90
	v_exp_f32_e32 v93, v93
	v_add_f32_e32 v89, v89, v85
	v_add_f32_e32 v90, 1.0, v90
	v_rcp_f32_e32 v110, v90
	v_cvt_pk_bf16_f32 v90, v72, v73
	v_add_f32_e32 v72, 1.0, v93
	v_rcp_f32_e32 v72, v72
	v_mul_f32_e32 v73, v110, v92
	v_add_f32_e32 v92, v94, v85
	v_mul_f32_e32 v73, v73, v92
	v_mul_f32_e32 v72, v72, v91
	v_add_f32_e32 v91, v95, v85
	v_mul_f32_e32 v72, v72, v91
	v_cvt_pk_bf16_f32 v91, v73, v72
	v_mov_b64_e32 v[72:73], s[50:51]
	v_mad_u64_u32 v[92:93], s[0:1], v82, s3, v[72:73]
	v_lshl_add_u64 v[92:93], v[92:93], 0, s[8:9]
	v_lshl_add_u64 v[92:93], v[92:93], 0, v[0:1]
	v_lshl_add_u64 v[92:93], v[92:93], 0, v[70:71]
	global_store_dwordx2 v[92:93], v[90:91], off
	v_add_f32_e32 v67, v67, v85
	v_add_f32_e32 v66, v66, v85
	global_load_dwordx2 v[76:77], v[78:79], off
	v_add_f32_e32 v68, v68, v85
	v_add_f32_e32 v69, v69, v85
	v_mfma_f32_16x16x32_bf16 v[54:57], v[18:21], v[100:103], v[112:115]
	s_waitcnt vmcnt(4)
	v_lshlrev_b32_e32 v94, 16, v104
	v_mul_f32_e32 v95, v94, v94
	v_and_b32_e32 v104, 0xffff0000, v104
	v_fmamk_f32 v95, v95, 0xbdd2d3e7, v129
	v_mul_f32_e32 v110, v104, v104
	v_mul_f32_e32 v95, v95, v94
	v_fmamk_f32 v110, v110, 0xbdd2d3e7, v129
	v_mul_f32_e32 v110, v110, v104
	v_exp_f32_e32 v95, v95
	v_exp_f32_e32 v110, v110
	v_mfma_f32_16x16x32_bf16 v[50:53], v[22:25], v[100:103], v[116:119]
	v_add_f32_e32 v95, 1.0, v95
	v_rcp_f32_e32 v95, v95
	v_add_f32_e32 v90, 1.0, v110
	v_rcp_f32_e32 v90, v90
	v_mfma_f32_16x16x32_bf16 v[62:65], v[14:17], v[100:103], v[62:65]
	v_mul_f32_e32 v91, v95, v94
	v_add_f32_e32 v94, v96, v85
	v_mul_f32_e32 v91, v91, v94
	v_mul_f32_e32 v90, v90, v104
	v_add_f32_e32 v94, v97, v85
	v_mul_f32_e32 v90, v90, v94
	v_lshlrev_b32_e32 v94, 16, v105
	v_mul_f32_e32 v95, v94, v94
	v_and_b32_e32 v96, 0xffff0000, v105
	v_fmamk_f32 v95, v95, 0xbdd2d3e7, v129
	v_mul_f32_e32 v97, v96, v96
	v_mul_f32_e32 v95, v95, v94
	v_fmamk_f32 v97, v97, 0xbdd2d3e7, v129
	v_mul_f32_e32 v97, v97, v96
	v_exp_f32_e32 v95, v95
	v_exp_f32_e32 v97, v97
	v_cvt_pk_bf16_f32 v90, v91, v90
	v_add_f32_e32 v95, 1.0, v95
	v_rcp_f32_e32 v95, v95
	v_add_f32_e32 v91, 1.0, v97
	v_rcp_f32_e32 v91, v91
	v_mul_f32_e32 v94, v95, v94
	v_add_f32_e32 v95, v98, v85
	v_mul_f32_e32 v94, v94, v95
	v_mul_f32_e32 v91, v91, v96
	v_add_f32_e32 v95, v99, v85
	v_mul_f32_e32 v91, v91, v95
	s_waitcnt vmcnt(3)
	v_and_b32_e32 v96, 0xffff0000, v106
	v_cvt_pk_bf16_f32 v91, v94, v91
	v_lshlrev_b32_e32 v94, 16, v106
	v_mul_f32_e32 v97, v96, v96
	v_mul_f32_e32 v95, v94, v94
	v_fmamk_f32 v97, v97, 0xbdd2d3e7, v129
	v_fmamk_f32 v95, v95, 0xbdd2d3e7, v129
	v_mul_f32_e32 v97, v97, v96
	v_mul_f32_e32 v95, v95, v94
	v_exp_f32_e32 v97, v97
	v_exp_f32_e32 v95, v95
	global_store_dwordx2 v[92:93], v[90:91], off offset:32
	v_add_f32_e32 v90, 1.0, v97
	v_add_f32_e32 v95, 1.0, v95
	v_rcp_f32_e32 v90, v90
	v_rcp_f32_e32 v95, v95
	v_mul_f32_e32 v90, v90, v96
	v_mul_f32_e32 v91, v95, v94
	v_mul_f32_e32 v87, v90, v87
	v_lshlrev_b32_e32 v90, 16, v107
	v_and_b32_e32 v94, 0xffff0000, v107
	v_mul_f32_e32 v86, v91, v86
	v_mul_f32_e32 v91, v90, v90
	v_mul_f32_e32 v95, v94, v94
	v_fmamk_f32 v91, v91, 0xbdd2d3e7, v129
	v_fmamk_f32 v95, v95, 0xbdd2d3e7, v129
	v_mul_f32_e32 v91, v91, v90
	v_mul_f32_e32 v95, v95, v94
	v_exp_f32_e32 v91, v91
	v_exp_f32_e32 v95, v95
	v_cvt_pk_bf16_f32 v86, v86, v87
	v_add_f32_e32 v91, 1.0, v91
	v_add_f32_e32 v87, 1.0, v95
	v_rcp_f32_e32 v91, v91
	v_rcp_f32_e32 v87, v87
	v_mul_f32_e32 v90, v91, v90
	v_mul_f32_e32 v87, v87, v94
	v_mul_f32_e32 v88, v90, v88
	v_mul_f32_e32 v87, v87, v89
	s_waitcnt vmcnt(3)
	v_and_b32_e32 v90, 0xffff0000, v108
	v_cvt_pk_bf16_f32 v87, v88, v87
	v_lshlrev_b32_e32 v88, 16, v108
	v_mul_f32_e32 v91, v90, v90
	v_mul_f32_e32 v89, v88, v88
	v_fmamk_f32 v91, v91, 0xbdd2d3e7, v129
	v_fmamk_f32 v89, v89, 0xbdd2d3e7, v129
	v_mul_f32_e32 v91, v91, v90
	v_mul_f32_e32 v89, v89, v88
	v_exp_f32_e32 v91, v91
	v_exp_f32_e32 v89, v89
	global_store_dwordx2 v[92:93], v[86:87], off offset:64
	v_add_f32_e32 v86, 1.0, v91
	v_add_f32_e32 v89, 1.0, v89
	v_rcp_f32_e32 v86, v86
	v_rcp_f32_e32 v89, v89
	v_mul_f32_e32 v86, v86, v90
	v_mul_f32_e32 v87, v89, v88
	v_mul_f32_e32 v67, v86, v67
	v_lshlrev_b32_e32 v86, 16, v109
	v_and_b32_e32 v88, 0xffff0000, v109
	v_mul_f32_e32 v66, v87, v66
	v_mul_f32_e32 v87, v86, v86
	v_mul_f32_e32 v89, v88, v88
	v_fmamk_f32 v87, v87, 0xbdd2d3e7, v129
	v_fmamk_f32 v89, v89, 0xbdd2d3e7, v129
	v_mul_f32_e32 v87, v87, v86
	v_mul_f32_e32 v89, v89, v88
	v_exp_f32_e32 v87, v87
	v_exp_f32_e32 v89, v89
	v_cvt_pk_bf16_f32 v66, v66, v67
	global_load_dwordx2 v[90:91], v[78:79], off offset:32
	v_add_f32_e32 v87, 1.0, v87
	v_add_f32_e32 v67, 1.0, v89
	v_rcp_f32_e32 v87, v87
	v_rcp_f32_e32 v67, v67
	v_mul_f32_e32 v86, v87, v86
	v_mul_f32_e32 v67, v67, v88
	v_mul_f32_e32 v68, v68, v86
	v_mul_f32_e32 v67, v69, v67
	v_cvt_pk_bf16_f32 v67, v68, v67
	global_store_dwordx2 v[92:93], v[66:67], off offset:96
	global_load_dword v85, v81, s[12:13] offset:64
	ds_read_b128 v[86:89], v83 offset:8896
	global_load_dwordx2 v[92:93], v[78:79], off offset:64
	global_load_dwordx2 v[94:95], v[78:79], off offset:96
	s_waitcnt vmcnt(7)
	v_lshlrev_b32_e32 v79, 16, v76
	v_and_b32_e32 v76, 0xffff0000, v76
	v_mul_f32_e32 v67, v76, v76
	v_mul_f32_e32 v66, v79, v79
	v_fmamk_f32 v67, v67, 0xbdd2d3e7, v129
	v_fmamk_f32 v66, v66, 0xbdd2d3e7, v129
	v_mul_f32_e32 v67, v67, v76
	v_mul_f32_e32 v66, v66, v79
	v_exp_f32_e32 v96, v67
	v_exp_f32_e32 v66, v66
	v_or_b32_e32 v78, 32, v82
	v_mad_u64_u32 v[68:69], s[0:1], v78, s3, v[74:75]
	v_add_f32_e32 v96, 1.0, v96
	v_add_f32_e32 v66, 1.0, v66
	v_rcp_f32_e32 v96, v96
	v_rcp_f32_e32 v97, v66
	global_load_dwordx2 v[66:67], v[68:69], off
	s_waitcnt lgkmcnt(0)
	v_mfma_f32_16x16x32_bf16 v[38:41], v[30:33], v[86:89], v[38:41]
	v_mul_f32_e32 v76, v96, v76
	v_mul_f32_e32 v79, v97, v79
	s_waitcnt vmcnt(3)
	v_add_f32_e32 v59, v59, v85
	v_add_f32_e32 v58, v58, v85
	v_mul_f32_e32 v59, v76, v59
	v_lshlrev_b32_e32 v76, 16, v77
	v_and_b32_e32 v77, 0xffff0000, v77
	v_mul_f32_e32 v58, v79, v58
	v_mul_f32_e32 v79, v76, v76
	v_mul_f32_e32 v96, v77, v77
	v_fmamk_f32 v79, v79, 0xbdd2d3e7, v129
	v_fmamk_f32 v96, v96, 0xbdd2d3e7, v129
	v_mul_f32_e32 v79, v79, v76
	v_mul_f32_e32 v96, v96, v77
	v_exp_f32_e32 v79, v79
	v_exp_f32_e32 v96, v96
	v_cvt_pk_bf16_f32 v58, v58, v59
	v_add_f32_e32 v60, v60, v85
	v_add_f32_e32 v79, 1.0, v79
	v_add_f32_e32 v59, 1.0, v96
	v_rcp_f32_e32 v79, v79
	v_rcp_f32_e32 v59, v59
	v_add_f32_e32 v61, v61, v85
	v_add_f32_e32 v55, v55, v85
	v_mul_f32_e32 v76, v79, v76
	v_mul_f32_e32 v59, v59, v77
	v_mul_f32_e32 v60, v76, v60
	v_mul_f32_e32 v59, v59, v61
	v_and_b32_e32 v79, 0xffff0000, v90
	v_cvt_pk_bf16_f32 v59, v60, v59
	v_mad_u64_u32 v[60:61], s[0:1], v84, s3, v[72:73]
	v_lshlrev_b32_e32 v76, 16, v90
	v_mul_f32_e32 v84, v79, v79
	v_mul_f32_e32 v77, v76, v76
	v_fmamk_f32 v84, v84, 0xbdd2d3e7, v129
	v_fmamk_f32 v77, v77, 0xbdd2d3e7, v129
	v_mul_f32_e32 v84, v84, v79
	v_mul_f32_e32 v77, v77, v76
	v_exp_f32_e32 v84, v84
	v_lshl_add_u64 v[60:61], v[60:61], 0, s[8:9]
	v_exp_f32_e32 v77, v77
	v_lshl_add_u64 v[60:61], v[60:61], 0, v[0:1]
	v_lshl_add_u64 v[60:61], v[60:61], 0, v[70:71]
	global_store_dwordx2 v[60:61], v[58:59], off
	v_add_f32_e32 v58, 1.0, v84
	v_add_f32_e32 v77, 1.0, v77
	v_rcp_f32_e32 v58, v58
	v_rcp_f32_e32 v77, v77
	v_add_f32_e32 v54, v54, v85
	v_add_f32_e32 v56, v56, v85
	v_mul_f32_e32 v58, v58, v79
	v_mul_f32_e32 v59, v77, v76
	v_mul_f32_e32 v55, v58, v55
	v_lshlrev_b32_e32 v58, 16, v91
	v_and_b32_e32 v76, 0xffff0000, v91
	v_mul_f32_e32 v54, v59, v54
	v_mul_f32_e32 v59, v58, v58
	v_mul_f32_e32 v77, v76, v76
	v_fmamk_f32 v59, v59, 0xbdd2d3e7, v129
	v_fmamk_f32 v77, v77, 0xbdd2d3e7, v129
	v_mul_f32_e32 v59, v59, v58
	v_mul_f32_e32 v77, v77, v76
	v_exp_f32_e32 v59, v59
	v_exp_f32_e32 v77, v77
	v_cvt_pk_bf16_f32 v54, v54, v55
	v_add_f32_e32 v57, v57, v85
	v_add_f32_e32 v59, 1.0, v59
	v_add_f32_e32 v55, 1.0, v77
	v_rcp_f32_e32 v59, v59
	v_rcp_f32_e32 v55, v55
	v_add_f32_e32 v51, v51, v85
	v_add_f32_e32 v50, v50, v85
	v_mul_f32_e32 v58, v59, v58
	v_mul_f32_e32 v55, v55, v76
	v_mul_f32_e32 v56, v58, v56
	v_mul_f32_e32 v55, v55, v57
	s_waitcnt vmcnt(3)
	v_and_b32_e32 v58, 0xffff0000, v92
	v_cvt_pk_bf16_f32 v55, v56, v55
	v_lshlrev_b32_e32 v56, 16, v92
	v_mul_f32_e32 v59, v58, v58
	v_mul_f32_e32 v57, v56, v56
	v_fmamk_f32 v59, v59, 0xbdd2d3e7, v129
	v_fmamk_f32 v57, v57, 0xbdd2d3e7, v129
	v_mul_f32_e32 v59, v59, v58
	v_mul_f32_e32 v57, v57, v56
	v_exp_f32_e32 v59, v59
	v_exp_f32_e32 v57, v57
	global_store_dwordx2 v[60:61], v[54:55], off offset:32
	v_add_f32_e32 v52, v52, v85
	v_add_f32_e32 v54, 1.0, v59
	v_add_f32_e32 v57, 1.0, v57
	v_rcp_f32_e32 v54, v54
	v_rcp_f32_e32 v57, v57
	v_add_f32_e32 v53, v53, v85
	v_mfma_f32_16x16x32_bf16 v[34:37], v[18:21], v[86:89], v[34:37]
	v_mul_f32_e32 v54, v54, v58
	v_mul_f32_e32 v55, v57, v56
	v_mul_f32_e32 v51, v54, v51
	v_lshlrev_b32_e32 v54, 16, v93
	v_and_b32_e32 v56, 0xffff0000, v93
	v_mul_f32_e32 v50, v55, v50
	v_mul_f32_e32 v55, v54, v54
	v_mul_f32_e32 v57, v56, v56
	v_fmamk_f32 v55, v55, 0xbdd2d3e7, v129
	v_fmamk_f32 v57, v57, 0xbdd2d3e7, v129
	v_mul_f32_e32 v55, v55, v54
	v_mul_f32_e32 v57, v57, v56
	v_exp_f32_e32 v55, v55
	v_exp_f32_e32 v57, v57
	v_cvt_pk_bf16_f32 v50, v50, v51
	v_mfma_f32_16x16x32_bf16 v[46:49], v[22:25], v[86:89], v[46:49]
	v_add_f32_e32 v55, 1.0, v55
	v_add_f32_e32 v51, 1.0, v57
	v_rcp_f32_e32 v55, v55
	v_rcp_f32_e32 v51, v51
	v_mfma_f32_16x16x32_bf16 v[42:45], v[14:17], v[86:89], v[42:45]
	v_or_b32_e32 v57, 48, v82
	v_mul_f32_e32 v54, v55, v54
	v_mul_f32_e32 v51, v51, v56
	v_mul_f32_e32 v52, v54, v52
	v_mul_f32_e32 v51, v51, v53
	v_cvt_pk_bf16_f32 v51, v52, v51
	s_waitcnt vmcnt(3)
	v_lshlrev_b32_e32 v52, 16, v94
	v_mul_f32_e32 v53, v52, v52
	v_and_b32_e32 v54, 0xffff0000, v94
	v_fmamk_f32 v53, v53, 0xbdd2d3e7, v129
	v_mul_f32_e32 v55, v54, v54
	v_mul_f32_e32 v53, v53, v52
	v_fmamk_f32 v55, v55, 0xbdd2d3e7, v129
	v_mul_f32_e32 v55, v55, v54
	v_exp_f32_e32 v53, v53
	v_exp_f32_e32 v55, v55
	global_store_dwordx2 v[60:61], v[50:51], off offset:64
	v_add_f32_e32 v53, 1.0, v53
	v_rcp_f32_e32 v53, v53
	v_add_f32_e32 v50, 1.0, v55
	v_rcp_f32_e32 v50, v50
	v_mul_f32_e32 v51, v53, v52
	v_add_f32_e32 v52, v62, v85
	v_mul_f32_e32 v51, v51, v52
	v_mul_f32_e32 v50, v50, v54
	v_add_f32_e32 v52, v63, v85
	v_mul_f32_e32 v50, v50, v52
	v_lshlrev_b32_e32 v52, 16, v95
	v_mul_f32_e32 v53, v52, v52
	v_and_b32_e32 v54, 0xffff0000, v95
	v_fmamk_f32 v53, v53, 0xbdd2d3e7, v129
	v_mul_f32_e32 v55, v54, v54
	v_mul_f32_e32 v53, v53, v52
	v_fmamk_f32 v55, v55, 0xbdd2d3e7, v129
	v_mul_f32_e32 v55, v55, v54
	v_exp_f32_e32 v53, v53
	v_exp_f32_e32 v55, v55
	v_cvt_pk_bf16_f32 v50, v51, v50
	v_add_f32_e32 v53, 1.0, v53
	v_rcp_f32_e32 v53, v53
	v_add_f32_e32 v51, 1.0, v55
	v_rcp_f32_e32 v51, v51
	v_mul_f32_e32 v52, v53, v52
	v_add_f32_e32 v53, v64, v85
	v_mul_f32_e32 v52, v52, v53
	v_mul_f32_e32 v51, v51, v54
	v_add_f32_e32 v53, v65, v85
	v_mul_f32_e32 v51, v51, v53
	v_cvt_pk_bf16_f32 v51, v52, v51
	global_store_dwordx2 v[60:61], v[50:51], off offset:96
	global_load_dword v56, v81, s[12:13] offset:128
	global_load_dwordx2 v[54:55], v[68:69], off offset:32
	ds_read_b128 v[50:53], v83 offset:13248
	global_load_dwordx2 v[58:59], v[68:69], off offset:64
	global_load_dwordx2 v[60:61], v[68:69], off offset:96
	s_waitcnt vmcnt(8)
	v_lshlrev_b32_e32 v62, 16, v66
	s_waitcnt lgkmcnt(0)
	v_mfma_f32_16x16x32_bf16 v[26:29], v[30:33], v[50:53], v[26:29]
	v_mul_f32_e32 v30, v62, v62
	v_and_b32_e32 v63, 0xffff0000, v66
	v_fmamk_f32 v30, v30, 0xbdd2d3e7, v129
	v_mul_f32_e32 v31, v63, v63
	v_mul_f32_e32 v30, v30, v62
	v_fmamk_f32 v31, v31, 0xbdd2d3e7, v129
	v_mul_f32_e32 v31, v31, v63
	v_exp_f32_e32 v30, v30
	v_exp_f32_e32 v64, v31
	v_mad_u64_u32 v[32:33], s[0:1], v57, s3, v[74:75]
	v_add_f32_e32 v30, 1.0, v30
	v_rcp_f32_e32 v65, v30
	v_add_f32_e32 v64, 1.0, v64
	v_rcp_f32_e32 v64, v64
	global_load_dwordx2 v[30:31], v[32:33], off
	v_mul_f32_e32 v62, v65, v62
	v_mfma_f32_16x16x32_bf16 v[6:9], v[18:21], v[50:53], v[6:9]
	global_load_dwordx2 v[18:19], v[32:33], off offset:32
	s_waitcnt vmcnt(5)
	v_add_f32_e32 v38, v38, v56
	v_mul_f32_e32 v38, v62, v38
	v_mul_f32_e32 v62, v64, v63
	v_add_f32_e32 v39, v39, v56
	v_mul_f32_e32 v39, v62, v39
	v_lshlrev_b32_e32 v62, 16, v67
	v_mul_f32_e32 v63, v62, v62
	v_fmamk_f32 v63, v63, 0xbdd2d3e7, v129
	v_and_b32_e32 v64, 0xffff0000, v67
	v_mul_f32_e32 v63, v63, v62
	v_mul_f32_e32 v65, v64, v64
	v_fmamk_f32 v65, v65, 0xbdd2d3e7, v129
	v_mul_f32_e32 v65, v65, v64
	v_exp_f32_e32 v63, v63
	v_exp_f32_e32 v65, v65
	v_add_f32_e32 v63, 1.0, v63
	v_rcp_f32_e32 v63, v63
	v_cvt_pk_bf16_f32 v38, v38, v39
	v_add_f32_e32 v39, 1.0, v65
	v_rcp_f32_e32 v39, v39
	v_mul_f32_e32 v62, v63, v62
	v_add_f32_e32 v40, v40, v56
	v_mul_f32_e32 v40, v62, v40
	s_waitcnt vmcnt(4)
	v_lshlrev_b32_e32 v62, 16, v54
	v_and_b32_e32 v54, 0xffff0000, v54
	v_mul_f32_e32 v39, v39, v64
	v_mul_f32_e32 v64, v54, v54
	v_mul_f32_e32 v63, v62, v62
	v_fmamk_f32 v64, v64, 0xbdd2d3e7, v129
	v_fmamk_f32 v63, v63, 0xbdd2d3e7, v129
	v_mul_f32_e32 v64, v64, v54
	v_add_f32_e32 v41, v41, v56
	v_mul_f32_e32 v63, v63, v62
	v_mul_f32_e32 v39, v39, v41
	v_cvt_pk_bf16_f32 v39, v40, v39
	v_mad_u64_u32 v[40:41], s[0:1], v78, s3, v[72:73]
	v_exp_f32_e32 v64, v64
	v_lshl_add_u64 v[40:41], v[40:41], 0, s[8:9]
	v_exp_f32_e32 v63, v63
	v_lshl_add_u64 v[40:41], v[40:41], 0, v[0:1]
	v_lshl_add_u64 v[40:41], v[40:41], 0, v[70:71]
	global_store_dwordx2 v[40:41], v[38:39], off
	v_add_f32_e32 v38, 1.0, v64
	v_add_f32_e32 v63, 1.0, v63
	v_rcp_f32_e32 v38, v38
	v_rcp_f32_e32 v63, v63
	v_add_f32_e32 v35, v35, v56
	v_add_f32_e32 v34, v34, v56
	v_mul_f32_e32 v38, v38, v54
	v_mul_f32_e32 v39, v63, v62
	v_mul_f32_e32 v35, v38, v35
	v_lshlrev_b32_e32 v38, 16, v55
	v_and_b32_e32 v54, 0xffff0000, v55
	v_mul_f32_e32 v34, v39, v34
	v_mul_f32_e32 v39, v38, v38
	v_mul_f32_e32 v55, v54, v54
	v_fmamk_f32 v39, v39, 0xbdd2d3e7, v129
	v_fmamk_f32 v55, v55, 0xbdd2d3e7, v129
	v_mul_f32_e32 v39, v39, v38
	v_mul_f32_e32 v55, v55, v54
	v_exp_f32_e32 v39, v39
	v_exp_f32_e32 v55, v55
	v_cvt_pk_bf16_f32 v34, v34, v35
	v_add_f32_e32 v36, v36, v56
	v_add_f32_e32 v39, 1.0, v39
	v_add_f32_e32 v35, 1.0, v55
	v_rcp_f32_e32 v39, v39
	v_rcp_f32_e32 v35, v35
	v_add_f32_e32 v37, v37, v56
	v_mfma_f32_16x16x32_bf16 v[2:5], v[22:25], v[50:53], v[2:5]
	v_mul_f32_e32 v38, v39, v38
	v_mul_f32_e32 v35, v35, v54
	v_mul_f32_e32 v36, v38, v36
	v_mul_f32_e32 v35, v35, v37
	v_cvt_pk_bf16_f32 v35, v36, v35
	s_waitcnt vmcnt(4)
	v_lshlrev_b32_e32 v36, 16, v58
	v_mul_f32_e32 v37, v36, v36
	v_and_b32_e32 v38, 0xffff0000, v58
	v_fmamk_f32 v37, v37, 0xbdd2d3e7, v129
	v_mul_f32_e32 v39, v38, v38
	v_mul_f32_e32 v37, v37, v36
	v_fmamk_f32 v39, v39, 0xbdd2d3e7, v129
	v_mul_f32_e32 v39, v39, v38
	v_exp_f32_e32 v37, v37
	v_exp_f32_e32 v39, v39
	global_store_dwordx2 v[40:41], v[34:35], off offset:32
	v_add_f32_e32 v37, 1.0, v37
	v_rcp_f32_e32 v37, v37
	v_add_f32_e32 v34, 1.0, v39
	v_rcp_f32_e32 v34, v34
	s_waitcnt vmcnt(3)
	v_lshlrev_b32_e32 v24, 16, v30
	v_mul_f32_e32 v35, v37, v36
	v_add_f32_e32 v36, v46, v56
	v_mul_f32_e32 v35, v35, v36
	v_mul_f32_e32 v34, v34, v38
	v_add_f32_e32 v36, v47, v56
	v_mul_f32_e32 v34, v34, v36
	v_lshlrev_b32_e32 v36, 16, v59
	v_mul_f32_e32 v37, v36, v36
	v_and_b32_e32 v38, 0xffff0000, v59
	v_fmamk_f32 v37, v37, 0xbdd2d3e7, v129
	v_mul_f32_e32 v39, v38, v38
	v_mul_f32_e32 v37, v37, v36
	v_fmamk_f32 v39, v39, 0xbdd2d3e7, v129
	v_mul_f32_e32 v39, v39, v38
	v_exp_f32_e32 v37, v37
	v_exp_f32_e32 v39, v39
	v_cvt_pk_bf16_f32 v34, v35, v34
	v_add_f32_e32 v37, 1.0, v37
	v_rcp_f32_e32 v37, v37
	v_add_f32_e32 v35, 1.0, v39
	v_rcp_f32_e32 v35, v35
	v_mul_f32_e32 v25, 0x3d372713, v24
	v_mul_f32_e32 v36, v37, v36
	v_add_f32_e32 v37, v48, v56
	v_mul_f32_e32 v36, v36, v37
	v_mul_f32_e32 v35, v35, v38
	v_add_f32_e32 v37, v49, v56
	v_mul_f32_e32 v35, v35, v37
	v_cvt_pk_bf16_f32 v35, v36, v35
	v_lshlrev_b32_e32 v36, 16, v60
	v_mul_f32_e32 v37, v36, v36
	v_and_b32_e32 v38, 0xffff0000, v60
	v_fmamk_f32 v37, v37, 0xbdd2d3e7, v129
	v_mul_f32_e32 v39, v38, v38
	v_mul_f32_e32 v37, v37, v36
	v_fmamk_f32 v39, v39, 0xbdd2d3e7, v129
	v_mul_f32_e32 v39, v39, v38
	v_exp_f32_e32 v37, v37
	v_exp_f32_e32 v39, v39
	global_store_dwordx2 v[40:41], v[34:35], off offset:64
	v_add_f32_e32 v37, 1.0, v37
	v_rcp_f32_e32 v37, v37
	v_add_f32_e32 v34, 1.0, v39
	v_rcp_f32_e32 v34, v34
	v_and_b32_e32 v30, 0xffff0000, v30
	v_mul_f32_e32 v35, v37, v36
	v_add_f32_e32 v36, v42, v56
	v_mul_f32_e32 v35, v35, v36
	v_mul_f32_e32 v34, v34, v38
	v_add_f32_e32 v36, v43, v56
	v_mul_f32_e32 v34, v34, v36
	v_lshlrev_b32_e32 v36, 16, v61
	v_mul_f32_e32 v37, v36, v36
	v_and_b32_e32 v38, 0xffff0000, v61
	v_fmamk_f32 v37, v37, 0xbdd2d3e7, v129
	v_mul_f32_e32 v39, v38, v38
	v_mul_f32_e32 v37, v37, v36
	v_fmamk_f32 v39, v39, 0xbdd2d3e7, v129
	v_mul_f32_e32 v39, v39, v38
	v_exp_f32_e32 v37, v37
	v_exp_f32_e32 v39, v39
	v_cvt_pk_bf16_f32 v34, v35, v34
	v_add_f32_e32 v37, 1.0, v37
	v_rcp_f32_e32 v37, v37
	v_add_f32_e32 v35, 1.0, v39
	v_rcp_f32_e32 v35, v35
	v_mul_f32_e32 v25, v25, v24
	v_mul_f32_e32 v36, v37, v36
	v_add_f32_e32 v37, v44, v56
	v_mul_f32_e32 v36, v36, v37
	v_mul_f32_e32 v35, v35, v38
	v_add_f32_e32 v37, v45, v56
	v_mul_f32_e32 v35, v35, v37
	v_cvt_pk_bf16_f32 v35, v36, v35
	global_store_dwordx2 v[40:41], v[34:35], off offset:96
	global_load_dword v34, v81, s[12:13] offset:192
	s_nop 0
	global_load_dwordx2 v[20:21], v[32:33], off offset:64
	global_load_dwordx2 v[22:23], v[32:33], off offset:96
	v_mul_f32_e32 v32, v30, v30
	v_fma_f32 v25, v25, v24, v24
	v_fmamk_f32 v32, v32, 0xbdd2d3e7, v129
	v_mul_f32_e32 v25, 0xbfcc422a, v25
	v_mul_f32_e32 v32, v32, v30
	v_mul_f32_e32 v25, 0x3fb8aa3b, v25
	v_exp_f32_e32 v25, v25
	v_exp_f32_e32 v32, v32
	v_mfma_f32_16x16x32_bf16 v[10:13], v[14:17], v[50:53], v[10:13]
	v_add_f32_e32 v25, 1.0, v25
	v_rcp_f32_e32 v25, v25
	v_add_f32_e32 v14, 1.0, v32
	v_rcp_f32_e32 v14, v14
	v_mul_f32_e32 v15, v25, v24
	v_and_b32_e32 v24, 0xffff0000, v31
	v_mul_f32_e32 v14, v14, v30
	v_mul_f32_e32 v25, v24, v24
	v_fmamk_f32 v25, v25, 0xbdd2d3e7, v129
	v_mul_f32_e32 v25, v25, v24
	v_exp_f32_e32 v25, v25
	s_waitcnt vmcnt(2)
	v_add_f32_e32 v16, v26, v34
	v_mul_f32_e32 v15, v15, v16
	v_add_f32_e32 v16, v27, v34
	v_mul_f32_e32 v14, v14, v16
	v_lshlrev_b32_e32 v16, 16, v31
	v_mul_f32_e32 v17, v16, v16
	v_fmamk_f32 v17, v17, 0xbdd2d3e7, v129
	v_mul_f32_e32 v17, v17, v16
	v_exp_f32_e32 v17, v17
	v_cvt_pk_bf16_f32 v14, v15, v14
	v_add_f32_e32 v15, 1.0, v25
	v_rcp_f32_e32 v15, v15
	v_add_f32_e32 v17, 1.0, v17
	v_rcp_f32_e32 v17, v17
	v_add_f32_e32 v6, v6, v34
	v_mul_f32_e32 v15, v15, v24
	v_add_f32_e32 v7, v7, v34
	v_mul_f32_e32 v16, v17, v16
	v_add_f32_e32 v17, v28, v34
	v_mul_f32_e32 v16, v16, v17
	v_add_f32_e32 v17, v29, v34
	v_mul_f32_e32 v15, v15, v17
	v_cvt_pk_bf16_f32 v15, v16, v15
	v_mad_u64_u32 v[16:17], s[0:1], v57, s3, v[72:73]
	v_lshl_add_u64 v[16:17], v[16:17], 0, s[8:9]
	v_lshl_add_u64 v[16:17], v[16:17], 0, v[0:1]
	v_lshlrev_b32_e32 v0, 16, v18
	v_mul_f32_e32 v24, v0, v0
	v_and_b32_e32 v18, 0xffff0000, v18
	v_fmamk_f32 v24, v24, 0xbdd2d3e7, v129
	v_mul_f32_e32 v25, v18, v18
	v_mul_f32_e32 v24, v24, v0
	v_fmamk_f32 v25, v25, 0xbdd2d3e7, v129
	v_mul_f32_e32 v25, v25, v18
	v_exp_f32_e32 v24, v24
	v_exp_f32_e32 v25, v25
	v_lshl_add_u64 v[16:17], v[16:17], 0, v[70:71]
	v_add_f32_e32 v24, 1.0, v24
	v_rcp_f32_e32 v24, v24
	global_store_dwordx2 v[16:17], v[14:15], off
	v_add_f32_e32 v14, 1.0, v25
	v_rcp_f32_e32 v14, v14
	v_mul_f32_e32 v0, v24, v0
	v_mul_f32_e32 v0, v0, v6
	v_and_b32_e32 v15, 0xffff0000, v19
	v_mul_f32_e32 v6, v14, v18
	v_mul_f32_e32 v6, v6, v7
	v_lshlrev_b32_e32 v7, 16, v19
	v_mul_f32_e32 v14, v7, v7
	v_fmamk_f32 v14, v14, 0xbdd2d3e7, v129
	v_mul_f32_e32 v18, v15, v15
	v_mul_f32_e32 v14, v14, v7
	v_fmamk_f32 v18, v18, 0xbdd2d3e7, v129
	v_mul_f32_e32 v18, v18, v15
	v_exp_f32_e32 v14, v14
	v_exp_f32_e32 v18, v18
	v_cvt_pk_bf16_f32 v6, v0, v6
	v_add_f32_e32 v14, 1.0, v14
	v_rcp_f32_e32 v14, v14
	v_add_f32_e32 v0, 1.0, v18
	v_rcp_f32_e32 v0, v0
	v_add_f32_e32 v8, v8, v34
	v_mul_f32_e32 v7, v14, v7
	v_mul_f32_e32 v7, v7, v8
	v_mul_f32_e32 v0, v0, v15
	v_add_f32_e32 v8, v9, v34
	v_mul_f32_e32 v0, v0, v8
	v_cvt_pk_bf16_f32 v7, v7, v0
	s_waitcnt vmcnt(2)
	v_lshlrev_b32_e32 v0, 16, v20
	v_mul_f32_e32 v8, v0, v0
	v_and_b32_e32 v9, 0xffff0000, v20
	v_fmamk_f32 v8, v8, 0xbdd2d3e7, v129
	v_mul_f32_e32 v14, v9, v9
	v_mul_f32_e32 v8, v8, v0
	v_fmamk_f32 v14, v14, 0xbdd2d3e7, v129
	v_mul_f32_e32 v14, v14, v9
	v_exp_f32_e32 v8, v8
	v_exp_f32_e32 v14, v14
	global_store_dwordx2 v[16:17], v[6:7], off offset:32
	v_add_f32_e32 v8, 1.0, v8
	v_rcp_f32_e32 v8, v8
	v_add_f32_e32 v6, 1.0, v14
	v_rcp_f32_e32 v6, v6
	v_add_f32_e32 v2, v2, v34
	v_mul_f32_e32 v0, v8, v0
	v_mul_f32_e32 v0, v0, v2
	v_mul_f32_e32 v2, v6, v9
	v_add_f32_e32 v3, v3, v34
	v_mul_f32_e32 v2, v2, v3
	v_lshlrev_b32_e32 v3, 16, v21
	v_mul_f32_e32 v6, v3, v3
	v_and_b32_e32 v7, 0xffff0000, v21
	v_fmamk_f32 v6, v6, 0xbdd2d3e7, v129
	v_mul_f32_e32 v8, v7, v7
	v_mul_f32_e32 v6, v6, v3
	v_fmamk_f32 v8, v8, 0xbdd2d3e7, v129
	v_mul_f32_e32 v8, v8, v7
	v_exp_f32_e32 v6, v6
	v_exp_f32_e32 v8, v8
	v_cvt_pk_bf16_f32 v2, v0, v2
	v_add_f32_e32 v6, 1.0, v6
	v_rcp_f32_e32 v6, v6
	v_add_f32_e32 v0, 1.0, v8
	v_rcp_f32_e32 v0, v0
	v_add_f32_e32 v4, v4, v34
	v_mul_f32_e32 v3, v6, v3
	v_mul_f32_e32 v3, v3, v4
	v_mul_f32_e32 v0, v0, v7
	v_add_f32_e32 v4, v5, v34
	v_mul_f32_e32 v0, v0, v4
	v_cvt_pk_bf16_f32 v3, v3, v0
	s_waitcnt vmcnt(2)
	v_lshlrev_b32_e32 v0, 16, v22
	v_mul_f32_e32 v4, v0, v0
	v_and_b32_e32 v5, 0xffff0000, v22
	v_fmamk_f32 v4, v4, 0xbdd2d3e7, v129
	v_mul_f32_e32 v6, v5, v5
	v_mul_f32_e32 v4, v4, v0
	v_fmamk_f32 v6, v6, 0xbdd2d3e7, v129
	v_mul_f32_e32 v6, v6, v5
	v_exp_f32_e32 v4, v4
	v_exp_f32_e32 v6, v6
	global_store_dwordx2 v[16:17], v[2:3], off offset:64
	v_add_f32_e32 v4, 1.0, v4
	v_rcp_f32_e32 v4, v4
	v_add_f32_e32 v2, 1.0, v6
	v_rcp_f32_e32 v2, v2
	v_add_f32_e32 v3, v10, v34
	v_mul_f32_e32 v0, v4, v0
	v_mul_f32_e32 v0, v0, v3
	v_mul_f32_e32 v2, v2, v5
	v_add_f32_e32 v3, v11, v34
	v_mul_f32_e32 v2, v2, v3
	v_lshlrev_b32_e32 v3, 16, v23
	v_mul_f32_e32 v4, v3, v3
	v_and_b32_e32 v5, 0xffff0000, v23
	v_fmamk_f32 v4, v4, 0xbdd2d3e7, v129
	v_mul_f32_e32 v6, v5, v5
	v_mul_f32_e32 v4, v4, v3
	v_fmamk_f32 v6, v6, 0xbdd2d3e7, v129
	v_mul_f32_e32 v6, v6, v5
	v_exp_f32_e32 v4, v4
	v_exp_f32_e32 v6, v6
	v_cvt_pk_bf16_f32 v2, v0, v2
	v_add_f32_e32 v4, 1.0, v4
	v_rcp_f32_e32 v4, v4
	v_add_f32_e32 v0, 1.0, v6
	v_rcp_f32_e32 v0, v0
	v_mul_f32_e32 v3, v4, v3
	v_add_f32_e32 v4, v12, v34
	v_mul_f32_e32 v3, v3, v4
	v_mul_f32_e32 v0, v0, v5
	v_add_f32_e32 v4, v13, v34
	v_mul_f32_e32 v0, v0, v4
	v_cvt_pk_bf16_f32 v3, v3, v0
	global_store_dwordx2 v[16:17], v[2:3], off offset:96
	s_barrier
	s_cbranch_scc0 .LBB0_626
	s_and_b32 s0, s10, 3
	s_lshl_b32 s1, s10, 5
	v_mov_b32_e32 v38, v194
	v_cvt_f32_ubyte0_e32 v0, s0
	s_and_b32 s1, s1, 0x7fffff80
	v_sub_f32_e32 v37, 0xc0a00000, v0
	v_bfe_u32 v36, v38, 1, 7
	s_mov_b32 s2, 0xc2fc0000
	v_cmp_gt_f32_e32 vcc, s2, v37
	v_or_b32_e32 v0, s1, v36
	v_mov_b64_e32 v[2:3], s[50:51]
	s_and_b64 s[4:5], vcc, exec
	v_mad_u64_u32 v[34:35], s[4:5], v0, s3, v[2:3]
	v_and_b32_e32 v40, 1, v38
	s_cselect_b32 s2, 0xffffffc0, 0
	s_lshl_b32 s4, s0, 8
	s_mov_b32 s5, s89
	v_lshl_add_u64 v[2:3], v[34:35], 0, s[4:5]
	v_lshlrev_b32_e32 v4, 7, v40
	v_mov_b32_e32 v5, v1
	v_lshl_add_u64 v[2:3], v[2:3], 0, v[4:5]
	global_load_dwordx4 v[30:33], v[2:3], off offset:3072
	global_load_dwordx4 v[26:29], v[2:3], off offset:3088
	global_load_dwordx4 v[22:25], v[2:3], off offset:3104
	global_load_dwordx4 v[18:21], v[2:3], off offset:3120
	global_load_dwordx4 v[14:17], v[2:3], off offset:3136
	global_load_dwordx4 v[10:13], v[2:3], off offset:3152
	global_load_dwordx4 v[6:9], v[2:3], off offset:3168
	s_nop 0
	global_load_dwordx4 v[2:5], v[2:3], off offset:3184
	s_mov_b32 s1, s89
	s_lshl_b32 s0, s0, 7
	v_lshlrev_b32_e32 v0, 6, v40
	v_mul_u32_u24_e32 v41, 0x2200, v40
	v_cndmask_b32_e32 v42, 0, v248, vcc
	v_lshl_add_u64 v[34:35], v[34:35], 0, s[0:1]
	v_lshlrev_b32_e32 v36, 1, v36
	v_lshlrev_b32_e32 v41, 1, v41
	v_add_f32_e32 v37, v37, v42
	v_lshl_add_u64 v[42:43], v[34:35], 0, v[0:1]
	v_add3_u32 v44, s15, v41, v36
	v_add3_u32 v41, s15, v36, v41
	v_exp_f32_e32 v45, v37
	global_load_dwordx4 v[34:37], v[42:43], off offset:2560
	v_lshrrev_b32_e32 v39, 1, v38
	v_and_b32_e32 v55, 0x60, v39
	v_ldexp_f32 v0, v45, s2
	v_sub_f32_e32 v0, 1.0, v0
	v_cmp_gt_f32_e32 vcc, s11, v0
	s_and_b64 s[0:1], vcc, exec
	s_cselect_b32 s0, 32, 0
	v_ldexp_f32 v0, v0, s0
	v_log_f32_e32 v0, v0
	s_mov_b32 s0, 0x3f317217
	v_bfe_u32 v54, v38, 4, 2
	s_mov_b32 s11, s89
	s_mul_i32 s2, s10, 3
	s_movk_i32 s39, 0xd80
	s_mov_b32 s69, 0x800000
	s_waitcnt vmcnt(8)
	ds_write_b16 v44, v30
	ds_write_b16_d16_hi v41, v30 offset:272
	ds_write_b16 v44, v31 offset:544
	ds_write_b16_d16_hi v41, v31 offset:816
	ds_write_b16 v44, v32 offset:1088
	ds_write_b16_d16_hi v41, v32 offset:1360
	ds_write_b16 v44, v33 offset:1632
	ds_write_b16_d16_hi v41, v33 offset:1904
	s_waitcnt vmcnt(7)
	ds_write_b16 v44, v26 offset:2176
	ds_write_b16_d16_hi v41, v26 offset:2448
	ds_write_b16 v44, v27 offset:2720
	ds_write_b16_d16_hi v41, v27 offset:2992
	ds_write_b16 v44, v28 offset:3264
	ds_write_b16_d16_hi v41, v28 offset:3536
	ds_write_b16 v44, v29 offset:3808
	ds_write_b16_d16_hi v41, v29 offset:4080
	s_waitcnt vmcnt(6)
	ds_write_b16 v44, v22 offset:4352
	ds_write_b16_d16_hi v41, v22 offset:4624
	ds_write_b16 v44, v23 offset:4896
	ds_write_b16_d16_hi v41, v23 offset:5168
	ds_write_b16 v44, v24 offset:5440
	ds_write_b16_d16_hi v41, v24 offset:5712
	ds_write_b16 v44, v25 offset:5984
	ds_write_b16_d16_hi v41, v25 offset:6256
	s_waitcnt vmcnt(5)
	ds_write_b16 v44, v18 offset:6528
	ds_write_b16_d16_hi v41, v18 offset:6800
	ds_write_b16 v44, v19 offset:7072
	ds_write_b16_d16_hi v41, v19 offset:7344
	ds_write_b16 v44, v20 offset:7616
	ds_write_b16_d16_hi v41, v20 offset:7888
	ds_write_b16 v44, v21 offset:8160
	ds_write_b16_d16_hi v41, v21 offset:8432
	s_waitcnt vmcnt(4)
	ds_write_b16 v44, v14 offset:8704
	ds_write_b16_d16_hi v41, v14 offset:8976
	ds_write_b16 v44, v15 offset:9248
	ds_write_b16_d16_hi v41, v15 offset:9520
	ds_write_b16 v44, v16 offset:9792
	ds_write_b16_d16_hi v41, v16 offset:10064
	ds_write_b16 v44, v17 offset:10336
	ds_write_b16_d16_hi v41, v17 offset:10608
	s_waitcnt vmcnt(3)
	ds_write_b16 v44, v10 offset:10880
	ds_write_b16_d16_hi v41, v10 offset:11152
	ds_write_b16 v44, v11 offset:11424
	ds_write_b16_d16_hi v41, v11 offset:11696
	ds_write_b16 v44, v12 offset:11968
	ds_write_b16_d16_hi v41, v12 offset:12240
	ds_write_b16 v44, v13 offset:12512
	ds_write_b16_d16_hi v41, v13 offset:12784
	s_waitcnt vmcnt(2)
	ds_write_b16 v44, v6 offset:13056
	ds_write_b16_d16_hi v41, v6 offset:13328
	ds_write_b16 v44, v7 offset:13600
	ds_write_b16_d16_hi v41, v7 offset:13872
	global_load_dwordx4 v[10:13], v[42:43], off offset:2576
	ds_write_b16 v44, v8 offset:14144
	ds_write_b16_d16_hi v41, v8 offset:14416
	ds_write_b16 v44, v9 offset:14688
	ds_write_b16_d16_hi v41, v9 offset:14960
	s_waitcnt vmcnt(2)
	ds_write_b16 v44, v2 offset:15232
	ds_write_b16_d16_hi v41, v2 offset:15504
	ds_write_b16 v44, v3 offset:15776
	ds_write_b16_d16_hi v41, v3 offset:16048
	ds_write_b16 v44, v4 offset:16320
	ds_write_b16_d16_hi v41, v4 offset:16592
	global_load_dwordx4 v[6:9], v[42:43], off offset:2592
	v_mul_f32_e32 v2, 0x3f317217, v0
	v_fma_f32 v2, v0, s0, -v2
	v_fmac_f32_e32 v2, 0x3377d1cf, v0
	s_mov_b32 s0, 0x7f800000
	v_fmac_f32_e32 v2, 0x3f317217, v0
	v_cmp_lt_f32_e64 s[0:1], |v0|, s0
	ds_write_b16 v44, v5 offset:16864
	ds_write_b16_d16_hi v41, v5 offset:17136
	v_cndmask_b32_e64 v0, v0, v2, s[0:1]
	v_cndmask_b32_e32 v2, 0, v231, vcc
	s_movk_i32 s0, 0x7f
	v_sub_f32_e32 v0, v0, v2
	v_bitop3_b32 v2, v39, s0, v39 bitop3:0xc
	v_cvt_f32_ubyte0_e32 v2, v2
	v_mul_f32_e32 v2, v0, v2
	v_mul_f32_e32 v0, 0x3fb8aa3b, v2
	s_mov_b32 s0, 0x3fb8aa3b
	v_fma_f32 v3, v2, s0, -v0
	v_rndne_f32_e32 v4, v0
	v_fmac_f32_e32 v3, 0x32a5705f, v2
	v_sub_f32_e32 v0, v0, v4
	v_add_f32_e32 v0, v0, v3
	v_exp_f32_e32 v3, v0
	v_cvt_i32_f32_e32 v4, v4
	s_mov_b32 s0, 0xc2ce8ed0
	v_cmp_ngt_f32_e32 vcc, s0, v2
	s_mov_b32 s0, 0x42b17218
	v_ldexp_f32 v3, v3, v4
	v_cndmask_b32_e32 v3, 0, v3, vcc
	v_cmp_nlt_f32_e32 vcc, s0, v2
	s_waitcnt vmcnt(2)
	v_lshlrev_b32_e32 v15, 16, v34
	v_and_b32_e32 v0, 15, v38
	v_cndmask_b32_e32 v2, v195, v3, vcc
	v_mul_f32_e32 v14, 0x3e000000, v2
	global_load_dwordx4 v[2:5], v[42:43], off offset:2608
	v_mul_f32_e32 v15, v14, v15
	v_cvt_pk_bf16_f32 v15, v15, s0
	s_movk_i32 s0, 0xde00
	v_mad_i32_i24 v16, v40, s0, v44
	ds_write_b16 v16, v15 offset:34816
	v_and_b32_e32 v15, 0xffff0000, v34
	v_mul_f32_e32 v15, v14, v15
	v_cvt_pk_bf16_f32 v15, v15, s0
	v_mad_i32_i24 v17, v40, s0, v41
	ds_write_b16 v17, v15 offset:35088
	v_lshlrev_b32_e32 v15, 16, v35
	v_mul_f32_e32 v15, v14, v15
	v_cvt_pk_bf16_f32 v15, v15, s0
	ds_write_b16 v16, v15 offset:35360
	v_and_b32_e32 v15, 0xffff0000, v35
	v_mul_f32_e32 v15, v14, v15
	v_cvt_pk_bf16_f32 v15, v15, s0
	ds_write_b16 v17, v15 offset:35632
	v_lshlrev_b32_e32 v15, 16, v36
	v_mul_f32_e32 v15, v14, v15
	v_cvt_pk_bf16_f32 v15, v15, s0
	ds_write_b16 v16, v15 offset:35904
	v_and_b32_e32 v15, 0xffff0000, v36
	v_mul_f32_e32 v15, v14, v15
	v_cvt_pk_bf16_f32 v15, v15, s0
	ds_write_b16 v17, v15 offset:36176
	v_lshlrev_b32_e32 v15, 16, v37
	v_mul_f32_e32 v15, v14, v15
	v_cvt_pk_bf16_f32 v15, v15, s0
	ds_write_b16 v16, v15 offset:36448
	v_and_b32_e32 v15, 0xffff0000, v37
	v_mul_f32_e32 v15, v14, v15
	v_cvt_pk_bf16_f32 v15, v15, s0
	ds_write_b16 v17, v15 offset:36720
	s_waitcnt vmcnt(2)
	v_lshlrev_b32_e32 v15, 16, v10
	v_and_b32_e32 v10, 0xffff0000, v10
	v_mul_f32_e32 v10, v14, v10
	v_cvt_pk_bf16_f32 v10, v10, s0
	ds_write_b16 v17, v10 offset:37264
	v_lshlrev_b32_e32 v10, 16, v11
	v_mul_f32_e32 v10, v14, v10
	v_cvt_pk_bf16_f32 v10, v10, s0
	ds_write_b16 v16, v10 offset:37536
	v_and_b32_e32 v10, 0xffff0000, v11
	v_mul_f32_e32 v10, v14, v10
	v_cvt_pk_bf16_f32 v10, v10, s0
	ds_write_b16 v17, v10 offset:37808
	v_lshlrev_b32_e32 v10, 16, v12
	v_mul_f32_e32 v10, v14, v10
	v_cvt_pk_bf16_f32 v10, v10, s0
	ds_write_b16 v16, v10 offset:38080
	v_and_b32_e32 v10, 0xffff0000, v12
	v_mul_f32_e32 v10, v14, v10
	v_cvt_pk_bf16_f32 v10, v10, s0
	ds_write_b16 v17, v10 offset:38352
	v_lshlrev_b32_e32 v10, 16, v13
	v_mul_f32_e32 v10, v14, v10
	v_cvt_pk_bf16_f32 v10, v10, s0
	ds_write_b16 v16, v10 offset:38624
	v_and_b32_e32 v10, 0xffff0000, v13
	v_mul_f32_e32 v10, v14, v10
	v_cvt_pk_bf16_f32 v10, v10, s0
	ds_write_b16 v17, v10 offset:38896
	s_waitcnt vmcnt(1)
	v_lshlrev_b32_e32 v10, 16, v6
	v_and_b32_e32 v6, 0xffff0000, v6
	v_mul_f32_e32 v6, v14, v6
	v_cvt_pk_bf16_f32 v6, v6, s0
	ds_write_b16 v17, v6 offset:39440
	v_lshlrev_b32_e32 v6, 16, v7
	v_mul_f32_e32 v6, v14, v6
	v_cvt_pk_bf16_f32 v6, v6, s0
	ds_write_b16 v16, v6 offset:39712
	v_and_b32_e32 v6, 0xffff0000, v7
	v_mul_f32_e32 v6, v14, v6
	v_cvt_pk_bf16_f32 v6, v6, s0
	ds_write_b16 v17, v6 offset:39984
	v_lshlrev_b32_e32 v6, 16, v8
	v_mul_f32_e32 v6, v14, v6
	v_cvt_pk_bf16_f32 v6, v6, s0
	ds_write_b16 v16, v6 offset:40256
	v_and_b32_e32 v6, 0xffff0000, v8
	v_mul_f32_e32 v6, v14, v6
	v_cvt_pk_bf16_f32 v6, v6, s0
	ds_write_b16 v17, v6 offset:40528
	v_lshlrev_b32_e32 v6, 16, v9
	v_mul_f32_e32 v6, v14, v6
	v_cvt_pk_bf16_f32 v6, v6, s0
	ds_write_b16 v16, v6 offset:40800
	v_and_b32_e32 v6, 0xffff0000, v9
	v_mul_f32_e32 v6, v14, v6
	v_cvt_pk_bf16_f32 v6, v6, s0
	ds_write_b16 v17, v6 offset:41072
	s_waitcnt vmcnt(0)
	v_lshlrev_b32_e32 v6, 16, v2
	v_and_b32_e32 v2, 0xffff0000, v2
	v_mul_f32_e32 v2, v14, v2
	v_cvt_pk_bf16_f32 v2, v2, s0
	ds_write_b16 v17, v2 offset:41616
	v_lshlrev_b32_e32 v2, 16, v3
	v_mul_f32_e32 v2, v14, v2
	v_cvt_pk_bf16_f32 v2, v2, s0
	ds_write_b16 v16, v2 offset:41888
	v_and_b32_e32 v2, 0xffff0000, v3
	v_mul_f32_e32 v2, v14, v2
	v_cvt_pk_bf16_f32 v2, v2, s0
	ds_write_b16 v17, v2 offset:42160
	v_lshlrev_b32_e32 v2, 16, v4
	v_mul_f32_e32 v2, v14, v2
	v_cvt_pk_bf16_f32 v2, v2, s0
	ds_write_b16 v16, v2 offset:42432
	v_and_b32_e32 v2, 0xffff0000, v4
	v_mul_f32_e32 v2, v14, v2
	v_cvt_pk_bf16_f32 v2, v2, s0
	ds_write_b16 v17, v2 offset:42704
	v_lshlrev_b32_e32 v2, 16, v5
	v_mul_f32_e32 v2, v14, v2
	v_cvt_pk_bf16_f32 v2, v2, s0
	ds_write_b16 v16, v2 offset:42976
	v_and_b32_e32 v2, 0xffff0000, v5
	v_mul_f32_e32 v2, v14, v2
	v_mul_f32_e32 v6, v14, v6
	v_cvt_pk_bf16_f32 v2, v2, s0
	v_cvt_pk_bf16_f32 v6, v6, s0
	ds_write_b16 v17, v2 offset:43248
	v_or_b32_e32 v2, v55, v0
	v_mul_f32_e32 v15, v14, v15
	v_mul_f32_e32 v10, v14, v10
	ds_write_b16 v16, v6 offset:41344
	v_lshl_add_u32 v6, v54, 4, s15
	v_mul_u32_u24_e32 v2, 0x88, v2
	v_mul_u32_u24_e32 v7, 0x88, v0
	v_cvt_pk_bf16_f32 v15, v15, s0
	v_cvt_pk_bf16_f32 v10, v10, s0
	v_lshl_add_u32 v56, v2, 1, v6
	v_lshl_add_u32 v57, v7, 1, v6
	ds_write_b16 v16, v15 offset:36992
	ds_write_b16 v16, v10 offset:39168
	s_waitcnt lgkmcnt(0)
	s_barrier
	ds_read_b128 v[2:5], v56
	ds_read_b128 v[38:41], v56 offset:64
	ds_read_b128 v[6:9], v57 offset:34816
	ds_read_b128 v[34:37], v56 offset:4352
	ds_read_b128 v[14:17], v57 offset:39168
	ds_read_b128 v[22:25], v57 offset:43520
	ds_read_b128 v[30:33], v57 offset:47872
	ds_read_b128 v[46:49], v57 offset:43584
	s_waitcnt lgkmcnt(5)
	v_mfma_f32_16x16x32_bf16 v[10:13], v[2:5], v[6:9], 0
	ds_read_b128 v[42:45], v57 offset:39232
	ds_read_b128 v[50:53], v57 offset:47936
	s_lshl_b64 s[0:1], s[10:11], 15
	s_waitcnt lgkmcnt(5)
	v_mfma_f32_16x16x32_bf16 v[18:21], v[2:5], v[14:17], 0
	s_add_u32 s0, s24, s0
	s_addc_u32 s1, s25, s1
	s_add_i32 s9, s2, 0xfffffd80
	s_waitcnt lgkmcnt(4)
	v_mfma_f32_16x16x32_bf16 v[26:29], v[2:5], v[22:25], 0
	s_waitcnt lgkmcnt(3)
	v_mfma_f32_16x16x32_bf16 v[2:5], v[2:5], v[30:33], 0
	v_mfma_f32_16x16x32_bf16 v[6:9], v[34:37], v[6:9], 0
	v_mfma_f32_16x16x32_bf16 v[14:17], v[34:37], v[14:17], 0
	v_mfma_f32_16x16x32_bf16 v[22:25], v[34:37], v[22:25], 0
	v_mfma_f32_16x16x32_bf16 v[30:33], v[34:37], v[30:33], 0
	ds_read_b128 v[34:37], v57 offset:34880
	s_waitcnt lgkmcnt(0)
	v_mfma_f32_16x16x32_bf16 v[10:13], v[38:41], v[34:37], v[10:13]
	v_mfma_f32_16x16x32_bf16 v[18:21], v[38:41], v[42:45], v[18:21]
	v_mfma_f32_16x16x32_bf16 v[26:29], v[38:41], v[46:49], v[26:29]
	v_mfma_f32_16x16x32_bf16 v[2:5], v[38:41], v[50:53], v[2:5]
	ds_read_b128 v[38:41], v56 offset:4416
	s_waitcnt lgkmcnt(0)
	v_mfma_f32_16x16x32_bf16 v[6:9], v[38:41], v[34:37], v[6:9]
	ds_read_b128 v[34:37], v56 offset:128
	v_mfma_f32_16x16x32_bf16 v[14:17], v[38:41], v[42:45], v[14:17]
	ds_read_b128 v[42:45], v57 offset:39296
	v_mfma_f32_16x16x32_bf16 v[22:25], v[38:41], v[46:49], v[22:25]
	ds_read_b128 v[46:49], v57 offset:43648
	v_mfma_f32_16x16x32_bf16 v[30:33], v[38:41], v[50:53], v[30:33]
	ds_read_b128 v[38:41], v57 offset:34944
	ds_read_b128 v[50:53], v57 offset:48000
	s_waitcnt lgkmcnt(1)
	v_mfma_f32_16x16x32_bf16 v[10:13], v[34:37], v[38:41], v[10:13]
	v_mfma_f32_16x16x32_bf16 v[18:21], v[34:37], v[42:45], v[18:21]
	v_mfma_f32_16x16x32_bf16 v[26:29], v[34:37], v[46:49], v[26:29]
	s_waitcnt lgkmcnt(0)
	v_mfma_f32_16x16x32_bf16 v[2:5], v[34:37], v[50:53], v[2:5]
	ds_read_b128 v[34:37], v56 offset:4480
	s_waitcnt lgkmcnt(0)
	v_mfma_f32_16x16x32_bf16 v[6:9], v[34:37], v[38:41], v[6:9]
	ds_read_b128 v[38:41], v56 offset:192
	v_mfma_f32_16x16x32_bf16 v[14:17], v[34:37], v[42:45], v[14:17]
	ds_read_b128 v[42:45], v57 offset:39360
	v_mfma_f32_16x16x32_bf16 v[22:25], v[34:37], v[46:49], v[22:25]
	ds_read_b128 v[46:49], v57 offset:43712
	v_mfma_f32_16x16x32_bf16 v[30:33], v[34:37], v[50:53], v[30:33]
	ds_read_b128 v[34:37], v57 offset:35008
	ds_read_b128 v[50:53], v57 offset:48064
	s_waitcnt lgkmcnt(1)
	v_mfma_f32_16x16x32_bf16 v[10:13], v[38:41], v[34:37], v[10:13]
	v_mfma_f32_16x16x32_bf16 v[18:21], v[38:41], v[42:45], v[18:21]
	v_mfma_f32_16x16x32_bf16 v[26:29], v[38:41], v[46:49], v[26:29]
	s_waitcnt lgkmcnt(0)
	v_mfma_f32_16x16x32_bf16 v[2:5], v[38:41], v[50:53], v[2:5]
	ds_read_b128 v[38:41], v56 offset:4544
	s_waitcnt lgkmcnt(0)
	v_mfma_f32_16x16x32_bf16 v[6:9], v[38:41], v[34:37], v[6:9]
	v_lshlrev_b32_e32 v37, 6, v55
	v_lshl_or_b32 v37, v54, 8, v37
	v_or_b32_e32 v34, 16, v0
	v_mfma_f32_16x16x32_bf16 v[14:17], v[38:41], v[42:45], v[14:17]
	v_or_b32_e32 v35, 32, v0
	v_or_b32_e32 v36, 48, v0
	v_mfma_f32_16x16x32_bf16 v[22:25], v[38:41], v[46:49], v[22:25]
	v_mfma_f32_16x16x32_bf16 v[30:33], v[38:41], v[50:53], v[30:33]
	v_or_b32_e32 v38, v37, v0
	v_lshlrev_b32_e32 v38, 2, v38
	global_store_dword v38, v10, s[0:1]
	global_store_dword v38, v11, s[0:1] offset:256
	global_store_dword v38, v12, s[0:1] offset:512
	global_store_dword v38, v13, s[0:1] offset:768
	global_store_dword v38, v18, s[0:1] offset:64
	v_or_b32_e32 v10, v37, v34
	v_lshlrev_b32_e32 v10, 2, v10
	global_store_dword v10, v19, s[0:1] offset:256
	global_store_dword v10, v20, s[0:1] offset:512
	global_store_dword v10, v21, s[0:1] offset:768
	global_store_dword v38, v26, s[0:1] offset:128
	v_or_b32_e32 v10, v37, v35
	v_lshlrev_b32_e32 v10, 2, v10
	global_store_dword v10, v27, s[0:1] offset:256
	global_store_dword v10, v28, s[0:1] offset:512
	global_store_dword v10, v29, s[0:1] offset:768
	global_store_dword v38, v2, s[0:1] offset:192
	v_or_b32_e32 v2, v37, v36
	v_lshlrev_b32_e32 v2, 2, v2
	global_store_dword v2, v3, s[0:1] offset:256
	global_store_dword v2, v4, s[0:1] offset:512
	global_store_dword v2, v5, s[0:1] offset:768
	v_or_b32_e32 v2, 0x400, v37
	v_or_b32_e32 v3, v2, v0
	v_lshlrev_b32_e32 v3, 2, v3
	global_store_dword v3, v6, s[0:1]
	v_or_b32_e32 v3, 0x440, v37
	v_or_b32_e32 v4, v3, v0
	v_lshlrev_b32_e32 v4, 2, v4
	global_store_dword v4, v7, s[0:1]
	v_or_b32_e32 v4, 0x480, v37
	v_or_b32_e32 v5, v4, v0
	v_lshlrev_b32_e32 v5, 2, v5
	global_store_dword v5, v8, s[0:1]
	v_or_b32_e32 v5, 0x4c0, v37
	v_or_b32_e32 v0, v5, v0
	v_lshlrev_b32_e32 v0, 2, v0
	global_store_dword v0, v9, s[0:1]
	v_or_b32_e32 v0, v2, v34
	v_lshlrev_b32_e32 v0, 2, v0
	global_store_dword v0, v14, s[0:1]
	v_or_b32_e32 v0, v3, v34
	v_lshlrev_b32_e32 v0, 2, v0
	global_store_dword v0, v15, s[0:1]
	v_or_b32_e32 v0, v4, v34
	v_lshlrev_b32_e32 v0, 2, v0
	global_store_dword v0, v16, s[0:1]
	v_or_b32_e32 v0, v5, v34
	v_lshlrev_b32_e32 v0, 2, v0
	global_store_dword v0, v17, s[0:1]
	v_or_b32_e32 v0, v2, v35
	v_lshlrev_b32_e32 v0, 2, v0
	global_store_dword v0, v22, s[0:1]
	v_or_b32_e32 v0, v3, v35
	v_lshlrev_b32_e32 v0, 2, v0
	global_store_dword v0, v23, s[0:1]
	v_or_b32_e32 v0, v4, v35
	v_lshlrev_b32_e32 v0, 2, v0
	global_store_dword v0, v24, s[0:1]
	v_or_b32_e32 v0, v5, v35
	v_lshlrev_b32_e32 v0, 2, v0
	global_store_dword v0, v25, s[0:1]
	v_or_b32_e32 v0, v2, v36
	v_lshlrev_b32_e32 v0, 2, v0
	global_store_dword v0, v30, s[0:1]
	v_or_b32_e32 v0, v3, v36
	v_lshlrev_b32_e32 v0, 2, v0
	global_store_dword v0, v31, s[0:1]
	v_or_b32_e32 v0, v4, v36
	v_lshlrev_b32_e32 v0, 2, v0
	global_store_dword v0, v32, s[0:1]
	v_or_b32_e32 v0, v5, v36
	v_lshlrev_b32_e32 v0, 2, v0
	global_store_dword v0, v33, s[0:1]
	s_lshl_b32 s0, s9, 6
	s_and_b32 s11, s0, 0x3fc0
	v_mov_b32_e32 v0, v194
	s_cmpk_lt_u32 s9, 0x200
	s_barrier
	s_cselect_b64 s[0:1], -1, 0
	s_and_b64 s[4:5], s[0:1], exec
	v_bfe_u32 v12, v0, 2, 6
	v_lshlrev_b32_e32 v0, 4, v0
	s_cselect_b32 s4, s39, 0xe80
	s_lshr_b32 s5, s9, 2
	v_and_b32_e32 v10, 48, v0
	v_or_b32_e32 v0, s11, v12
	s_and_b32 s9, s5, 64
	v_mul_u32_u24_e32 v0, 0xf80, v0
	s_or_b32 s4, s4, s9
	v_lshlrev_b32_e32 v0, 1, v0
	v_lshl_add_u64 v[2:3], s[50:51], 0, v[0:1]
	s_lshl_b32 s4, s4, 1
	s_mov_b32 s5, s89
	v_lshl_add_u64 v[2:3], v[2:3], 0, s[4:5]
	v_lshlrev_b32_e32 v0, 1, v10
	v_lshl_add_u64 v[6:7], v[2:3], 0, v[0:1]
	global_load_dwordx4 v[2:5], v[6:7], off
	s_nop 0
	global_load_dwordx4 v[6:9], v[6:7], off offset:16
	v_mul_u32_u24_e32 v10, 0x48, v10
	v_lshlrev_b32_e32 v10, 1, v10
	v_lshlrev_b32_e32 v11, 1, v12
	v_add3_u32 v13, s15, v10, v11
	v_add3_u32 v10, s15, v11, v10
	s_and_b64 s[0:1], s[0:1], exec
	s_cselect_b32 s1, s53, s55
	s_cselect_b32 s0, s52, s54
	s_waitcnt vmcnt(1)
	ds_write_b16 v13, v2
	ds_write_b16_d16_hi v10, v2 offset:144
	ds_write_b16 v13, v3 offset:288
	ds_write_b16_d16_hi v10, v3 offset:432
	ds_write_b16 v13, v4 offset:576
	ds_write_b16_d16_hi v10, v4 offset:720
	ds_write_b16 v13, v5 offset:864
	ds_write_b16_d16_hi v10, v5 offset:1008
	s_waitcnt vmcnt(0)
	ds_write_b16 v13, v6 offset:1152
	ds_write_b16_d16_hi v10, v6 offset:1296
	ds_write_b16 v13, v7 offset:1440
	ds_write_b16_d16_hi v10, v7 offset:1584
	ds_write_b16 v13, v8 offset:1728
	ds_write_b16_d16_hi v10, v8 offset:1872
	ds_write_b16 v13, v9 offset:2016
	ds_write_b16_d16_hi v10, v9 offset:2160
	v_or_b32_e32 v2, s9, v12
	v_lshlrev_b32_e32 v2, 15, v2
	v_mov_b32_e32 v3, v1
	v_lshl_add_u64 v[10:11], s[0:1], 0, v[2:3]
	v_mul_u32_u24_e32 v2, 0x90, v12
	v_add3_u32 v6, s15, v2, v0
	s_waitcnt lgkmcnt(0)
	s_barrier
	ds_read_b128 v[2:5], v6
	ds_read_b128 v[6:9], v6 offset:16
	s_lshl_b32 s0, s11, 1
	s_mov_b32 s1, s89
	s_add_i32 s9, s2, 0xfffffd81
	v_lshl_add_u64 v[10:11], v[10:11], 0, s[0:1]
	s_lshl_b32 s0, s9, 6
	s_and_b32 s11, s0, 0x3fc0
	v_lshl_add_u64 v[10:11], v[10:11], 0, v[0:1]
	v_mov_b32_e32 v0, v194
	s_cmpk_lt_u32 s9, 0x200
	s_waitcnt lgkmcnt(1)
	global_store_dwordx4 v[10:11], v[2:5], off
	s_waitcnt lgkmcnt(0)
	global_store_dwordx4 v[10:11], v[6:9], off offset:16
	s_barrier
	s_cselect_b64 s[0:1], -1, 0
	s_and_b64 s[4:5], s[0:1], exec
	v_bfe_u32 v12, v0, 2, 6
	v_lshlrev_b32_e32 v0, 4, v0
	s_cselect_b32 s4, s39, 0xe80
	s_lshr_b32 s5, s9, 2
	v_and_b32_e32 v10, 48, v0
	v_or_b32_e32 v0, s11, v12
	s_and_b32 s9, s5, 64
	v_mul_u32_u24_e32 v0, 0xf80, v0
	s_or_b32 s4, s4, s9
	v_lshlrev_b32_e32 v0, 1, v0
	v_lshl_add_u64 v[2:3], s[50:51], 0, v[0:1]
	s_lshl_b32 s4, s4, 1
	s_mov_b32 s5, s89
	v_lshl_add_u64 v[2:3], v[2:3], 0, s[4:5]
	v_lshlrev_b32_e32 v0, 1, v10
	v_lshl_add_u64 v[6:7], v[2:3], 0, v[0:1]
	global_load_dwordx4 v[2:5], v[6:7], off
	s_nop 0
	global_load_dwordx4 v[6:9], v[6:7], off offset:16
	v_mul_u32_u24_e32 v10, 0x48, v10
	v_lshlrev_b32_e32 v10, 1, v10
	v_lshlrev_b32_e32 v11, 1, v12
	v_add3_u32 v13, s15, v10, v11
	v_add3_u32 v10, s15, v11, v10
	s_and_b64 s[0:1], s[0:1], exec
	s_cselect_b32 s1, s53, s55
	s_cselect_b32 s0, s52, s54
	s_addk_i32 s2, 0xfd82
	s_waitcnt vmcnt(1)
	ds_write_b16 v13, v2
	ds_write_b16_d16_hi v10, v2 offset:144
	ds_write_b16 v13, v3 offset:288
	ds_write_b16_d16_hi v10, v3 offset:432
	ds_write_b16 v13, v4 offset:576
	ds_write_b16_d16_hi v10, v4 offset:720
	ds_write_b16 v13, v5 offset:864
	ds_write_b16_d16_hi v10, v5 offset:1008
	s_waitcnt vmcnt(0)
	ds_write_b16 v13, v6 offset:1152
	ds_write_b16_d16_hi v10, v6 offset:1296
	ds_write_b16 v13, v7 offset:1440
	ds_write_b16_d16_hi v10, v7 offset:1584
	ds_write_b16 v13, v8 offset:1728
	ds_write_b16_d16_hi v10, v8 offset:1872
	ds_write_b16 v13, v9 offset:2016
	ds_write_b16_d16_hi v10, v9 offset:2160
	v_or_b32_e32 v2, s9, v12
	v_lshlrev_b32_e32 v2, 15, v2
	v_mov_b32_e32 v3, v1
	v_lshl_add_u64 v[10:11], s[0:1], 0, v[2:3]
	v_mul_u32_u24_e32 v2, 0x90, v12
	v_add3_u32 v6, s15, v2, v0
	s_waitcnt lgkmcnt(0)
	s_barrier
	ds_read_b128 v[2:5], v6
	ds_read_b128 v[6:9], v6 offset:16
	s_lshl_b32 s0, s11, 1
	s_mov_b32 s1, s89
	v_lshl_add_u64 v[10:11], v[10:11], 0, s[0:1]
	s_lshl_b32 s0, s2, 6
	s_and_b32 s9, s0, 0x3fc0
	v_lshl_add_u64 v[10:11], v[10:11], 0, v[0:1]
	v_mov_b32_e32 v0, v194
	s_cmpk_lt_u32 s2, 0x200
	s_waitcnt lgkmcnt(1)
	global_store_dwordx4 v[10:11], v[2:5], off
	s_waitcnt lgkmcnt(0)
	global_store_dwordx4 v[10:11], v[6:9], off offset:16
	s_barrier
	s_cselect_b64 s[0:1], -1, 0
	s_and_b64 s[4:5], s[0:1], exec
	v_bfe_u32 v12, v0, 2, 6
	v_lshlrev_b32_e32 v0, 4, v0
	s_cselect_b32 s4, s39, 0xe80
	s_lshr_b32 s2, s2, 2
	v_and_b32_e32 v10, 48, v0
	v_or_b32_e32 v0, s9, v12
	s_and_b32 s2, s2, 64
	v_mul_u32_u24_e32 v0, 0xf80, v0
	s_or_b32 s4, s4, s2
	v_lshlrev_b32_e32 v0, 1, v0
	v_lshl_add_u64 v[2:3], s[50:51], 0, v[0:1]
	s_lshl_b32 s4, s4, 1
	s_mov_b32 s5, s89
	v_lshl_add_u64 v[2:3], v[2:3], 0, s[4:5]
	v_lshlrev_b32_e32 v0, 1, v10
	v_lshl_add_u64 v[6:7], v[2:3], 0, v[0:1]
	global_load_dwordx4 v[2:5], v[6:7], off
	s_nop 0
	global_load_dwordx4 v[6:9], v[6:7], off offset:16
	v_mul_u32_u24_e32 v10, 0x48, v10
	v_lshlrev_b32_e32 v10, 1, v10
	v_lshlrev_b32_e32 v11, 1, v12
	v_add3_u32 v13, s15, v10, v11
	v_add3_u32 v10, s15, v11, v10
	s_and_b64 s[0:1], s[0:1], exec
	s_cselect_b32 s1, s53, s55
	s_cselect_b32 s0, s52, s54
	s_mov_b64 s[4:5], 0
	s_waitcnt vmcnt(1)
	ds_write_b16 v13, v2
	ds_write_b16_d16_hi v10, v2 offset:144
	ds_write_b16 v13, v3 offset:288
	ds_write_b16_d16_hi v10, v3 offset:432
	ds_write_b16 v13, v4 offset:576
	ds_write_b16_d16_hi v10, v4 offset:720
	ds_write_b16 v13, v5 offset:864
	ds_write_b16_d16_hi v10, v5 offset:1008
	s_waitcnt vmcnt(0)
	ds_write_b16 v13, v6 offset:1152
	ds_write_b16_d16_hi v10, v6 offset:1296
	ds_write_b16 v13, v7 offset:1440
	ds_write_b16_d16_hi v10, v7 offset:1584
	ds_write_b16 v13, v8 offset:1728
	ds_write_b16_d16_hi v10, v8 offset:1872
	ds_write_b16 v13, v9 offset:2016
	ds_write_b16_d16_hi v10, v9 offset:2160
	v_or_b32_e32 v2, s2, v12
	v_lshlrev_b32_e32 v2, 15, v2
	v_mov_b32_e32 v3, v1
	v_lshl_add_u64 v[10:11], s[0:1], 0, v[2:3]
	v_mul_u32_u24_e32 v2, 0x90, v12
	v_add3_u32 v6, s15, v2, v0
	s_waitcnt lgkmcnt(0)
	s_barrier
	ds_read_b128 v[2:5], v6
	ds_read_b128 v[6:9], v6 offset:16
	s_lshl_b32 s0, s9, 1
	s_mov_b32 s1, s89
	v_lshl_add_u64 v[10:11], v[10:11], 0, s[0:1]
	v_lshl_add_u64 v[10:11], v[10:11], 0, v[0:1]
	s_mov_b64 s[0:1], 0
	s_cmpk_lt_u32 s10, 0x180
	s_waitcnt lgkmcnt(1)
	global_store_dwordx4 v[10:11], v[2:5], off
	s_waitcnt lgkmcnt(0)
	global_store_dwordx4 v[10:11], v[6:9], off offset:16
	s_barrier
	s_cbranch_scc0 .LBB0_627
	s_lshl_b32 s2, s10, 6
	v_mov_b32_e32 v0, v194
	s_and_b32 s2, s2, 0x3fc0
	s_xor_b32 s2, s2, 0x2000
	v_bfe_u32 v12, v0, 2, 6
	v_lshlrev_b32_e32 v0, 4, v0
	v_and_b32_e32 v10, 48, v0
	v_or_b32_e32 v0, s2, v12
	v_mul_u32_u24_e32 v0, 0xf80, v0
	v_readlane_b32 s40, v251, 54
	v_lshlrev_b32_e32 v0, 1, v0
	v_readlane_b32 s46, v251, 60
	v_readlane_b32 s47, v251, 61
	s_mov_b64 s[4:5], 0x1d80
	v_lshlrev_b32_e32 v11, 1, v12
	v_lshl_add_u64 v[2:3], s[46:47], 0, v[0:1]
	v_lshlrev_b32_e32 v0, 1, v10
	v_lshl_add_u64 v[2:3], v[2:3], 0, v[0:1]
	v_lshl_add_u64 v[6:7], v[2:3], 0, s[4:5]
	v_add_co_u32_e32 v2, vcc, s68, v2
	v_mul_u32_u24_e32 v10, 0x48, v10
	s_nop 0
	v_addc_co_u32_e32 v3, vcc, 0, v3, vcc
	global_load_dwordx4 v[2:5], v[2:3], off offset:3456
	s_nop 0
	global_load_dwordx4 v[6:9], v[6:7], off offset:16
	v_lshlrev_b32_e32 v10, 1, v10
	v_add3_u32 v13, s15, v10, v11
	v_add3_u32 v10, s15, v11, v10
	v_readlane_b32 s50, v252, 0
	v_readlane_b32 s51, v252, 1
	s_lshl_b32 s4, s2, 1
	s_mov_b32 s5, s89
	v_readlane_b32 s41, v251, 55
	v_readlane_b32 s42, v251, 56
	v_readlane_b32 s43, v251, 57
	v_readlane_b32 s44, v251, 58
	v_readlane_b32 s45, v251, 59
	v_readlane_b32 s48, v251, 62
	v_readlane_b32 s49, v251, 63
	v_readlane_b32 s52, v252, 2
	v_readlane_b32 s53, v252, 3
	v_readlane_b32 s54, v252, 4
	v_readlane_b32 s55, v252, 5
	s_waitcnt vmcnt(1)
	ds_write_b16 v13, v2
	ds_write_b16_d16_hi v10, v2 offset:144
	ds_write_b16 v13, v3 offset:288
	ds_write_b16_d16_hi v10, v3 offset:432
	ds_write_b16 v13, v4 offset:576
	ds_write_b16_d16_hi v10, v4 offset:720
	ds_write_b16 v13, v5 offset:864
	ds_write_b16_d16_hi v10, v5 offset:1008
	s_waitcnt vmcnt(0)
	ds_write_b16 v13, v6 offset:1152
	ds_write_b16_d16_hi v10, v6 offset:1296
	ds_write_b16 v13, v7 offset:1440
	ds_write_b16_d16_hi v10, v7 offset:1584
	ds_write_b16 v13, v8 offset:1728
	ds_write_b16_d16_hi v10, v8 offset:1872
	ds_write_b16 v13, v9 offset:2016
	ds_write_b16_d16_hi v10, v9 offset:2160
	v_lshlrev_b32_e32 v2, 15, v12
	v_mov_b32_e32 v3, v1
	v_lshl_add_u64 v[2:3], s[50:51], 0, v[2:3]
	v_lshl_add_u64 v[2:3], v[2:3], 0, s[4:5]
	v_lshl_add_u64 v[2:3], v[2:3], 0, v[0:1]
	v_mul_u32_u24_e32 v4, 0x90, v12
	s_mov_b64 s[4:5], 0x200000
	v_add3_u32 v0, s15, v4, v0
	v_add_co_u32_e32 v12, vcc, 0x200000, v2
	s_waitcnt lgkmcnt(0)
	s_barrier
	v_lshl_add_u64 v[10:11], v[2:3], 0, s[4:5]
	v_addc_co_u32_e32 v13, vcc, 0, v3, vcc
	ds_read_b128 v[2:5], v0
	ds_read_b128 v[6:9], v0 offset:16
	s_waitcnt lgkmcnt(1)
	global_store_dwordx4 v[12:13], v[2:5], off
	s_waitcnt lgkmcnt(0)
	global_store_dwordx4 v[10:11], v[6:9], off offset:16
	s_barrier
	s_mov_b64 s[4:5], -1
	s_branch .LBB0_627

.LBB0_627:
	s_and_b64 vcc, exec, s[0:1]
	s_cbranch_vccz .LBB0_631
	s_lshl_b32 s0, s10, 5
	s_and_b32 s4, s0, 0x1f80
	v_mov_b32_e32 v50, v194
	s_bitset1_b32 s4, 13
	v_readlane_b32 s40, v251, 54
	v_bfe_u32 v31, v50, 1, 7
	v_or_b32_e32 v0, s4, v31
	v_and_b32_e32 v16, 1, v50
	v_mul_u32_u24_e32 v0, 0x1f00, v0
	v_readlane_b32 s46, v251, 60
	v_readlane_b32 s47, v251, 61
	v_mov_b32_e32 v18, 0
	v_lshrrev_b32_e32 v30, 1, v50
	v_lshl_add_u64 v[10:11], s[46:47], 0, v[0:1]
	v_lshlrev_b32_e32 v0, 9, v16
	v_readlane_b32 s41, v251, 55
	v_readlane_b32 s42, v251, 56
	v_readlane_b32 s43, v251, 57
	v_readlane_b32 s44, v251, 58
	v_readlane_b32 s45, v251, 59
	v_readlane_b32 s48, v251, 62
	v_readlane_b32 s49, v251, 63
	v_readlane_b32 s50, v252, 0
	v_readlane_b32 s51, v252, 1
	v_readlane_b32 s52, v252, 2
	v_readlane_b32 s53, v252, 3
	v_readlane_b32 s54, v252, 4
	v_readlane_b32 s55, v252, 5
	v_lshl_add_u64 v[12:13], v[10:11], 0, v[0:1]
	v_readfirstlane_b32 s64, v194
	s_lshr_b32 s64, s64, 8
	s_lshl_b32 s0, s64, 8
	s_mov_b32 s1, 0
	s_add_i32 s65, s0, 0x100
	v_mov_b32_e32 v19, v18
.LBB0_629:
	v_lshl_add_u64 v[14:15], v[12:13], 0, s[0:1]
	global_load_dwordx4 v[2:5], v[14:15], off offset:1072
	global_load_dwordx4 v[6:9], v[14:15], off offset:1056
	global_load_dwordx4 v[20:23], v[14:15], off offset:1040
	global_load_dwordx4 v[24:27], v[14:15], off offset:1024
	s_add_u32 s0, s0, 0x80
	s_addc_u32 s1, s1, 0
	s_cmp_lg_u32 s0, s65
	s_waitcnt vmcnt(0)
	v_lshlrev_b32_e32 v0, 16, v24
	v_mul_f32_e32 v17, v0, v0
	v_fmamk_f32 v17, v17, 0xbdd2d3e7, v129
	v_mul_f32_e32 v17, v17, v0
	v_exp_f32_e32 v17, v17
	v_and_b32_e32 v40, 0xffff0000, v27
	v_add_f32_e32 v17, 1.0, v17
	v_rcp_f32_e32 v17, v17
	s_nop 0
	v_mul_f32_e32 v29, v17, v0
	v_and_b32_e32 v0, 0xffff0000, v24
	v_mul_f32_e32 v17, v0, v0
	v_fmamk_f32 v17, v17, 0xbdd2d3e7, v129
	v_mul_f32_e32 v17, v17, v0
	v_exp_f32_e32 v17, v17
	v_mul_f32_e32 v28, v29, v29
	v_add_f32_e32 v17, 1.0, v17
	v_rcp_f32_e32 v17, v17
	s_nop 0
	v_mul_f32_e32 v33, v17, v0
	v_lshlrev_b32_e32 v0, 16, v25
	v_mul_f32_e32 v17, v0, v0
	v_fmamk_f32 v17, v17, 0xbdd2d3e7, v129
	v_mul_f32_e32 v17, v17, v0
	v_exp_f32_e32 v17, v17
	v_mul_f32_e32 v32, v33, v33
	v_add_f32_e32 v17, 1.0, v17
	v_rcp_f32_e32 v17, v17
	s_nop 0
	v_mul_f32_e32 v35, v17, v0
	v_and_b32_e32 v0, 0xffff0000, v25
	v_mul_f32_e32 v17, v0, v0
	v_fmamk_f32 v17, v17, 0xbdd2d3e7, v129
	v_mul_f32_e32 v17, v17, v0
	v_exp_f32_e32 v17, v17
	v_mul_f32_e32 v34, v35, v35
	v_add_f32_e32 v17, 1.0, v17
	v_rcp_f32_e32 v17, v17
	s_nop 0
	v_mul_f32_e32 v25, v17, v0
	v_lshlrev_b32_e32 v0, 16, v26
	v_mul_f32_e32 v17, v0, v0
	v_fmamk_f32 v17, v17, 0xbdd2d3e7, v129
	v_mul_f32_e32 v17, v17, v0
	v_exp_f32_e32 v17, v17
	v_mul_f32_e32 v24, v25, v25
	v_pk_add_f32 v[24:25], v[34:35], v[24:25]
	v_add_f32_e32 v17, 1.0, v17
	v_rcp_f32_e32 v17, v17
	s_nop 0
	v_mul_f32_e32 v37, v17, v0
	v_and_b32_e32 v0, 0xffff0000, v26
	v_mul_f32_e32 v17, v0, v0
	v_fmamk_f32 v17, v17, 0xbdd2d3e7, v129
	v_mul_f32_e32 v17, v17, v0
	v_exp_f32_e32 v17, v17
	v_mul_f32_e32 v26, v40, v40
	v_fmamk_f32 v26, v26, 0xbdd2d3e7, v129
	v_mul_f32_e32 v26, v26, v40
	v_add_f32_e32 v17, 1.0, v17
	v_rcp_f32_e32 v17, v17
	v_exp_f32_e32 v26, v26
	v_mul_f32_e32 v39, v17, v0
	v_lshlrev_b32_e32 v0, 16, v27
	v_mul_f32_e32 v17, v0, v0
	v_fmamk_f32 v17, v17, 0xbdd2d3e7, v129
	v_mul_f32_e32 v17, v17, v0
	v_exp_f32_e32 v17, v17
	v_add_f32_e32 v26, 1.0, v26
	v_rcp_f32_e32 v41, v26
	v_pk_add_f32 v[26:27], v[28:29], v[32:33]
	v_add_f32_e32 v17, 1.0, v17
	v_rcp_f32_e32 v17, v17
	v_mul_f32_e32 v36, v37, v37
	v_mul_f32_e32 v38, v39, v39
	v_pk_add_f32 v[18:19], v[18:19], v[26:27]
	v_mul_f32_e32 v27, v41, v40
	v_pk_add_f32 v[18:19], v[18:19], v[24:25]
	v_pk_add_f32 v[24:25], v[36:37], v[38:39]
	v_mul_f32_e32 v26, v27, v27
	v_pk_add_f32 v[18:19], v[18:19], v[24:25]
	v_mul_f32_e32 v25, v17, v0
	v_lshlrev_b32_e32 v0, 16, v20
	v_mul_f32_e32 v17, v0, v0
	v_fmamk_f32 v17, v17, 0xbdd2d3e7, v129
	v_mul_f32_e32 v17, v17, v0
	v_exp_f32_e32 v17, v17
	v_mul_f32_e32 v24, v25, v25
	v_pk_add_f32 v[24:25], v[24:25], v[26:27]
	v_and_b32_e32 v36, 0xffff0000, v23
	v_add_f32_e32 v17, 1.0, v17
	v_rcp_f32_e32 v17, v17
	v_pk_add_f32 v[18:19], v[18:19], v[24:25]
	v_mul_f32_e32 v25, v17, v0
	v_and_b32_e32 v0, 0xffff0000, v20
	v_mul_f32_e32 v17, v0, v0
	v_fmamk_f32 v17, v17, 0xbdd2d3e7, v129
	v_mul_f32_e32 v17, v17, v0
	v_exp_f32_e32 v17, v17
	v_mul_f32_e32 v24, v25, v25
	v_add_f32_e32 v17, 1.0, v17
	v_rcp_f32_e32 v17, v17
	s_nop 0
	v_mul_f32_e32 v27, v17, v0
	v_lshlrev_b32_e32 v0, 16, v21
	v_mul_f32_e32 v17, v0, v0
	v_fmamk_f32 v17, v17, 0xbdd2d3e7, v129
	v_mul_f32_e32 v17, v17, v0
	v_exp_f32_e32 v17, v17
	v_mul_f32_e32 v26, v27, v27
	v_add_f32_e32 v17, 1.0, v17
	v_rcp_f32_e32 v17, v17
	s_nop 0
	v_mul_f32_e32 v29, v17, v0
	v_and_b32_e32 v0, 0xffff0000, v21
	v_mul_f32_e32 v17, v0, v0
	v_fmamk_f32 v17, v17, 0xbdd2d3e7, v129
	v_mul_f32_e32 v17, v17, v0
	v_exp_f32_e32 v17, v17
	v_mul_f32_e32 v28, v29, v29
	v_add_f32_e32 v17, 1.0, v17
	v_rcp_f32_e32 v17, v17
	s_nop 0
	v_mul_f32_e32 v21, v17, v0
	v_lshlrev_b32_e32 v0, 16, v22
	v_mul_f32_e32 v17, v0, v0
	v_fmamk_f32 v17, v17, 0xbdd2d3e7, v129
	v_mul_f32_e32 v17, v17, v0
	v_exp_f32_e32 v17, v17
	v_mul_f32_e32 v20, v21, v21
	v_pk_add_f32 v[20:21], v[28:29], v[20:21]
	v_add_f32_e32 v17, 1.0, v17
	v_rcp_f32_e32 v17, v17
	s_nop 0
	v_mul_f32_e32 v33, v17, v0
	v_and_b32_e32 v0, 0xffff0000, v22
	v_mul_f32_e32 v17, v0, v0
	v_fmamk_f32 v17, v17, 0xbdd2d3e7, v129
	v_mul_f32_e32 v17, v17, v0
	v_exp_f32_e32 v17, v17
	v_mul_f32_e32 v22, v36, v36
	v_fmamk_f32 v22, v22, 0xbdd2d3e7, v129
	v_mul_f32_e32 v22, v22, v36
	v_add_f32_e32 v17, 1.0, v17
	v_rcp_f32_e32 v17, v17
	v_exp_f32_e32 v22, v22
	v_mul_f32_e32 v35, v17, v0
	v_lshlrev_b32_e32 v0, 16, v23
	v_mul_f32_e32 v17, v0, v0
	v_fmamk_f32 v17, v17, 0xbdd2d3e7, v129
	v_mul_f32_e32 v17, v17, v0
	v_exp_f32_e32 v17, v17
	v_add_f32_e32 v22, 1.0, v22
	v_rcp_f32_e32 v37, v22
	v_pk_add_f32 v[22:23], v[24:25], v[26:27]
	v_add_f32_e32 v17, 1.0, v17
	v_rcp_f32_e32 v17, v17
	v_mul_f32_e32 v32, v33, v33
	v_mul_f32_e32 v34, v35, v35
	v_pk_add_f32 v[18:19], v[18:19], v[22:23]
	v_mul_f32_e32 v23, v37, v36
	v_pk_add_f32 v[18:19], v[18:19], v[20:21]
	v_pk_add_f32 v[20:21], v[32:33], v[34:35]
	v_mul_f32_e32 v22, v23, v23
	v_pk_add_f32 v[18:19], v[18:19], v[20:21]
	v_mul_f32_e32 v21, v17, v0
	v_lshlrev_b32_e32 v0, 16, v6
	v_mul_f32_e32 v17, v0, v0
	v_fmamk_f32 v17, v17, 0xbdd2d3e7, v129
	v_mul_f32_e32 v17, v17, v0
	v_exp_f32_e32 v17, v17
	v_mul_f32_e32 v20, v21, v21
	v_pk_add_f32 v[20:21], v[20:21], v[22:23]
	v_and_b32_e32 v32, 0xffff0000, v9
	v_add_f32_e32 v17, 1.0, v17
	v_rcp_f32_e32 v17, v17
	v_pk_add_f32 v[18:19], v[18:19], v[20:21]
	v_mul_f32_e32 v21, v17, v0
	v_and_b32_e32 v0, 0xffff0000, v6
	v_mul_f32_e32 v6, v0, v0
	v_fmamk_f32 v6, v6, 0xbdd2d3e7, v129
	v_mul_f32_e32 v6, v6, v0
	v_exp_f32_e32 v6, v6
	v_mul_f32_e32 v20, v21, v21
	v_add_f32_e32 v6, 1.0, v6
	v_rcp_f32_e32 v6, v6
	s_nop 0
	v_mul_f32_e32 v23, v6, v0
	v_lshlrev_b32_e32 v0, 16, v7
	v_mul_f32_e32 v6, v0, v0
	v_fmamk_f32 v6, v6, 0xbdd2d3e7, v129
	v_mul_f32_e32 v6, v6, v0
	v_exp_f32_e32 v6, v6
	v_mul_f32_e32 v22, v23, v23
	v_add_f32_e32 v6, 1.0, v6
	v_rcp_f32_e32 v6, v6
	s_nop 0
	v_mul_f32_e32 v25, v6, v0
	v_and_b32_e32 v0, 0xffff0000, v7
	v_mul_f32_e32 v6, v0, v0
	v_fmamk_f32 v6, v6, 0xbdd2d3e7, v129
	v_mul_f32_e32 v6, v6, v0
	v_exp_f32_e32 v6, v6
	v_mul_f32_e32 v24, v25, v25
	v_add_f32_e32 v6, 1.0, v6
	v_rcp_f32_e32 v6, v6
	s_nop 0
	v_mul_f32_e32 v7, v6, v0
	v_lshlrev_b32_e32 v0, 16, v8
	v_mul_f32_e32 v17, v0, v0
	v_fmamk_f32 v17, v17, 0xbdd2d3e7, v129
	v_mul_f32_e32 v17, v17, v0
	v_exp_f32_e32 v17, v17
	v_mul_f32_e32 v6, v7, v7
	v_pk_add_f32 v[6:7], v[24:25], v[6:7]
	v_add_f32_e32 v17, 1.0, v17
	v_rcp_f32_e32 v17, v17
	s_nop 0
	v_mul_f32_e32 v27, v17, v0
	v_and_b32_e32 v0, 0xffff0000, v8
	v_mul_f32_e32 v8, v0, v0
	v_fmamk_f32 v8, v8, 0xbdd2d3e7, v129
	v_mul_f32_e32 v8, v8, v0
	v_exp_f32_e32 v8, v8
	v_mul_f32_e32 v26, v27, v27
	v_add_f32_e32 v8, 1.0, v8
	v_rcp_f32_e32 v8, v8
	s_nop 0
	v_mul_f32_e32 v29, v8, v0
	v_lshlrev_b32_e32 v0, 16, v9
	v_mul_f32_e32 v8, v0, v0
	v_fmamk_f32 v8, v8, 0xbdd2d3e7, v129
	v_mul_f32_e32 v8, v8, v0
	v_exp_f32_e32 v8, v8
	v_mul_f32_e32 v28, v29, v29
	v_add_f32_e32 v8, 1.0, v8
	v_rcp_f32_e32 v17, v8
	v_mul_f32_e32 v8, v32, v32
	v_fmamk_f32 v8, v8, 0xbdd2d3e7, v129
	v_mul_f32_e32 v8, v8, v32
	v_exp_f32_e32 v8, v8
	s_nop 0
	v_add_f32_e32 v8, 1.0, v8
	v_rcp_f32_e32 v33, v8
	v_pk_add_f32 v[8:9], v[20:21], v[22:23]
	s_nop 0
	v_pk_add_f32 v[8:9], v[18:19], v[8:9]
	v_mul_f32_e32 v19, v33, v32
	v_pk_add_f32 v[6:7], v[8:9], v[6:7]
	v_pk_add_f32 v[8:9], v[26:27], v[28:29]
	v_mul_f32_e32 v18, v19, v19
	v_pk_add_f32 v[6:7], v[6:7], v[8:9]
	v_mul_f32_e32 v9, v17, v0
	v_mul_f32_e32 v8, v9, v9
	v_pk_add_f32 v[8:9], v[8:9], v[18:19]
	v_lshlrev_b32_e32 v0, 16, v2
	v_pk_add_f32 v[6:7], v[6:7], v[8:9]
	v_mul_f32_e32 v8, v0, v0
	v_fmamk_f32 v8, v8, 0xbdd2d3e7, v129
	v_mul_f32_e32 v8, v8, v0
	v_exp_f32_e32 v8, v8
	v_and_b32_e32 v26, 0xffff0000, v5
	v_add_f32_e32 v8, 1.0, v8
	v_rcp_f32_e32 v8, v8
	s_nop 0
	v_mul_f32_e32 v9, v8, v0
	v_and_b32_e32 v0, 0xffff0000, v2
	v_mul_f32_e32 v2, v0, v0
	v_fmamk_f32 v2, v2, 0xbdd2d3e7, v129
	v_mul_f32_e32 v2, v2, v0
	v_exp_f32_e32 v2, v2
	v_mul_f32_e32 v8, v9, v9
	v_add_f32_e32 v2, 1.0, v2
	v_rcp_f32_e32 v2, v2
	s_nop 0
	v_mul_f32_e32 v19, v2, v0
	v_lshlrev_b32_e32 v0, 16, v3
	v_mul_f32_e32 v2, v0, v0
	v_fmamk_f32 v2, v2, 0xbdd2d3e7, v129
	v_mul_f32_e32 v2, v2, v0
	v_exp_f32_e32 v2, v2
	v_mul_f32_e32 v18, v19, v19
	v_add_f32_e32 v2, 1.0, v2
	v_rcp_f32_e32 v2, v2
	s_nop 0
	v_mul_f32_e32 v21, v2, v0
	v_and_b32_e32 v0, 0xffff0000, v3
	v_mul_f32_e32 v2, v0, v0
	v_fmamk_f32 v2, v2, 0xbdd2d3e7, v129
	v_mul_f32_e32 v2, v2, v0
	v_exp_f32_e32 v2, v2
	v_mul_f32_e32 v20, v21, v21
	v_add_f32_e32 v2, 1.0, v2
	v_rcp_f32_e32 v2, v2
	s_nop 0
	v_mul_f32_e32 v3, v2, v0
	v_lshlrev_b32_e32 v0, 16, v4
	v_mul_f32_e32 v17, v0, v0
	v_fmamk_f32 v17, v17, 0xbdd2d3e7, v129
	v_mul_f32_e32 v17, v17, v0
	v_exp_f32_e32 v17, v17
	v_mul_f32_e32 v2, v3, v3
	v_pk_add_f32 v[2:3], v[20:21], v[2:3]
	v_add_f32_e32 v17, 1.0, v17
	v_rcp_f32_e32 v17, v17
	s_nop 0
	v_mul_f32_e32 v23, v17, v0
	v_and_b32_e32 v0, 0xffff0000, v4
	v_mul_f32_e32 v4, v0, v0
	v_fmamk_f32 v4, v4, 0xbdd2d3e7, v129
	v_mul_f32_e32 v4, v4, v0
	v_exp_f32_e32 v4, v4
	v_mul_f32_e32 v22, v23, v23
	v_add_f32_e32 v4, 1.0, v4
	v_rcp_f32_e32 v4, v4
	s_nop 0
	v_mul_f32_e32 v25, v4, v0
	v_lshlrev_b32_e32 v0, 16, v5
	v_mul_f32_e32 v4, v0, v0
	v_fmamk_f32 v4, v4, 0xbdd2d3e7, v129
	v_mul_f32_e32 v4, v4, v0
	v_exp_f32_e32 v4, v4
	v_mul_f32_e32 v24, v25, v25
	v_add_f32_e32 v4, 1.0, v4
	v_rcp_f32_e32 v17, v4
	v_mul_f32_e32 v4, v26, v26
	v_fmamk_f32 v4, v4, 0xbdd2d3e7, v129
	v_mul_f32_e32 v4, v4, v26
	v_exp_f32_e32 v4, v4
	s_nop 0
	v_add_f32_e32 v4, 1.0, v4
	v_rcp_f32_e32 v27, v4
	v_pk_add_f32 v[4:5], v[8:9], v[18:19]
	s_nop 0
	v_pk_add_f32 v[4:5], v[6:7], v[4:5]
	v_mul_f32_e32 v7, v27, v26
	v_pk_add_f32 v[2:3], v[4:5], v[2:3]
	v_pk_add_f32 v[4:5], v[22:23], v[24:25]
	v_mul_f32_e32 v6, v7, v7
	v_pk_add_f32 v[2:3], v[2:3], v[4:5]
	v_mul_f32_e32 v5, v17, v0
	v_mul_f32_e32 v4, v5, v5
	v_pk_add_f32 v[4:5], v[4:5], v[6:7]
	s_nop 0
	v_pk_add_f32 v[26:27], v[2:3], v[4:5]
	global_load_dwordx4 v[2:5], v[14:15], off offset:1136
	global_load_dwordx4 v[6:9], v[14:15], off offset:1120
	global_load_dwordx4 v[18:21], v[14:15], off offset:1104
	global_load_dwordx4 v[22:25], v[14:15], off offset:1088
	s_waitcnt vmcnt(0)
	v_lshlrev_b32_e32 v0, 16, v22
	v_mul_f32_e32 v14, v0, v0
	v_fmamk_f32 v14, v14, 0xbdd2d3e7, v129
	v_mul_f32_e32 v14, v14, v0
	v_exp_f32_e32 v14, v14
	s_nop 0
	v_add_f32_e32 v14, 1.0, v14
	v_rcp_f32_e32 v14, v14
	s_nop 0
	v_mul_f32_e32 v15, v14, v0
	v_and_b32_e32 v0, 0xffff0000, v22
	v_mul_f32_e32 v14, v0, v0
	v_fmamk_f32 v14, v14, 0xbdd2d3e7, v129
	v_mul_f32_e32 v14, v14, v0
	v_exp_f32_e32 v14, v14
	s_nop 0
	v_add_f32_e32 v14, 1.0, v14
	v_rcp_f32_e32 v14, v14
	s_nop 0
	v_mul_f32_e32 v29, v14, v0
	v_lshlrev_b32_e32 v0, 16, v23
	v_mul_f32_e32 v17, v0, v0
	v_fmamk_f32 v17, v17, 0xbdd2d3e7, v129
	v_mul_f32_e32 v17, v17, v0
	v_exp_f32_e32 v17, v17
	v_mul_f32_e32 v14, v15, v15
	v_mul_f32_e32 v28, v29, v29
	v_pk_add_f32 v[14:15], v[14:15], v[28:29]
	v_add_f32_e32 v17, 1.0, v17
	v_rcp_f32_e32 v17, v17
	v_pk_add_f32 v[14:15], v[26:27], v[14:15]
	v_mul_f32_e32 v33, v17, v0
	v_and_b32_e32 v0, 0xffff0000, v23
	v_mul_f32_e32 v17, v0, v0
	v_fmamk_f32 v17, v17, 0xbdd2d3e7, v129
	v_mul_f32_e32 v17, v17, v0
	v_exp_f32_e32 v17, v17
	v_mul_f32_e32 v32, v33, v33
	v_add_f32_e32 v17, 1.0, v17
	v_rcp_f32_e32 v17, v17
	s_nop 0
	v_mul_f32_e32 v23, v17, v0
	v_lshlrev_b32_e32 v0, 16, v24
	v_mul_f32_e32 v17, v0, v0
	v_fmamk_f32 v17, v17, 0xbdd2d3e7, v129
	v_mul_f32_e32 v17, v17, v0
	v_exp_f32_e32 v17, v17
	v_mul_f32_e32 v22, v23, v23
	v_pk_add_f32 v[22:23], v[32:33], v[22:23]
	v_add_f32_e32 v17, 1.0, v17
	v_rcp_f32_e32 v17, v17
	v_pk_add_f32 v[14:15], v[14:15], v[22:23]
	v_mul_f32_e32 v35, v17, v0
	v_and_b32_e32 v0, 0xffff0000, v24
	v_mul_f32_e32 v17, v0, v0
	v_fmamk_f32 v17, v17, 0xbdd2d3e7, v129
	v_mul_f32_e32 v17, v17, v0
	v_exp_f32_e32 v17, v17
	v_and_b32_e32 v24, 0xffff0000, v25
	v_mul_f32_e32 v34, v35, v35
	v_add_f32_e32 v17, 1.0, v17
	v_rcp_f32_e32 v17, v17
	s_nop 0
	v_mul_f32_e32 v37, v17, v0
	v_lshlrev_b32_e32 v0, 16, v25
	v_mul_f32_e32 v17, v0, v0
	v_fmamk_f32 v17, v17, 0xbdd2d3e7, v129
	v_mul_f32_e32 v17, v17, v0
	v_exp_f32_e32 v17, v17
	v_mul_f32_e32 v36, v37, v37
	v_mul_f32_e32 v25, v24, v24
	v_fmamk_f32 v25, v25, 0xbdd2d3e7, v129
	v_add_f32_e32 v17, 1.0, v17
	v_rcp_f32_e32 v17, v17
	v_pk_add_f32 v[22:23], v[34:35], v[36:37]
	v_mul_f32_e32 v25, v25, v24
	v_pk_add_f32 v[14:15], v[14:15], v[22:23]
	v_mul_f32_e32 v23, v17, v0
	v_lshlrev_b32_e32 v0, 16, v18
	v_mul_f32_e32 v17, v0, v0
	v_fmamk_f32 v17, v17, 0xbdd2d3e7, v129
	v_exp_f32_e32 v25, v25
	v_mul_f32_e32 v17, v17, v0
	v_exp_f32_e32 v17, v17
	v_add_f32_e32 v25, 1.0, v25
	v_rcp_f32_e32 v25, v25
	v_mul_f32_e32 v22, v23, v23
	v_add_f32_e32 v17, 1.0, v17
	v_rcp_f32_e32 v17, v17
	v_mul_f32_e32 v25, v25, v24
	v_mul_f32_e32 v24, v25, v25
	v_pk_add_f32 v[22:23], v[22:23], v[24:25]
	v_and_b32_e32 v34, 0xffff0000, v21
	v_pk_add_f32 v[14:15], v[14:15], v[22:23]
	v_mul_f32_e32 v23, v17, v0
	v_and_b32_e32 v0, 0xffff0000, v18
	v_mul_f32_e32 v17, v0, v0
	v_fmamk_f32 v17, v17, 0xbdd2d3e7, v129
	v_mul_f32_e32 v17, v17, v0
	v_exp_f32_e32 v17, v17
	v_mul_f32_e32 v22, v23, v23
	v_add_f32_e32 v17, 1.0, v17
	v_rcp_f32_e32 v17, v17
	s_nop 0
	v_mul_f32_e32 v25, v17, v0
	v_lshlrev_b32_e32 v0, 16, v19
	v_mul_f32_e32 v17, v0, v0
	v_fmamk_f32 v17, v17, 0xbdd2d3e7, v129
	v_mul_f32_e32 v17, v17, v0
	v_exp_f32_e32 v17, v17
	v_mul_f32_e32 v24, v25, v25
	v_add_f32_e32 v17, 1.0, v17
	v_rcp_f32_e32 v17, v17
	s_nop 0
	v_mul_f32_e32 v27, v17, v0
	v_and_b32_e32 v0, 0xffff0000, v19
	v_mul_f32_e32 v17, v0, v0
	v_fmamk_f32 v17, v17, 0xbdd2d3e7, v129
	v_mul_f32_e32 v17, v17, v0
	v_exp_f32_e32 v17, v17
	v_mul_f32_e32 v26, v27, v27
	v_add_f32_e32 v17, 1.0, v17
	v_rcp_f32_e32 v17, v17
	s_nop 0
	v_mul_f32_e32 v19, v17, v0
	v_lshlrev_b32_e32 v0, 16, v20
	v_mul_f32_e32 v17, v0, v0
	v_fmamk_f32 v17, v17, 0xbdd2d3e7, v129
	v_mul_f32_e32 v17, v17, v0
	v_exp_f32_e32 v17, v17
	v_mul_f32_e32 v18, v19, v19
	v_pk_add_f32 v[18:19], v[26:27], v[18:19]
	v_add_f32_e32 v17, 1.0, v17
	v_rcp_f32_e32 v17, v17
	s_nop 0
	v_mul_f32_e32 v29, v17, v0
	v_and_b32_e32 v0, 0xffff0000, v20
	v_mul_f32_e32 v17, v0, v0
	v_fmamk_f32 v17, v17, 0xbdd2d3e7, v129
	v_mul_f32_e32 v17, v17, v0
	v_exp_f32_e32 v17, v17
	v_mul_f32_e32 v20, v34, v34
	v_fmamk_f32 v20, v20, 0xbdd2d3e7, v129
	v_mul_f32_e32 v20, v20, v34
	v_add_f32_e32 v17, 1.0, v17
	v_rcp_f32_e32 v17, v17
	v_exp_f32_e32 v20, v20
	v_mul_f32_e32 v33, v17, v0
	v_lshlrev_b32_e32 v0, 16, v21
	v_mul_f32_e32 v17, v0, v0
	v_fmamk_f32 v17, v17, 0xbdd2d3e7, v129
	v_mul_f32_e32 v17, v17, v0
	v_exp_f32_e32 v17, v17
	v_add_f32_e32 v20, 1.0, v20
	v_rcp_f32_e32 v35, v20
	v_pk_add_f32 v[20:21], v[22:23], v[24:25]
	v_add_f32_e32 v17, 1.0, v17
	v_rcp_f32_e32 v17, v17
	v_mul_f32_e32 v28, v29, v29
	v_mul_f32_e32 v32, v33, v33
	v_pk_add_f32 v[14:15], v[14:15], v[20:21]
	v_mul_f32_e32 v21, v35, v34
	v_pk_add_f32 v[14:15], v[14:15], v[18:19]
	v_pk_add_f32 v[18:19], v[28:29], v[32:33]
	v_mul_f32_e32 v20, v21, v21
	v_pk_add_f32 v[14:15], v[14:15], v[18:19]
	v_mul_f32_e32 v19, v17, v0
	v_lshlrev_b32_e32 v0, 16, v6
	v_mul_f32_e32 v17, v0, v0
	v_fmamk_f32 v17, v17, 0xbdd2d3e7, v129
	v_mul_f32_e32 v17, v17, v0
	v_exp_f32_e32 v17, v17
	v_mul_f32_e32 v18, v19, v19
	v_pk_add_f32 v[18:19], v[18:19], v[20:21]
	v_and_b32_e32 v28, 0xffff0000, v9
	v_add_f32_e32 v17, 1.0, v17
	v_rcp_f32_e32 v17, v17
	v_pk_add_f32 v[14:15], v[14:15], v[18:19]
	v_mul_f32_e32 v19, v17, v0
	v_and_b32_e32 v0, 0xffff0000, v6
	v_mul_f32_e32 v6, v0, v0
	v_fmamk_f32 v6, v6, 0xbdd2d3e7, v129
	v_mul_f32_e32 v6, v6, v0
	v_exp_f32_e32 v6, v6
	v_mul_f32_e32 v18, v19, v19
	v_add_f32_e32 v6, 1.0, v6
	v_rcp_f32_e32 v6, v6
	s_nop 0
	v_mul_f32_e32 v21, v6, v0
	v_lshlrev_b32_e32 v0, 16, v7
	v_mul_f32_e32 v6, v0, v0
	v_fmamk_f32 v6, v6, 0xbdd2d3e7, v129
	v_mul_f32_e32 v6, v6, v0
	v_exp_f32_e32 v6, v6
	v_mul_f32_e32 v20, v21, v21
	v_add_f32_e32 v6, 1.0, v6
	v_rcp_f32_e32 v6, v6
	s_nop 0
	v_mul_f32_e32 v23, v6, v0
	v_and_b32_e32 v0, 0xffff0000, v7
	v_mul_f32_e32 v6, v0, v0
	v_fmamk_f32 v6, v6, 0xbdd2d3e7, v129
	v_mul_f32_e32 v6, v6, v0
	v_exp_f32_e32 v6, v6
	v_mul_f32_e32 v22, v23, v23
	v_add_f32_e32 v6, 1.0, v6
	v_rcp_f32_e32 v6, v6
	s_nop 0
	v_mul_f32_e32 v7, v6, v0
	v_lshlrev_b32_e32 v0, 16, v8
	v_mul_f32_e32 v17, v0, v0
	v_fmamk_f32 v17, v17, 0xbdd2d3e7, v129
	v_mul_f32_e32 v17, v17, v0
	v_exp_f32_e32 v17, v17
	v_mul_f32_e32 v6, v7, v7
	v_pk_add_f32 v[6:7], v[22:23], v[6:7]
	v_add_f32_e32 v17, 1.0, v17
	v_rcp_f32_e32 v17, v17
	s_nop 0
	v_mul_f32_e32 v25, v17, v0
	v_and_b32_e32 v0, 0xffff0000, v8
	v_mul_f32_e32 v8, v0, v0
	v_fmamk_f32 v8, v8, 0xbdd2d3e7, v129
	v_mul_f32_e32 v8, v8, v0
	v_exp_f32_e32 v8, v8
	v_mul_f32_e32 v24, v25, v25
	v_add_f32_e32 v8, 1.0, v8
	v_rcp_f32_e32 v8, v8
	s_nop 0
	v_mul_f32_e32 v27, v8, v0
	v_lshlrev_b32_e32 v0, 16, v9
	v_mul_f32_e32 v8, v0, v0
	v_fmamk_f32 v8, v8, 0xbdd2d3e7, v129
	v_mul_f32_e32 v8, v8, v0
	v_exp_f32_e32 v8, v8
	v_mul_f32_e32 v26, v27, v27
	v_add_f32_e32 v8, 1.0, v8
	v_rcp_f32_e32 v17, v8
	v_mul_f32_e32 v8, v28, v28
	v_fmamk_f32 v8, v8, 0xbdd2d3e7, v129
	v_mul_f32_e32 v8, v8, v28
	v_exp_f32_e32 v8, v8
	s_nop 0
	v_add_f32_e32 v8, 1.0, v8
	v_rcp_f32_e32 v29, v8
	v_pk_add_f32 v[8:9], v[18:19], v[20:21]
	s_nop 0
	v_pk_add_f32 v[8:9], v[14:15], v[8:9]
	v_mul_f32_e32 v15, v29, v28
	v_pk_add_f32 v[6:7], v[8:9], v[6:7]
	v_pk_add_f32 v[8:9], v[24:25], v[26:27]
	v_mul_f32_e32 v14, v15, v15
	v_pk_add_f32 v[6:7], v[6:7], v[8:9]
	v_mul_f32_e32 v9, v17, v0
	v_mul_f32_e32 v8, v9, v9
	v_pk_add_f32 v[8:9], v[8:9], v[14:15]
	v_lshlrev_b32_e32 v0, 16, v2
	v_pk_add_f32 v[6:7], v[6:7], v[8:9]
	v_mul_f32_e32 v8, v0, v0
	v_fmamk_f32 v8, v8, 0xbdd2d3e7, v129
	v_mul_f32_e32 v8, v8, v0
	v_exp_f32_e32 v8, v8
	v_and_b32_e32 v24, 0xffff0000, v5
	v_add_f32_e32 v8, 1.0, v8
	v_rcp_f32_e32 v8, v8
	s_nop 0
	v_mul_f32_e32 v9, v8, v0
	v_and_b32_e32 v0, 0xffff0000, v2
	v_mul_f32_e32 v2, v0, v0
	v_fmamk_f32 v2, v2, 0xbdd2d3e7, v129
	v_mul_f32_e32 v2, v2, v0
	v_exp_f32_e32 v2, v2
	v_mul_f32_e32 v8, v9, v9
	v_add_f32_e32 v2, 1.0, v2
	v_rcp_f32_e32 v2, v2
	s_nop 0
	v_mul_f32_e32 v15, v2, v0
	v_lshlrev_b32_e32 v0, 16, v3
	v_mul_f32_e32 v2, v0, v0
	v_fmamk_f32 v2, v2, 0xbdd2d3e7, v129
	v_mul_f32_e32 v2, v2, v0
	v_exp_f32_e32 v2, v2
	v_mul_f32_e32 v14, v15, v15
	v_add_f32_e32 v2, 1.0, v2
	v_rcp_f32_e32 v2, v2
	s_nop 0
	v_mul_f32_e32 v19, v2, v0
	v_and_b32_e32 v0, 0xffff0000, v3
	v_mul_f32_e32 v2, v0, v0
	v_fmamk_f32 v2, v2, 0xbdd2d3e7, v129
	v_mul_f32_e32 v2, v2, v0
	v_exp_f32_e32 v2, v2
	v_mul_f32_e32 v18, v19, v19
	v_add_f32_e32 v2, 1.0, v2
	v_rcp_f32_e32 v2, v2
	s_nop 0
	v_mul_f32_e32 v3, v2, v0
	v_lshlrev_b32_e32 v0, 16, v4
	v_mul_f32_e32 v17, v0, v0
	v_fmamk_f32 v17, v17, 0xbdd2d3e7, v129
	v_mul_f32_e32 v17, v17, v0
	v_exp_f32_e32 v17, v17
	v_mul_f32_e32 v2, v3, v3
	v_pk_add_f32 v[2:3], v[18:19], v[2:3]
	v_add_f32_e32 v17, 1.0, v17
	v_rcp_f32_e32 v17, v17
	s_nop 0
	v_mul_f32_e32 v21, v17, v0
	v_and_b32_e32 v0, 0xffff0000, v4
	v_mul_f32_e32 v4, v0, v0
	v_fmamk_f32 v4, v4, 0xbdd2d3e7, v129
	v_mul_f32_e32 v4, v4, v0
	v_exp_f32_e32 v4, v4
	v_mul_f32_e32 v20, v21, v21
	v_add_f32_e32 v4, 1.0, v4
	v_rcp_f32_e32 v4, v4
	s_nop 0
	v_mul_f32_e32 v23, v4, v0
	v_lshlrev_b32_e32 v0, 16, v5
	v_mul_f32_e32 v4, v0, v0
	v_fmamk_f32 v4, v4, 0xbdd2d3e7, v129
	v_mul_f32_e32 v4, v4, v0
	v_exp_f32_e32 v4, v4
	v_mul_f32_e32 v22, v23, v23
	v_add_f32_e32 v4, 1.0, v4
	v_rcp_f32_e32 v17, v4
	v_mul_f32_e32 v4, v24, v24
	v_fmamk_f32 v4, v4, 0xbdd2d3e7, v129
	v_mul_f32_e32 v4, v4, v24
	v_exp_f32_e32 v4, v4
	s_nop 0
	v_add_f32_e32 v4, 1.0, v4
	v_rcp_f32_e32 v25, v4
	v_pk_add_f32 v[4:5], v[8:9], v[14:15]
	s_nop 0
	v_pk_add_f32 v[4:5], v[6:7], v[4:5]
	v_mul_f32_e32 v7, v25, v24
	v_pk_add_f32 v[2:3], v[4:5], v[2:3]
	v_pk_add_f32 v[4:5], v[20:21], v[22:23]
	v_mul_f32_e32 v6, v7, v7
	v_pk_add_f32 v[2:3], v[2:3], v[4:5]
	v_mul_f32_e32 v5, v17, v0
	v_mul_f32_e32 v4, v5, v5
	v_pk_add_f32 v[4:5], v[4:5], v[6:7]
	s_nop 0
	v_pk_add_f32 v[18:19], v[2:3], v[4:5]
	s_cbranch_scc1 .LBB0_629
	v_and_b32_e32 v171, 0xff, v194
	v_lshlrev_b32_e32 v171, 3, v171
	s_mul_i32 s66, s64, 0x12000
	s_add_i32 s66, s66, 0x11000
	s_xor_b32 s67, s64, 1
	s_mul_i32 s67, s67, 0x12000
	s_add_i32 s67, s67, 0x11000
	v_add_u32_e32 v172, s66, v171
	v_add_u32_e32 v173, s67, v171
	ds_write_b64 v172, v[18:19]
	s_waitcnt lgkmcnt(0)
	s_barrier
	ds_read_b64 v[174:175], v173
	s_waitcnt lgkmcnt(0)
	v_add_f32_e32 v18, v18, v174
	v_add_f32_e32 v19, v19, v175
	s_mov_b32 s9, s89
	v_lshl_add_u64 v[2:3], v[10:11], 0, s[8:9]
	v_lshlrev_b32_e32 v0, 7, v16
	v_lshl_add_u64 v[22:23], v[2:3], 0, v[0:1]
	global_load_dwordx4 v[10:13], v[22:23], off offset:1024
	v_lshlrev_b32_e32 v20, 8, v16
	global_load_dwordx2 v[28:29], v20, s[16:17]
	global_load_dwordx2 v[36:37], v20, s[20:21]
	global_load_dwordx2 v[40:41], v20, s[16:17] offset:16
	global_load_dwordx2 v[42:43], v20, s[16:17] offset:32
	global_load_dwordx2 v[24:25], v20, s[16:17] offset:48
	global_load_dwordx2 v[44:45], v20, s[20:21] offset:16
	global_load_dwordx2 v[46:47], v20, s[20:21] offset:32
	global_load_dwordx2 v[26:27], v20, s[20:21] offset:48
	v_lshlrev_b32_e32 v34, 6, v16
	v_mul_u32_u24_e32 v4, 0x4400, v16
	global_load_dwordx4 v[14:17], v[22:23], off offset:1040
	ds_bpermute_b32 v3, v80, v19
	ds_bpermute_b32 v2, v80, v18
	s_mov_b32 s0, 0x3b000000
	v_lshlrev_b32_e32 v33, 1, v31
	v_add3_u32 v38, s15, v4, v33
	v_or_b32_e32 v4, 1, v34
	s_waitcnt lgkmcnt(0)
	v_pk_add_f32 v[2:3], v[18:19], v[2:3]
	v_mul_u32_u24_e32 v39, 0x110, v4
	v_pk_mul_f32 v[18:19], v[2:3], s[0:1] op_sel_hi:[1,0]
	v_or_b32_e32 v78, 7, v34
	v_fma_f32 v2, -v19, v19, v18
	v_max_f32_e32 v2, 0, v2
	v_add_f32_e32 v2, 0x358637bd, v2
	v_mul_f32_e32 v3, 0x4b800000, v2
	v_cmp_gt_f32_e32 vcc, s69, v2
	v_add3_u32 v18, s15, v39, v33
	v_or_b32_e32 v80, 10, v34
	v_cndmask_b32_e32 v2, v2, v3, vcc
	v_rsq_f32_e32 v48, v2
	global_load_dwordx4 v[2:5], v[22:23], off offset:1072
	global_load_dwordx4 v[6:9], v[22:23], off offset:1056
	v_or_b32_e32 v79, 11, v34
	v_readlane_b32 s40, v251, 22
	v_mul_f32_e32 v39, 0x45800000, v48
	v_cndmask_b32_e32 v39, v48, v39, vcc
	v_readlane_b32 s41, v251, 23
	v_mov_b32_e32 v21, v1
	v_mul_u32_u24_e32 v83, 0x110, v31
	v_add3_u32 v0, s15, v83, v0
	v_or_b32_e32 v100, 31, v34
	v_cmp_gt_u32_e32 vcc, v31, v34
	v_or_b32_e32 v35, 4, v34
	v_and_b32_e32 v32, 15, v50
	v_readlane_b32 s42, v251, 24
	v_readlane_b32 s43, v251, 25
	v_readlane_b32 s44, v251, 26
	v_readlane_b32 s45, v251, 27
	v_readlane_b32 s46, v251, 28
	v_readlane_b32 s47, v251, 29
	v_readlane_b32 s48, v251, 30
	v_readlane_b32 s49, v251, 31
	v_readlane_b32 s50, v251, 32
	v_readlane_b32 s51, v251, 33
	v_readlane_b32 s52, v251, 34
	v_readlane_b32 s53, v251, 35
	v_readlane_b32 s54, v251, 36
	v_readlane_b32 s55, v251, 37
	s_mov_b32 s2, 0x1f000
	s_waitcnt vmcnt(11)
	v_lshlrev_b32_e32 v48, 16, v10
	v_and_b32_e32 v10, 0xffff0000, v10
	v_lshlrev_b32_e32 v49, 16, v11
	v_and_b32_e32 v11, 0xffff0000, v11
	v_mul_f32_e32 v52, v48, v48
	v_mul_f32_e32 v53, v10, v10
	v_mul_f32_e32 v55, v11, v11
	v_fmamk_f32 v52, v52, 0xbdd2d3e7, v129
	v_fmamk_f32 v53, v53, 0xbdd2d3e7, v129
	v_fmamk_f32 v55, v55, 0xbdd2d3e7, v129
	v_mul_f32_e32 v52, v52, v48
	v_mul_f32_e32 v53, v53, v10
	v_mul_f32_e32 v55, v55, v11
	v_exp_f32_e32 v52, v52
	v_exp_f32_e32 v53, v53
	v_exp_f32_e32 v55, v55
	v_lshlrev_b32_e32 v51, 16, v12
	v_add_f32_e32 v52, 1.0, v52
	v_add_f32_e32 v53, 1.0, v53
	v_add_f32_e32 v55, 1.0, v55
	v_rcp_f32_e32 v52, v52
	v_mul_f32_e32 v56, v51, v51
	v_rcp_f32_e32 v53, v53
	v_rcp_f32_e32 v55, v55
	v_fmamk_f32 v56, v56, 0xbdd2d3e7, v129
	v_mul_f32_e32 v56, v56, v51
	v_fma_f32 v48, v52, v48, -v19
	v_and_b32_e32 v12, 0xffff0000, v12
	v_fma_f32 v10, v53, v10, -v19
	v_fma_f32 v11, v55, v11, -v19
	v_mul_f32_e32 v48, v39, v48
	v_mul_f32_e32 v57, 0x3d372713, v12
	v_exp_f32_e32 v56, v56
	v_mul_f32_e32 v10, v39, v10
	v_mul_f32_e32 v59, v39, v11
	s_waitcnt vmcnt(9)
	v_fma_f32 v11, v28, v48, v36
	v_mul_f32_e32 v57, v57, v12
	v_fmac_f32_e32 v37, v29, v10
	v_cvt_pk_bf16_f32 v10, v11, s0
	v_cvt_pk_bf16_f32 v11, v37, s0
	ds_write_b16 v38, v10 offset:34816
	ds_write_b16 v18, v11 offset:34816
	v_fma_f32 v10, v57, v12, v12
	v_mul_f32_e32 v10, 0xbfcc422a, v10
	v_lshlrev_b32_e32 v28, 16, v13
	v_add_f32_e32 v56, 1.0, v56
	v_mul_f32_e32 v10, 0x3fb8aa3b, v10
	v_mul_f32_e32 v29, v28, v28
	v_rcp_f32_e32 v56, v56
	v_exp_f32_e32 v10, v10
	v_fmamk_f32 v29, v29, 0xbdd2d3e7, v129
	v_mul_f32_e32 v29, v29, v28
	v_fma_f32 v51, v56, v51, -v19
	v_add_f32_e32 v10, 1.0, v10
	v_exp_f32_e32 v29, v29
	v_mul_f32_e32 v11, v39, v51
	v_rcp_f32_e32 v10, v10
	s_waitcnt vmcnt(5)
	v_fma_f32 v11, v40, v11, v44
	v_cvt_pk_bf16_f32 v11, v11, s0
	ds_write_b16 v18, v11 offset:35632
	v_add_f32_e32 v11, 1.0, v29
	v_fma_f32 v10, v10, v12, -v19
	v_rcp_f32_e32 v11, v11
	v_mul_f32_e32 v10, v39, v10
	v_fmac_f32_e32 v45, v10, v41
	v_cvt_pk_bf16_f32 v10, v45, s0
	ds_write_b16 v18, v10 offset:35904
	v_fma_f32 v10, v11, v28, -v19
	v_and_b32_e32 v11, 0xffff0000, v13
	v_mul_f32_e32 v12, v11, v11
	v_fmamk_f32 v12, v12, 0xbdd2d3e7, v129
	v_mul_f32_e32 v12, v12, v11
	v_exp_f32_e32 v12, v12
	s_waitcnt vmcnt(2)
	v_lshlrev_b32_e32 v13, 16, v14
	v_mul_f32_e32 v28, v13, v13
	v_fmamk_f32 v28, v28, 0xbdd2d3e7, v129
	v_add_f32_e32 v12, 1.0, v12
	v_rcp_f32_e32 v12, v12
	v_mul_f32_e32 v28, v28, v13
	v_fma_f32 v11, v12, v11, -v19
	v_exp_f32_e32 v28, v28
	v_mul_f32_e32 v44, v39, v11
	v_and_b32_e32 v11, 0xffff0000, v14
	v_mul_f32_e32 v12, v11, v11
	v_fmamk_f32 v12, v12, 0xbdd2d3e7, v129
	v_mul_f32_e32 v12, v12, v11
	v_mul_f32_e32 v45, v39, v10
	v_add_f32_e32 v10, 1.0, v28
	v_rcp_f32_e32 v10, v10
	v_exp_f32_e32 v12, v12
	v_lshlrev_b32_e32 v29, 16, v16
	v_fma_f32 v10, v10, v13, -v19
	v_lshlrev_b32_e32 v13, 16, v15
	v_add_f32_e32 v12, 1.0, v12
	v_mul_f32_e32 v14, v13, v13
	v_rcp_f32_e32 v12, v12
	v_fmamk_f32 v14, v14, 0xbdd2d3e7, v129
	v_mul_f32_e32 v10, v39, v10
	v_mul_f32_e32 v14, v14, v13
	v_fma_f32 v10, v42, v10, v46
	v_cvt_pk_bf16_f32 v10, v10, s0
	v_exp_f32_e32 v14, v14
	ds_write_b16 v18, v10 offset:36720
	v_fma_f32 v10, v12, v11, -v19
	v_mul_f32_e32 v10, v39, v10
	v_fmac_f32_e32 v47, v43, v10
	v_cvt_pk_bf16_f32 v10, v47, s0
	v_and_b32_e32 v15, 0xffff0000, v15
	v_add_f32_e32 v11, 1.0, v14
	ds_write_b16 v18, v10 offset:36992
	v_mul_f32_e32 v10, v15, v15
	v_rcp_f32_e32 v11, v11
	v_fmamk_f32 v10, v10, 0xbdd2d3e7, v129
	v_mul_f32_e32 v10, v10, v15
	v_fma_f32 v14, v11, v13, -v19
	v_exp_f32_e32 v28, v10
	global_load_dwordx2 v[10:11], v20, s[16:17] offset:64
	global_load_dwordx2 v[12:13], v20, s[20:21] offset:64
	v_mul_f32_e32 v37, v29, v29
	v_fmamk_f32 v37, v37, 0xbdd2d3e7, v129
	v_add_f32_e32 v28, 1.0, v28
	v_mul_f32_e32 v37, v37, v29
	v_rcp_f32_e32 v28, v28
	v_exp_f32_e32 v37, v37
	v_fma_f32 v15, v28, v15, -v19
	v_mul_f32_e32 v46, v39, v15
	v_and_b32_e32 v15, 0xffff0000, v16
	v_mul_f32_e32 v16, v15, v15
	v_mul_f32_e32 v47, v39, v14
	v_add_f32_e32 v14, 1.0, v37
	v_fmamk_f32 v16, v16, 0xbdd2d3e7, v129
	v_rcp_f32_e32 v14, v14
	v_mul_f32_e32 v16, v16, v15
	v_exp_f32_e32 v16, v16
	v_fma_f32 v14, v14, v29, -v19
	v_mul_f32_e32 v14, v39, v14
	v_fma_f32 v14, v24, v14, v26
	v_lshlrev_b32_e32 v24, 16, v17
	v_add_f32_e32 v16, 1.0, v16
	v_mul_f32_e32 v26, v24, v24
	v_rcp_f32_e32 v16, v16
	v_fmamk_f32 v26, v26, 0xbdd2d3e7, v129
	v_mul_f32_e32 v26, v26, v24
	v_cvt_pk_bf16_f32 v14, v14, s0
	v_exp_f32_e32 v26, v26
	ds_write_b16 v18, v14 offset:37808
	v_fma_f32 v14, v16, v15, -v19
	v_mul_f32_e32 v14, v39, v14
	v_fmac_f32_e32 v27, v14, v25
	v_cvt_pk_bf16_f32 v14, v27, s0
	v_and_b32_e32 v25, 0xffff0000, v17
	v_add_f32_e32 v15, 1.0, v26
	ds_write_b16 v18, v14 offset:38080
	v_mul_f32_e32 v14, v25, v25
	v_rcp_f32_e32 v15, v15
	v_fmamk_f32 v14, v14, 0xbdd2d3e7, v129
	v_mul_f32_e32 v14, v14, v25
	v_fma_f32 v24, v15, v24, -v19
	v_exp_f32_e32 v26, v14
	global_load_dwordx2 v[14:15], v20, s[16:17] offset:80
	global_load_dwordx2 v[16:17], v20, s[20:21] offset:80
	s_waitcnt vmcnt(4)
	v_lshlrev_b32_e32 v27, 16, v6
	v_mul_f32_e32 v28, v27, v27
	v_fmamk_f32 v28, v28, 0xbdd2d3e7, v129
	v_mul_f32_e32 v28, v28, v27
	v_exp_f32_e32 v28, v28
	v_mul_f32_e32 v55, v39, v24
	v_mul_f32_e32 v54, v49, v49
	v_fmamk_f32 v54, v54, 0xbdd2d3e7, v129
	v_add_f32_e32 v24, 1.0, v28
	v_rcp_f32_e32 v24, v24
	v_and_b32_e32 v6, 0xffff0000, v6
	v_mul_f32_e32 v54, v54, v49
	v_fma_f32 v24, v24, v27, -v19
	v_mul_f32_e32 v40, v39, v24
	v_mul_f32_e32 v24, v6, v6
	v_fmamk_f32 v24, v24, 0xbdd2d3e7, v129
	v_mul_f32_e32 v24, v24, v6
	v_exp_f32_e32 v54, v54
	v_exp_f32_e32 v41, v24
	v_add_f32_e32 v54, 1.0, v54
	v_add_f32_e32 v26, 1.0, v26
	v_rcp_f32_e32 v54, v54
	v_rcp_f32_e32 v26, v26
	s_waitcnt vmcnt(2)
	v_fma_f32 v10, v10, v40, v12
	v_lshlrev_b32_e32 v40, 16, v7
	v_add_f32_e32 v12, 1.0, v41
	v_mul_f32_e32 v41, v40, v40
	v_fmamk_f32 v41, v41, 0xbdd2d3e7, v129
	v_mul_f32_e32 v41, v41, v40
	v_fma_f32 v49, v54, v49, -v19
	v_fma_f32 v25, v26, v25, -v19
	v_mul_f32_e32 v65, v39, v49
	v_mul_f32_e32 v54, v39, v25
	global_load_dwordx2 v[24:25], v20, s[16:17] offset:96
	global_load_dwordx2 v[28:29], v20, s[16:17] offset:112
	global_load_dwordx2 v[26:27], v20, s[20:21] offset:96
	global_load_dwordx2 v[48:49], v20, s[20:21] offset:112
	v_exp_f32_e32 v41, v41
	v_rcp_f32_e32 v12, v12
	v_cvt_pk_bf16_f32 v10, v10, s0
	ds_write_b16 v18, v10 offset:38896
	v_add_f32_e32 v10, 1.0, v41
	v_fma_f32 v6, v12, v6, -v19
	v_rcp_f32_e32 v10, v10
	v_mul_f32_e32 v6, v39, v6
	v_fmac_f32_e32 v13, v11, v6
	v_cvt_pk_bf16_f32 v6, v13, s0
	v_and_b32_e32 v7, 0xffff0000, v7
	ds_write_b16 v18, v6 offset:39168
	v_fma_f32 v6, v10, v40, -v19
	v_mul_f32_e32 v10, v7, v7
	v_fmamk_f32 v10, v10, 0xbdd2d3e7, v129
	v_mul_f32_e32 v10, v10, v7
	v_exp_f32_e32 v10, v10
	v_lshlrev_b32_e32 v11, 16, v8
	v_mul_f32_e32 v12, v11, v11
	v_fmamk_f32 v12, v12, 0xbdd2d3e7, v129
	v_mul_f32_e32 v12, v12, v11
	v_add_f32_e32 v10, 1.0, v10
	v_rcp_f32_e32 v10, v10
	v_exp_f32_e32 v12, v12
	v_mul_f32_e32 v53, v39, v6
	v_fma_f32 v7, v10, v7, -v19
	v_mul_f32_e32 v52, v39, v7
	v_and_b32_e32 v7, 0xffff0000, v8
	v_add_f32_e32 v6, 1.0, v12
	v_mul_f32_e32 v8, v7, v7
	v_rcp_f32_e32 v6, v6
	v_fmamk_f32 v8, v8, 0xbdd2d3e7, v129
	v_mul_f32_e32 v8, v8, v7
	v_lshlrev_b32_e32 v10, 16, v9
	v_fma_f32 v6, v6, v11, -v19
	v_exp_f32_e32 v8, v8
	v_mul_f32_e32 v11, v10, v10
	v_fmamk_f32 v11, v11, 0xbdd2d3e7, v129
	v_mul_f32_e32 v11, v11, v10
	v_add_f32_e32 v8, 1.0, v8
	v_rcp_f32_e32 v8, v8
	v_exp_f32_e32 v11, v11
	v_mul_f32_e32 v6, v39, v6
	s_waitcnt vmcnt(4)
	v_fma_f32 v6, v14, v6, v16
	v_cvt_pk_bf16_f32 v6, v6, s0
	ds_write_b16 v18, v6 offset:39984
	v_fma_f32 v6, v8, v7, -v19
	v_add_f32_e32 v7, 1.0, v11
	v_rcp_f32_e32 v7, v7
	v_mul_f32_e32 v6, v39, v6
	v_fmac_f32_e32 v17, v6, v15
	v_cvt_pk_bf16_f32 v6, v17, s0
	ds_write_b16 v18, v6 offset:40256
	v_fma_f32 v6, v7, v10, -v19
	v_and_b32_e32 v7, 0xffff0000, v9
	v_lshlrev_b32_e32 v9, 16, v2
	v_mul_f32_e32 v10, v9, v9
	v_fmamk_f32 v10, v10, 0xbdd2d3e7, v129
	v_mul_f32_e32 v8, v7, v7
	v_mul_f32_e32 v10, v10, v9
	v_fmamk_f32 v8, v8, 0xbdd2d3e7, v129
	v_mul_f32_e32 v8, v8, v7
	v_exp_f32_e32 v10, v10
	v_exp_f32_e32 v8, v8
	v_mul_f32_e32 v58, v39, v6
	v_add_f32_e32 v6, 1.0, v10
	global_load_dwordx4 v[10:13], v[22:23], off offset:1104
	global_load_dwordx4 v[14:17], v[22:23], off offset:1088
	v_add_f32_e32 v8, 1.0, v8
	v_rcp_f32_e32 v8, v8
	v_and_b32_e32 v2, 0xffff0000, v2
	v_rcp_f32_e32 v6, v6
	v_or_b32_e32 v36, 8, v34
	v_fma_f32 v7, v8, v7, -v19
	v_mul_f32_e32 v56, v39, v7
	v_mul_f32_e32 v7, v2, v2
	v_fmamk_f32 v7, v7, 0xbdd2d3e7, v129
	v_mul_f32_e32 v7, v7, v2
	v_exp_f32_e32 v7, v7
	v_lshlrev_b32_e32 v8, 16, v3
	v_fma_f32 v6, v6, v9, -v19
	v_mul_f32_e32 v9, v8, v8
	v_add_f32_e32 v7, 1.0, v7
	v_rcp_f32_e32 v7, v7
	v_fmamk_f32 v9, v9, 0xbdd2d3e7, v129
	v_mul_f32_e32 v9, v9, v8
	v_fma_f32 v2, v7, v2, -v19
	v_mul_f32_e32 v6, v39, v6
	v_mul_f32_e32 v2, v39, v2
	s_waitcnt vmcnt(3)
	v_fma_f32 v6, v24, v6, v26
	v_exp_f32_e32 v9, v9
	v_fmac_f32_e32 v27, v25, v2
	v_cvt_pk_bf16_f32 v6, v6, s0
	v_cvt_pk_bf16_f32 v2, v27, s0
	ds_write_b16 v18, v6 offset:41072
	ds_write_b16 v18, v2 offset:41344
	global_load_dwordx2 v[24:25], v20, s[16:17] offset:128
	global_load_dwordx2 v[26:27], v20, s[20:21] offset:128
	v_add_f32_e32 v6, 1.0, v9
	v_rcp_f32_e32 v6, v6
	v_and_b32_e32 v3, 0xffff0000, v3
	v_lshlrev_b32_e32 v7, 16, v4
	v_or_b32_e32 v37, 12, v34
	v_fma_f32 v2, v6, v8, -v19
	v_mul_f32_e32 v6, v3, v3
	v_fmamk_f32 v6, v6, 0xbdd2d3e7, v129
	v_mul_f32_e32 v6, v6, v3
	v_exp_f32_e32 v6, v6
	v_mul_f32_e32 v8, v7, v7
	v_fmamk_f32 v8, v8, 0xbdd2d3e7, v129
	v_mul_f32_e32 v8, v8, v7
	v_add_f32_e32 v6, 1.0, v6
	v_rcp_f32_e32 v6, v6
	v_exp_f32_e32 v8, v8
	v_mul_f32_e32 v64, v39, v2
	v_fma_f32 v3, v6, v3, -v19
	v_mul_f32_e32 v63, v39, v3
	v_and_b32_e32 v3, 0xffff0000, v4
	v_add_f32_e32 v2, 1.0, v8
	v_mul_f32_e32 v4, v3, v3
	v_rcp_f32_e32 v2, v2
	v_fmamk_f32 v4, v4, 0xbdd2d3e7, v129
	v_mul_f32_e32 v4, v4, v3
	v_fma_f32 v2, v2, v7, -v19
	v_exp_f32_e32 v4, v4
	v_mul_f32_e32 v2, v39, v2
	s_waitcnt vmcnt(4)
	v_fma_f32 v2, v28, v2, v48
	v_cvt_pk_bf16_f32 v2, v2, s0
	ds_write_b16 v18, v2 offset:42160
	v_add_f32_e32 v2, 1.0, v4
	v_lshlrev_b32_e32 v4, 16, v5
	v_mul_f32_e32 v6, v4, v4
	v_fmamk_f32 v6, v6, 0xbdd2d3e7, v129
	v_rcp_f32_e32 v2, v2
	v_mul_f32_e32 v6, v6, v4
	v_exp_f32_e32 v6, v6
	v_fma_f32 v2, v2, v3, -v19
	v_mul_f32_e32 v2, v39, v2
	v_fmac_f32_e32 v49, v2, v29
	v_add_f32_e32 v2, 1.0, v6
	v_cvt_pk_bf16_f32 v6, v49, s0
	ds_write_b16 v18, v6 offset:42432
	global_load_dwordx2 v[60:61], v20, s[16:17] offset:144
	global_load_dwordx2 v[66:67], v20, s[20:21] offset:144
	v_and_b32_e32 v3, 0xffff0000, v5
	v_mul_f32_e32 v5, v3, v3
	v_fmamk_f32 v5, v5, 0xbdd2d3e7, v129
	v_mul_f32_e32 v5, v5, v3
	v_rcp_f32_e32 v2, v2
	v_exp_f32_e32 v5, v5
	s_waitcnt vmcnt(4)
	v_lshlrev_b32_e32 v28, 16, v14
	v_and_b32_e32 v14, 0xffff0000, v14
	v_fma_f32 v2, v2, v4, -v19
	v_add_f32_e32 v4, 1.0, v5
	v_mul_f32_e32 v5, v28, v28
	v_fmamk_f32 v5, v5, 0xbdd2d3e7, v129
	v_mul_f32_e32 v5, v5, v28
	v_rcp_f32_e32 v4, v4
	v_exp_f32_e32 v5, v5
	v_mul_f32_e32 v69, v39, v2
	v_fma_f32 v2, v4, v3, -v19
	v_mul_f32_e32 v68, v39, v2
	v_add_f32_e32 v2, 1.0, v5
	v_rcp_f32_e32 v29, v2
	global_load_dwordx4 v[2:5], v[22:23], off offset:1136
	global_load_dwordx4 v[6:9], v[22:23], off offset:1120
	v_or_b32_e32 v38, 16, v34
	v_or_b32_e32 v40, 20, v34
	v_fma_f32 v22, v29, v28, -v19
	v_mul_f32_e32 v48, v39, v22
	v_mul_f32_e32 v22, v14, v14
	v_fmamk_f32 v22, v22, 0xbdd2d3e7, v129
	v_mul_f32_e32 v22, v22, v14
	v_exp_f32_e32 v49, v22
	global_load_dwordx2 v[74:75], v20, s[16:17] offset:160
	global_load_dwordx2 v[22:23], v20, s[16:17] offset:176
	global_load_dwordx2 v[76:77], v20, s[20:21] offset:160
	global_load_dwordx2 v[28:29], v20, s[20:21] offset:176
	s_waitcnt vmcnt(8)
	v_fma_f32 v24, v24, v48, v26
	v_lshlrev_b32_e32 v48, 16, v15
	v_add_f32_e32 v26, 1.0, v49
	v_mul_f32_e32 v49, v48, v48
	v_fmamk_f32 v49, v49, 0xbdd2d3e7, v129
	v_mul_f32_e32 v49, v49, v48
	v_exp_f32_e32 v49, v49
	v_rcp_f32_e32 v26, v26
	v_cvt_pk_bf16_f32 v24, v24, s0
	ds_write_b16 v18, v24 offset:43248
	v_add_f32_e32 v24, 1.0, v49
	v_fma_f32 v14, v26, v14, -v19
	v_rcp_f32_e32 v24, v24
	v_mul_f32_e32 v14, v39, v14
	v_fmac_f32_e32 v27, v25, v14
	v_cvt_pk_bf16_f32 v14, v27, s0
	v_and_b32_e32 v15, 0xffff0000, v15
	ds_write_b16 v18, v14 offset:43520
	v_fma_f32 v14, v24, v48, -v19
	v_mul_f32_e32 v24, v15, v15
	v_fmamk_f32 v24, v24, 0xbdd2d3e7, v129
	v_mul_f32_e32 v24, v24, v15
	v_exp_f32_e32 v24, v24
	v_lshlrev_b32_e32 v25, 16, v16
	v_mul_f32_e32 v26, v25, v25
	v_fmamk_f32 v26, v26, 0xbdd2d3e7, v129
	v_mul_f32_e32 v26, v26, v25
	v_add_f32_e32 v24, 1.0, v24
	v_rcp_f32_e32 v24, v24
	v_exp_f32_e32 v26, v26
	v_mul_f32_e32 v73, v39, v14
	v_fma_f32 v15, v24, v15, -v19
	v_mul_f32_e32 v72, v39, v15
	v_and_b32_e32 v15, 0xffff0000, v16
	v_add_f32_e32 v14, 1.0, v26
	v_mul_f32_e32 v16, v15, v15
	v_rcp_f32_e32 v14, v14
	v_fmamk_f32 v16, v16, 0xbdd2d3e7, v129
	v_mul_f32_e32 v16, v16, v15
	v_lshlrev_b32_e32 v24, 16, v17
	v_fma_f32 v14, v14, v25, -v19
	v_exp_f32_e32 v16, v16
	v_mul_f32_e32 v25, v24, v24
	v_fmamk_f32 v25, v25, 0xbdd2d3e7, v129
	v_mul_f32_e32 v25, v25, v24
	v_add_f32_e32 v16, 1.0, v16
	v_rcp_f32_e32 v16, v16
	v_exp_f32_e32 v25, v25
	v_mul_f32_e32 v14, v39, v14
	s_waitcnt vmcnt(6)
	v_fma_f32 v14, v60, v14, v66
	v_cvt_pk_bf16_f32 v14, v14, s0
	ds_write_b16 v18, v14 offset:44336
	v_fma_f32 v14, v16, v15, -v19
	v_add_f32_e32 v15, 1.0, v25
	v_rcp_f32_e32 v15, v15
	v_mul_f32_e32 v14, v39, v14
	v_fmac_f32_e32 v67, v14, v61
	v_cvt_pk_bf16_f32 v14, v67, s0
	ds_write_b16 v18, v14 offset:44608
	v_fma_f32 v14, v15, v24, -v19
	v_and_b32_e32 v15, 0xffff0000, v17
	v_mul_f32_e32 v16, v15, v15
	v_fmamk_f32 v16, v16, 0xbdd2d3e7, v129
	v_mul_f32_e32 v16, v16, v15
	v_exp_f32_e32 v16, v16
	v_lshlrev_b32_e32 v17, 16, v10
	v_mul_f32_e32 v24, v17, v17
	v_fmamk_f32 v24, v24, 0xbdd2d3e7, v129
	v_mul_f32_e32 v24, v24, v17
	v_add_f32_e32 v16, 1.0, v16
	v_rcp_f32_e32 v16, v16
	v_exp_f32_e32 v24, v24
	v_and_b32_e32 v10, 0xffff0000, v10
	v_mul_f32_e32 v71, v39, v14
	v_fma_f32 v15, v16, v15, -v19
	v_add_f32_e32 v14, 1.0, v24
	v_mul_f32_e32 v70, v39, v15
	v_mul_f32_e32 v15, v10, v10
	v_rcp_f32_e32 v14, v14
	v_fmamk_f32 v15, v15, 0xbdd2d3e7, v129
	v_mul_f32_e32 v15, v15, v10
	v_fma_f32 v14, v14, v17, -v19
	v_exp_f32_e32 v15, v15
	v_mul_f32_e32 v14, v39, v14
	s_waitcnt vmcnt(1)
	v_fma_f32 v14, v74, v14, v76
	v_cvt_pk_bf16_f32 v14, v14, s0
	ds_write_b16 v18, v14 offset:45424
	v_add_f32_e32 v14, 1.0, v15
	v_lshlrev_b32_e32 v15, 16, v11
	v_rcp_f32_e32 v14, v14
	v_mul_f32_e32 v16, v15, v15
	v_fmamk_f32 v16, v16, 0xbdd2d3e7, v129
	v_mul_f32_e32 v16, v16, v15
	v_and_b32_e32 v11, 0xffff0000, v11
	v_fma_f32 v10, v14, v10, -v19
	v_mul_f32_e32 v14, v11, v11
	v_exp_f32_e32 v16, v16
	v_fmamk_f32 v14, v14, 0xbdd2d3e7, v129
	v_mul_f32_e32 v14, v14, v11
	v_mul_f32_e32 v10, v39, v10
	v_fmac_f32_e32 v77, v75, v10
	v_add_f32_e32 v10, 1.0, v16
	v_exp_f32_e32 v14, v14
	v_rcp_f32_e32 v10, v10
	v_cvt_pk_bf16_f32 v16, v77, s0
	ds_write_b16 v18, v16 offset:45696
	v_add_f32_e32 v14, 1.0, v14
	v_fma_f32 v10, v10, v15, -v19
	v_rcp_f32_e32 v14, v14
	v_lshlrev_b32_e32 v15, 16, v12
	v_mul_f32_e32 v16, v15, v15
	v_fmamk_f32 v16, v16, 0xbdd2d3e7, v129
	v_mul_f32_e32 v16, v16, v15
	v_mul_f32_e32 v67, v39, v10
	v_fma_f32 v10, v14, v11, -v19
	v_and_b32_e32 v11, 0xffff0000, v12
	v_mul_f32_e32 v12, v11, v11
	v_exp_f32_e32 v16, v16
	v_fmamk_f32 v12, v12, 0xbdd2d3e7, v129
	v_mul_f32_e32 v12, v12, v11
	v_mul_f32_e32 v66, v39, v10
	v_add_f32_e32 v10, 1.0, v16
	v_exp_f32_e32 v12, v12
	v_rcp_f32_e32 v10, v10
	v_or_b32_e32 v76, 2, v34
	v_or_b32_e32 v77, 3, v34
	v_add_f32_e32 v12, 1.0, v12
	v_fma_f32 v10, v10, v15, -v19
	v_rcp_f32_e32 v12, v12
	v_mul_f32_e32 v10, v39, v10
	s_waitcnt vmcnt(0)
	v_fma_f32 v10, v22, v10, v28
	v_cvt_pk_bf16_f32 v10, v10, s0
	ds_write_b16 v18, v10 offset:46512
	v_fma_f32 v10, v12, v11, -v19
	v_lshlrev_b32_e32 v11, 16, v13
	v_mul_f32_e32 v12, v11, v11
	v_fmamk_f32 v12, v12, 0xbdd2d3e7, v129
	v_mul_f32_e32 v12, v12, v11
	v_exp_f32_e32 v12, v12
	v_mul_f32_e32 v10, v39, v10
	v_fmac_f32_e32 v29, v10, v23
	v_lshlrev_b32_e32 v14, 2, v76
	v_add_f32_e32 v12, 1.0, v12
	v_rcp_f32_e32 v12, v12
	v_cvt_pk_bf16_f32 v10, v29, s0
	v_lshlrev_b32_e32 v16, 2, v77
	global_load_dword v15, v14, s[16:17]
	s_nop 0
	global_load_dword v14, v14, s[20:21]
	s_nop 0
	global_load_dword v17, v16, s[16:17]
	s_nop 0
	global_load_dword v16, v16, s[20:21]
	ds_write_b16 v18, v10 offset:46784
	v_fma_f32 v10, v12, v11, -v19
	v_and_b32_e32 v11, 0xffff0000, v13
	v_lshlrev_b32_e32 v13, 16, v6
	v_mul_f32_e32 v22, v13, v13
	v_fmamk_f32 v22, v22, 0xbdd2d3e7, v129
	v_mul_f32_e32 v22, v22, v13
	v_mul_f32_e32 v12, v11, v11
	v_fmamk_f32 v12, v12, 0xbdd2d3e7, v129
	v_exp_f32_e32 v22, v22
	v_mul_f32_e32 v12, v12, v11
	v_exp_f32_e32 v12, v12
	v_mul_f32_e32 v75, v39, v10
	v_add_f32_e32 v10, 1.0, v22
	v_rcp_f32_e32 v10, v10
	v_add_f32_e32 v12, 1.0, v12
	v_and_b32_e32 v6, 0xffff0000, v6
	v_rcp_f32_e32 v12, v12
	v_fma_f32 v22, v10, v13, -v19
	v_mul_f32_e32 v10, v6, v6
	v_fmamk_f32 v10, v10, 0xbdd2d3e7, v129
	v_mul_f32_e32 v10, v10, v6
	v_fma_f32 v11, v12, v11, -v19
	v_mul_f32_e32 v74, v39, v11
	v_exp_f32_e32 v23, v10
	global_load_dwordx2 v[10:11], v20, s[16:17] offset:192
	global_load_dwordx2 v[12:13], v20, s[20:21] offset:192
	v_mul_f32_e32 v81, v39, v22
	v_lshlrev_b32_e32 v90, 16, v8
	v_add_f32_e32 v22, 1.0, v23
	v_lshlrev_b32_e32 v23, 16, v7
	v_mul_f32_e32 v24, v23, v23
	v_and_b32_e32 v7, 0xffff0000, v7
	v_fmamk_f32 v24, v24, 0xbdd2d3e7, v129
	v_mul_f32_e32 v25, v7, v7
	v_mul_f32_e32 v24, v24, v23
	v_fmamk_f32 v25, v25, 0xbdd2d3e7, v129
	v_mul_f32_e32 v25, v25, v7
	v_rcp_f32_e32 v22, v22
	v_exp_f32_e32 v24, v24
	v_exp_f32_e32 v25, v25
	v_fma_f32 v6, v22, v6, -v19
	v_add_f32_e32 v22, 1.0, v24
	v_rcp_f32_e32 v22, v22
	v_add_f32_e32 v24, 1.0, v25
	v_rcp_f32_e32 v24, v24
	v_mul_f32_e32 v82, v39, v6
	v_fma_f32 v6, v22, v23, -v19
	v_mul_f32_e32 v62, v39, v6
	v_fma_f32 v6, v24, v7, -v19
	v_mul_f32_e32 v61, v39, v6
	v_or_b32_e32 v6, s88, v31
	v_lshlrev_b32_e32 v6, 7, v6
	v_mov_b32_e32 v7, v1
	v_lshl_add_u64 v[6:7], v[6:7], 2, s[40:41]
	v_lshl_add_u64 v[6:7], v[6:7], 0, v[20:21]
	v_and_b32_e32 v8, 0xffff0000, v8
	v_mul_f32_e32 v97, v8, v8
	v_fmamk_f32 v97, v97, 0xbdd2d3e7, v129
	v_mul_f32_e32 v97, v97, v8
	v_exp_f32_e32 v97, v97
	v_and_b32_e32 v98, 0xffff0000, v9
	v_and_b32_e32 v104, 0xffff0000, v5
	v_or_b32_e32 v41, 24, v34
	v_or_b32_e32 v42, 28, v34
	v_or_b32_e32 v43, 32, v34
	v_or_b32_e32 v48, 36, v34
	s_waitcnt vmcnt(4)
	v_fmac_f32_e32 v14, v15, v65
	v_mul_u32_u24_e32 v15, 0x110, v76
	v_cvt_pk_bf16_f32 v14, v14, s0
	v_add3_u32 v15, s15, v15, v33
	v_or_b32_e32 v65, 6, v34
	ds_write_b16 v15, v14 offset:34816
	v_lshlrev_b32_e32 v14, 2, v65
	global_load_dword v84, v14, s[16:17]
	global_load_dword v85, v14, s[20:21]
	s_waitcnt vmcnt(4)
	v_fmac_f32_e32 v16, v17, v59
	v_lshlrev_b32_e32 v14, 2, v78
	v_mul_u32_u24_e32 v15, 0x110, v77
	global_load_dword v86, v14, s[16:17]
	global_load_dword v87, v14, s[20:21]
	v_cvt_pk_bf16_f32 v14, v16, s0
	v_add3_u32 v15, s15, v15, v33
	ds_write_b16 v15, v14 offset:34816
	v_lshlrev_b32_e32 v14, 2, v80
	global_load_dwordx2 v[22:23], v20, s[16:17] offset:208
	global_load_dwordx2 v[24:25], v20, s[20:21] offset:208
	global_load_dword v88, v14, s[16:17]
	global_load_dword v89, v14, s[20:21]
	v_lshlrev_b32_e32 v14, 2, v79
	global_load_dword v91, v14, s[16:17]
	global_load_dword v92, v14, s[20:21]
	v_mul_f32_e32 v14, v90, v90
	v_fmamk_f32 v14, v14, 0xbdd2d3e7, v129
	v_mul_f32_e32 v14, v14, v90
	v_or_b32_e32 v59, 14, v34
	v_lshlrev_b32_e32 v15, 2, v59
	global_load_dword v93, v15, s[16:17]
	global_load_dword v94, v15, s[20:21]
	v_exp_f32_e32 v95, v14
	global_load_dwordx2 v[14:15], v20, s[16:17] offset:224
	global_load_dwordx2 v[16:17], v20, s[16:17] offset:240
	global_load_dwordx2 v[26:27], v20, s[20:21] offset:224
	s_nop 0
	global_load_dwordx2 v[20:21], v20, s[20:21] offset:240
	v_or_b32_e32 v49, 40, v34
	v_or_b32_e32 v51, 44, v34
	v_or_b32_e32 v57, 48, v34
	s_waitcnt vmcnt(16)
	v_fma_f32 v10, v10, v81, v12
	v_cvt_pk_bf16_f32 v12, v10, s0
	v_or_b32_e32 v10, 15, v34
	v_add_f32_e32 v81, 1.0, v95
	v_lshlrev_b32_e32 v95, 2, v10
	global_load_dword v96, v95, s[16:17]
	s_nop 0
	global_load_dword v95, v95, s[20:21]
	v_rcp_f32_e32 v81, v81
	ds_write_b16 v18, v12 offset:47600
	v_fmac_f32_e32 v13, v11, v82
	v_cvt_pk_bf16_f32 v11, v13, s0
	v_fma_f32 v12, v81, v90, -v19
	v_lshlrev_b32_e32 v90, 16, v9
	v_add_f32_e32 v81, 1.0, v97
	v_mul_f32_e32 v97, v90, v90
	v_fmamk_f32 v97, v97, 0xbdd2d3e7, v129
	v_mul_f32_e32 v97, v97, v90
	v_rcp_f32_e32 v81, v81
	v_exp_f32_e32 v97, v97
	v_mul_f32_e32 v12, v39, v12
	v_mul_u32_u24_e32 v13, 0x110, v80
	v_fma_f32 v8, v81, v8, -v19
	v_add_f32_e32 v81, 1.0, v97
	v_rcp_f32_e32 v81, v81
	v_mul_f32_e32 v99, v39, v8
	v_add3_u32 v13, s15, v13, v33
	v_mul_f32_e32 v9, v98, v98
	v_fma_f32 v8, v81, v90, -v19
	v_mul_u32_u24_e32 v81, 0x110, v65
	v_add3_u32 v81, s15, v81, v33
	v_fmamk_f32 v9, v9, 0xbdd2d3e7, v129
	v_mul_f32_e32 v9, v9, v98
	v_exp_f32_e32 v9, v9
	v_or_b32_e32 v90, 26, v34
	v_or_b32_e32 v60, 52, v34
	v_or_b32_e32 v29, 56, v34
	v_add_f32_e32 v9, 1.0, v9
	v_rcp_f32_e32 v97, v9
	v_mul_f32_e32 v9, v39, v8
	v_or_b32_e32 v28, 60, v34
	v_readlane_b32 s40, v251, 54
	v_fma_f32 v8, v97, v98, -v19
	v_or_b32_e32 v97, 30, v34
	v_mul_f32_e32 v8, v39, v8
	v_readlane_b32 s46, v251, 60
	v_readlane_b32 s47, v251, 61
	v_readlane_b32 s48, v251, 62
	v_readlane_b32 s49, v251, 63
	v_readlane_b32 s41, v251, 55
	v_readlane_b32 s42, v251, 56
	v_readlane_b32 s43, v251, 57
	s_waitcnt vmcnt(16)
	v_fmac_f32_e32 v85, v45, v84
	v_cvt_pk_bf16_f32 v45, v85, s0
	ds_write_b16 v81, v45 offset:34816
	v_mul_u32_u24_e32 v45, 0x110, v78
	s_waitcnt vmcnt(14)
	v_fmac_f32_e32 v87, v44, v86
	v_cvt_pk_bf16_f32 v44, v87, s0
	v_add3_u32 v45, s15, v45, v33
	ds_write_b16 v45, v44 offset:34816
	ds_write_b16 v18, v11 offset:47872
	s_waitcnt vmcnt(12)
	v_fma_f32 v11, v22, v12, v24
	s_waitcnt vmcnt(10)
	v_fmac_f32_e32 v89, v88, v47
	v_cvt_pk_bf16_f32 v12, v89, s0
	ds_write_b16 v13, v12 offset:34816
	s_waitcnt vmcnt(8)
	v_fmac_f32_e32 v92, v91, v46
	v_mul_u32_u24_e32 v13, 0x110, v79
	v_cvt_pk_bf16_f32 v12, v92, s0
	v_add3_u32 v13, s15, v13, v33
	v_cvt_pk_bf16_f32 v11, v11, s0
	ds_write_b16 v13, v12 offset:34816
	ds_write_b16 v18, v11 offset:48688
	v_lshlrev_b32_e32 v13, 16, v2
	v_mul_f32_e32 v22, v13, v13
	v_fmamk_f32 v22, v22, 0xbdd2d3e7, v129
	v_mul_f32_e32 v22, v22, v13
	v_exp_f32_e32 v22, v22
	v_fmac_f32_e32 v25, v99, v23
	v_cvt_pk_bf16_f32 v11, v25, s0
	s_waitcnt vmcnt(6)
	v_fmac_f32_e32 v94, v55, v93
	v_mul_u32_u24_e32 v12, 0x110, v59
	ds_write_b16 v18, v11 offset:48960
	v_cvt_pk_bf16_f32 v11, v94, s0
	v_add3_u32 v12, s15, v12, v33
	ds_write_b16 v12, v11 offset:34816
	v_add_f32_e32 v12, 1.0, v22
	v_rcp_f32_e32 v12, v12
	s_waitcnt vmcnt(0)
	v_fmac_f32_e32 v95, v54, v96
	v_mul_u32_u24_e32 v22, 0x110, v10
	v_cvt_pk_bf16_f32 v11, v95, s0
	v_add3_u32 v22, s15, v22, v33
	v_and_b32_e32 v2, 0xffff0000, v2
	ds_write_b16 v22, v11 offset:34816
	v_fma_f32 v11, v12, v13, -v19
	v_mul_f32_e32 v12, v2, v2
	v_lshlrev_b32_e32 v13, 16, v3
	v_fmamk_f32 v12, v12, 0xbdd2d3e7, v129
	v_mul_f32_e32 v22, v13, v13
	v_mul_f32_e32 v12, v12, v2
	v_fmamk_f32 v22, v22, 0xbdd2d3e7, v129
	v_mul_f32_e32 v22, v22, v13
	v_exp_f32_e32 v12, v12
	v_exp_f32_e32 v22, v22
	v_mul_f32_e32 v11, v39, v11
	v_add_f32_e32 v12, 1.0, v12
	v_fma_f32 v11, v14, v11, v26
	v_rcp_f32_e32 v12, v12
	v_add_f32_e32 v14, 1.0, v22
	v_rcp_f32_e32 v14, v14
	v_and_b32_e32 v3, 0xffff0000, v3
	v_fma_f32 v2, v12, v2, -v19
	v_mul_f32_e32 v12, v39, v2
	v_fma_f32 v2, v14, v13, -v19
	v_mul_f32_e32 v13, v3, v3
	v_fmamk_f32 v13, v13, 0xbdd2d3e7, v129
	v_mul_f32_e32 v13, v13, v3
	v_or_b32_e32 v81, 18, v34
	v_or_b32_e32 v86, 19, v34
	v_lshlrev_b32_e32 v14, 2, v81
	v_lshlrev_b32_e32 v22, 2, v86
	global_load_dword v26, v14, s[16:17]
	s_nop 0
	global_load_dword v14, v14, s[20:21]
	s_nop 0
	global_load_dword v54, v22, s[16:17]
	global_load_dword v55, v22, s[20:21]
	v_lshlrev_b32_e32 v22, 16, v4
	v_exp_f32_e32 v13, v13
	v_mul_f32_e32 v23, v22, v22
	v_fmamk_f32 v23, v23, 0xbdd2d3e7, v129
	v_mul_f32_e32 v23, v23, v22
	v_add_f32_e32 v13, 1.0, v13
	v_rcp_f32_e32 v13, v13
	v_exp_f32_e32 v23, v23
	v_or_b32_e32 v87, 22, v34
	v_lshlrev_b32_e32 v24, 2, v87
	v_fma_f32 v3, v13, v3, -v19
	v_add_f32_e32 v13, 1.0, v23
	global_load_dword v82, v24, s[16:17]
	global_load_dword v83, v24, s[20:21]
	v_or_b32_e32 v88, 23, v34
	v_rcp_f32_e32 v13, v13
	v_and_b32_e32 v4, 0xffff0000, v4
	v_lshlrev_b32_e32 v24, 2, v88
	v_mul_f32_e32 v23, v4, v4
	global_load_dword v84, v24, s[16:17]
	global_load_dword v85, v24, s[20:21]
	v_fmamk_f32 v23, v23, 0xbdd2d3e7, v129
	v_mul_f32_e32 v23, v23, v4
	v_fma_f32 v13, v13, v22, -v19
	v_lshlrev_b32_e32 v22, 2, v90
	global_load_dword v91, v22, s[16:17]
	global_load_dword v92, v22, s[20:21]
	v_or_b32_e32 v93, 27, v34
	v_exp_f32_e32 v23, v23
	v_lshlrev_b32_e32 v22, 2, v93
	global_load_dword v94, v22, s[16:17]
	global_load_dword v95, v22, s[20:21]
	v_lshlrev_b32_e32 v96, 16, v5
	v_lshlrev_b32_e32 v22, 2, v97
	global_load_dword v98, v22, s[16:17]
	global_load_dword v99, v22, s[20:21]
	v_mul_f32_e32 v22, 0x3d372713, v96
	v_mul_f32_e32 v89, v39, v13
	v_add_f32_e32 v13, 1.0, v23
	v_lshlrev_b32_e32 v23, 2, v100
	v_mul_f32_e32 v22, v22, v96
	global_load_dword v101, v23, s[16:17]
	global_load_dword v102, v23, s[20:21]
	v_fma_f32 v22, v22, v96, v96
	v_mul_f32_e32 v22, 0xbfcc422a, v22
	v_mul_f32_e32 v103, 0x3fb8aa3b, v22
	global_load_dwordx4 v[22:25], v[6:7], off offset:16
	global_load_dwordx4 v[44:47], v[6:7], off
	v_rcp_f32_e32 v13, v13
	v_exp_f32_e32 v103, v103
	v_mul_f32_e32 v5, v104, v104
	v_fmamk_f32 v5, v5, 0xbdd2d3e7, v129
	v_mul_f32_e32 v5, v5, v104
	v_fma_f32 v4, v13, v4, -v19
	v_add_f32_e32 v13, 1.0, v103
	v_rcp_f32_e32 v13, v13
	v_exp_f32_e32 v5, v5
	v_mul_f32_e32 v105, v39, v4
	v_cvt_pk_bf16_f32 v11, v11, s0
	v_fma_f32 v4, v13, v96, -v19
	v_add_f32_e32 v5, 1.0, v5
	v_rcp_f32_e32 v103, v5
	v_fmac_f32_e32 v27, v15, v12
	v_mul_f32_e32 v5, v39, v4
	v_fma_f32 v16, v16, v89, v20
	v_fma_f32 v4, v103, v104, -v19
	v_mul_u32_u24_e32 v19, 0x110, v87
	v_add3_u32 v19, s15, v19, v33
	v_cvt_pk_bf16_f32 v16, v16, s0
	v_fmac_f32_e32 v21, v105, v17
	v_mul_f32_e32 v2, v39, v2
	v_mul_f32_e32 v3, v39, v3
	v_mul_f32_e32 v4, v39, v4
	v_mul_u32_u24_e32 v17, 0x110, v90
	v_add3_u32 v17, s15, v17, v33
	v_readlane_b32 s44, v251, 58
	v_readlane_b32 s45, v251, 59
	v_readlane_b32 s50, v252, 0
	v_readlane_b32 s51, v252, 1
	s_waitcnt vmcnt(16)
	v_fmac_f32_e32 v14, v26, v53
	v_cvt_pk_bf16_f32 v13, v14, s0
	v_mul_u32_u24_e32 v14, 0x110, v81
	v_add3_u32 v14, s15, v14, v33
	ds_write_b16 v14, v13 offset:34816
	s_waitcnt vmcnt(14)
	v_fmac_f32_e32 v55, v54, v52
	v_mul_u32_u24_e32 v14, 0x110, v86
	v_cvt_pk_bf16_f32 v13, v55, s0
	v_add3_u32 v14, s15, v14, v33
	ds_write_b16 v14, v13 offset:34816
	ds_write_b16 v18, v11 offset:49776
	v_cvt_pk_bf16_f32 v11, v27, s0
	ds_write_b16 v18, v11 offset:50048
	global_load_dwordx4 v[12:15], v[6:7], off offset:48
	global_load_dwordx4 v[52:55], v[6:7], off offset:32
	v_readlane_b32 s52, v252, 2
	v_readlane_b32 s53, v252, 3
	v_readlane_b32 s54, v252, 4
	s_waitcnt vmcnt(14)
	v_fmac_f32_e32 v83, v58, v82
	v_cvt_pk_bf16_f32 v11, v83, s0
	ds_write_b16 v19, v11 offset:34816
	v_mul_u32_u24_e32 v19, 0x110, v88
	v_add3_u32 v19, s15, v19, v33
	v_or_b32_e32 v58, 35, v34
	s_waitcnt vmcnt(12)
	v_fmac_f32_e32 v85, v56, v84
	v_cvt_pk_bf16_f32 v11, v85, s0
	v_or_b32_e32 v56, 34, v34
	ds_write_b16 v19, v11 offset:34816
	v_lshlrev_b32_e32 v11, 2, v56
	v_lshlrev_b32_e32 v19, 2, v58
	global_load_dword v39, v11, s[16:17]
	s_nop 0
	global_load_dword v11, v11, s[20:21]
	s_nop 0
	global_load_dword v89, v19, s[16:17]
	global_load_dword v96, v19, s[20:21]
	ds_write_b16 v18, v16 offset:50864
	v_cvt_pk_bf16_f32 v16, v21, s0
	s_waitcnt vmcnt(14)
	v_fmac_f32_e32 v92, v91, v64
	ds_write_b16 v18, v16 offset:51136
	v_cvt_pk_bf16_f32 v16, v92, s0
	ds_write_b16 v17, v16 offset:34816
	s_waitcnt vmcnt(12)
	v_fmac_f32_e32 v95, v94, v63
	v_mul_u32_u24_e32 v17, 0x110, v93
	v_cvt_pk_bf16_f32 v16, v95, s0
	v_add3_u32 v17, s15, v17, v33
	ds_write_b16 v17, v16 offset:34816
	s_waitcnt vmcnt(10)
	v_fmac_f32_e32 v99, v69, v98
	v_mul_u32_u24_e32 v17, 0x110, v97
	v_cvt_pk_bf16_f32 v16, v99, s0
	v_add3_u32 v17, s15, v17, v33
	ds_write_b16 v17, v16 offset:34816
	s_waitcnt vmcnt(8)
	v_fmac_f32_e32 v102, v68, v101
	v_mul_u32_u24_e32 v17, 0x110, v100
	v_cvt_pk_bf16_f32 v16, v102, s0
	v_add3_u32 v17, s15, v17, v33
	ds_write_b16 v17, v16 offset:34816
	s_waitcnt vmcnt(6)
	v_cndmask_b32_e32 v16, 0, v45, vcc
	v_cmp_le_u32_e32 vcc, v34, v31
	v_or_b32_e32 v63, 38, v34
	v_or_b32_e32 v69, 39, v34
	v_cndmask_b32_e32 v17, 0, v44, vcc
	v_cvt_pk_bf16_f32 v16, v17, v16
	v_lshlrev_b32_e32 v17, 2, v63
	global_load_dword v64, v17, s[16:17]
	global_load_dword v68, v17, s[20:21]
	v_lshlrev_b32_e32 v18, 2, v69
	global_load_dword v91, v18, s[16:17]
	global_load_dword v92, v18, s[20:21]
	v_cvt_pk_bf16_f32 v17, v46, v47
	v_cmp_le_u32_e32 vcc, v76, v31
	global_load_dwordx4 v[44:47], v[6:7], off offset:80
	global_load_dwordx4 v[82:85], v[6:7], off offset:64
	v_cndmask_b32_e32 v18, 0, v17, vcc
	v_lshrrev_b32_e32 v17, 16, v17
	v_cmp_le_u32_e32 vcc, v77, v31
	v_or_b32_e32 v76, 47, v34
	v_readlane_b32 s55, v252, 5
	v_cndmask_b32_e32 v17, 0, v17, vcc
	v_cmp_gt_u32_e32 vcc, v31, v35
	v_perm_b32 v17, v17, v18, s19
	s_waitcnt vmcnt(8)
	v_fmac_f32_e32 v11, v39, v73
	v_cndmask_b32_e32 v18, 0, v23, vcc
	v_cmp_le_u32_e32 vcc, v35, v31
	v_cvt_pk_bf16_f32 v11, v11, s0
	v_or_b32_e32 v35, 42, v34
	v_cndmask_b32_e32 v19, 0, v22, vcc
	v_cvt_pk_bf16_f32 v18, v19, v18
	v_cvt_pk_bf16_f32 v19, v24, v25
	v_cmp_le_u32_e32 vcc, v65, v31
	s_waitcnt vmcnt(6)
	v_fmac_f32_e32 v96, v89, v72
	s_waitcnt vmcnt(4)
	v_fmac_f32_e32 v68, v71, v64
	v_cndmask_b32_e32 v20, 0, v19, vcc
	v_lshrrev_b32_e32 v19, 16, v19
	v_cmp_le_u32_e32 vcc, v78, v31
	s_waitcnt vmcnt(2)
	v_fmac_f32_e32 v92, v70, v91
	v_cndmask_b32_e32 v19, 0, v19, vcc
	v_perm_b32 v19, v19, v20, s19
	ds_write_b128 v0, v[16:19]
	global_load_dwordx4 v[20:23], v[6:7], off offset:112
	global_load_dwordx4 v[24:27], v[6:7], off offset:96
	v_cmp_gt_u32_e32 vcc, v31, v36
	s_nop 1
	v_cndmask_b32_e32 v16, 0, v53, vcc
	v_cmp_le_u32_e32 vcc, v36, v31
	s_nop 1
	v_cndmask_b32_e32 v17, 0, v52, vcc
	v_cvt_pk_bf16_f32 v16, v17, v16
	v_cvt_pk_bf16_f32 v17, v54, v55
	v_cmp_le_u32_e32 vcc, v80, v31
	v_or_b32_e32 v54, 43, v34
	v_lshlrev_b32_e32 v19, 2, v54
	v_cndmask_b32_e32 v18, 0, v17, vcc
	v_lshrrev_b32_e32 v17, 16, v17
	v_cmp_le_u32_e32 vcc, v79, v31
	s_nop 1
	v_cndmask_b32_e32 v17, 0, v17, vcc
	v_perm_b32 v17, v17, v18, s19
	v_mul_u32_u24_e32 v18, 0x110, v56
	v_add3_u32 v18, s15, v18, v33
	ds_write_b16 v18, v11 offset:34816
	v_lshlrev_b32_e32 v18, 2, v35
	global_load_dword v52, v18, s[16:17]
	global_load_dword v53, v18, s[20:21]
	v_mul_u32_u24_e32 v18, 0x110, v58
	v_cvt_pk_bf16_f32 v11, v96, s0
	v_add3_u32 v18, s15, v18, v33
	v_cmp_gt_u32_e32 vcc, v31, v37
	global_load_dword v55, v19, s[16:17]
	global_load_dword v65, v19, s[20:21]
	ds_write_b16 v18, v11 offset:34816
	v_cndmask_b32_e32 v11, 0, v13, vcc
	v_cmp_le_u32_e32 vcc, v37, v31
	s_waitcnt vmcnt(2)
	v_fmac_f32_e32 v53, v52, v67
	v_cndmask_b32_e32 v12, 0, v12, vcc
	v_cvt_pk_bf16_f32 v18, v12, v11
	v_cvt_pk_bf16_f32 v11, v14, v15
	v_cmp_le_u32_e32 vcc, v59, v31
	v_or_b32_e32 v59, 46, v34
	s_waitcnt vmcnt(0)
	v_fmac_f32_e32 v65, v55, v66
	v_cndmask_b32_e32 v12, 0, v11, vcc
	v_lshrrev_b32_e32 v11, 16, v11
	v_cmp_le_u32_e32 vcc, v10, v31
	v_or_b32_e32 v52, 54, v34
	s_nop 0
	v_cndmask_b32_e32 v10, 0, v11, vcc
	v_perm_b32 v19, v10, v12, s19
	v_lshlrev_b32_e32 v10, 2, v59
	global_load_dword v72, v10, s[16:17]
	global_load_dword v73, v10, s[20:21]
	ds_write_b128 v0, v[16:19] offset:16
	v_lshlrev_b32_e32 v10, 2, v76
	v_mul_u32_u24_e32 v11, 0x110, v63
	global_load_dword v77, v10, s[16:17]
	global_load_dword v78, v10, s[20:21]
	v_cvt_pk_bf16_f32 v10, v68, s0
	v_add3_u32 v11, s15, v11, v33
	ds_write_b16 v11, v10 offset:34816
	global_load_dwordx4 v[10:13], v[6:7], off offset:144
	global_load_dwordx4 v[14:17], v[6:7], off offset:128
	v_mul_u32_u24_e32 v19, 0x110, v69
	v_cvt_pk_bf16_f32 v18, v92, s0
	v_add3_u32 v19, s15, v19, v33
	v_cmp_gt_u32_e32 vcc, v31, v38
	ds_write_b16 v19, v18 offset:34816
	s_waitcnt vmcnt(4)
	v_fmac_f32_e32 v73, v75, v72
	v_cndmask_b32_e32 v18, 0, v83, vcc
	v_cmp_le_u32_e32 vcc, v38, v31
	s_waitcnt vmcnt(2)
	v_fmac_f32_e32 v78, v74, v77
	v_cndmask_b32_e32 v19, 0, v82, vcc
	v_cvt_pk_bf16_f32 v36, v19, v18
	v_cvt_pk_bf16_f32 v18, v84, v85
	v_cmp_le_u32_e32 vcc, v81, v31
	s_nop 1
	v_cndmask_b32_e32 v19, 0, v18, vcc
	v_lshrrev_b32_e32 v18, 16, v18
	v_cmp_le_u32_e32 vcc, v86, v31
	s_nop 1
	v_cndmask_b32_e32 v18, 0, v18, vcc
	v_cmp_gt_u32_e32 vcc, v31, v40
	v_perm_b32 v37, v18, v19, s19
	s_nop 0
	v_cndmask_b32_e32 v18, 0, v45, vcc
	v_cmp_le_u32_e32 vcc, v40, v31
	s_nop 1
	v_cndmask_b32_e32 v19, 0, v44, vcc
	v_cvt_pk_bf16_f32 v38, v19, v18
	v_cvt_pk_bf16_f32 v18, v46, v47
	v_cmp_le_u32_e32 vcc, v87, v31
	s_nop 1
	v_cndmask_b32_e32 v19, 0, v18, vcc
	v_lshrrev_b32_e32 v18, 16, v18
	v_cmp_le_u32_e32 vcc, v88, v31
	s_nop 1
	v_cndmask_b32_e32 v18, 0, v18, vcc
	v_cmp_gt_u32_e32 vcc, v31, v41
	v_perm_b32 v39, v18, v19, s19
	ds_write_b128 v0, v[36:39] offset:32
	v_cndmask_b32_e32 v18, 0, v25, vcc
	v_cmp_le_u32_e32 vcc, v41, v31
	v_mul_u32_u24_e32 v41, 0x110, v35
	v_add3_u32 v41, s15, v41, v33
	v_cndmask_b32_e32 v19, 0, v24, vcc
	v_cvt_pk_bf16_f32 v18, v19, v18
	v_cvt_pk_bf16_f32 v19, v26, v27
	global_load_dwordx4 v[24:27], v[6:7], off offset:176
	global_load_dwordx4 v[36:39], v[6:7], off offset:160
	v_cmp_le_u32_e32 vcc, v90, v31
	s_nop 1
	v_cndmask_b32_e32 v40, 0, v19, vcc
	v_lshrrev_b32_e32 v19, 16, v19
	v_cmp_le_u32_e32 vcc, v93, v31
	s_nop 1
	v_cndmask_b32_e32 v19, 0, v19, vcc
	v_cmp_gt_u32_e32 vcc, v31, v42
	v_perm_b32 v19, v19, v40, s19
	v_cvt_pk_bf16_f32 v40, v53, s0
	v_cndmask_b32_e32 v21, 0, v21, vcc
	v_cmp_le_u32_e32 vcc, v42, v31
	ds_write_b16 v41, v40 offset:34816
	v_mul_u32_u24_e32 v41, 0x110, v54
	v_cndmask_b32_e32 v20, 0, v20, vcc
	v_cvt_pk_bf16_f32 v20, v20, v21
	v_cvt_pk_bf16_f32 v21, v22, v23
	v_cmp_le_u32_e32 vcc, v97, v31
	v_cvt_pk_bf16_f32 v40, v65, s0
	v_add3_u32 v41, s15, v41, v33
	v_cndmask_b32_e32 v22, 0, v21, vcc
	v_lshrrev_b32_e32 v21, 16, v21
	v_cmp_le_u32_e32 vcc, v100, v31
	ds_write_b16 v41, v40 offset:34816
	v_mul_u32_u24_e32 v23, 0x110, v76
	v_cndmask_b32_e32 v21, 0, v21, vcc
	v_perm_b32 v21, v21, v22, s19
	ds_write_b128 v0, v[18:21] offset:48
	v_mul_u32_u24_e32 v19, 0x110, v59
	v_cvt_pk_bf16_f32 v18, v73, s0
	v_add3_u32 v19, s15, v19, v33
	v_cmp_gt_u32_e32 vcc, v31, v43
	ds_write_b16 v19, v18 offset:34816
	v_cvt_pk_bf16_f32 v22, v78, s0
	v_add3_u32 v23, s15, v23, v33
	s_waitcnt vmcnt(2)
	v_cndmask_b32_e32 v15, 0, v15, vcc
	v_cmp_le_u32_e32 vcc, v43, v31
	global_load_dwordx4 v[18:21], v[6:7], off offset:208
	global_load_dwordx4 v[44:47], v[6:7], off offset:192
	ds_write_b16 v23, v22 offset:34816
	v_cndmask_b32_e32 v14, 0, v14, vcc
	v_or_b32_e32 v23, 50, v34
	v_cvt_pk_bf16_f32 v14, v14, v15
	v_cvt_pk_bf16_f32 v15, v16, v17
	v_or_b32_e32 v22, 51, v34
	v_lshlrev_b32_e32 v17, 2, v23
	v_cmp_le_u32_e32 vcc, v56, v31
	global_load_dword v40, v17, s[16:17]
	global_load_dword v41, v17, s[20:21]
	v_lshlrev_b32_e32 v17, 2, v22
	v_cndmask_b32_e32 v16, 0, v15, vcc
	v_lshrrev_b32_e32 v15, 16, v15
	global_load_dword v42, v17, s[16:17]
	global_load_dword v43, v17, s[20:21]
	v_cmp_le_u32_e32 vcc, v58, v31
	s_waitcnt vmcnt(2)
	v_fmac_f32_e32 v41, v40, v62
	v_cndmask_b32_e32 v15, 0, v15, vcc
	v_cmp_gt_u32_e32 vcc, v31, v48
	v_perm_b32 v15, v15, v16, s19
	s_waitcnt vmcnt(0)
	v_fmac_f32_e32 v43, v42, v61
	v_cndmask_b32_e32 v11, 0, v11, vcc
	v_cmp_le_u32_e32 vcc, v48, v31
	v_or_b32_e32 v48, 55, v34
	s_nop 0
	v_cndmask_b32_e32 v10, 0, v10, vcc
	v_cvt_pk_bf16_f32 v16, v10, v11
	v_cvt_pk_bf16_f32 v10, v12, v13
	v_cmp_le_u32_e32 vcc, v63, v31
	s_nop 1
	v_cndmask_b32_e32 v11, 0, v10, vcc
	v_lshrrev_b32_e32 v10, 16, v10
	v_cmp_le_u32_e32 vcc, v69, v31
	s_nop 1
	v_cndmask_b32_e32 v10, 0, v10, vcc
	v_perm_b32 v17, v10, v11, s19
	v_lshlrev_b32_e32 v10, 2, v52
	global_load_dword v53, v10, s[16:17]
	global_load_dword v55, v10, s[20:21]
	v_lshlrev_b32_e32 v10, 2, v48
	global_load_dword v56, v10, s[16:17]
	global_load_dword v58, v10, s[20:21]
	v_cmp_gt_u32_e32 vcc, v31, v49
	ds_write_b128 v0, v[14:17] offset:64
	s_waitcnt vmcnt(2)
	v_fmac_f32_e32 v55, v9, v53
	v_cndmask_b32_e32 v10, 0, v37, vcc
	v_cmp_le_u32_e32 vcc, v49, v31
	v_or_b32_e32 v49, 58, v34
	v_cvt_pk_bf16_f32 v9, v55, s0
	v_cndmask_b32_e32 v11, 0, v36, vcc
	v_cvt_pk_bf16_f32 v10, v11, v10
	v_cvt_pk_bf16_f32 v11, v38, v39
	v_cmp_le_u32_e32 vcc, v35, v31
	global_load_dwordx4 v[14:17], v[6:7], off offset:240
	global_load_dwordx4 v[36:39], v[6:7], off offset:224
	v_cndmask_b32_e32 v12, 0, v11, vcc
	v_lshrrev_b32_e32 v11, 16, v11
	v_cmp_le_u32_e32 vcc, v54, v31
	v_or_b32_e32 v35, 59, v34
	s_waitcnt vmcnt(2)
	v_fmac_f32_e32 v58, v8, v56
	v_cndmask_b32_e32 v6, 0, v11, vcc
	v_perm_b32 v11, v6, v12, s19
	v_lshlrev_b32_e32 v6, 2, v49
	global_load_dword v54, v6, s[16:17]
	global_load_dword v63, v6, s[20:21]
	v_lshlrev_b32_e32 v6, 2, v35
	v_cmp_gt_u32_e32 vcc, v31, v51
	global_load_dword v64, v6, s[16:17]
	global_load_dword v65, v6, s[20:21]
	v_cndmask_b32_e32 v6, 0, v25, vcc
	v_cmp_le_u32_e32 vcc, v51, v31
	s_waitcnt vmcnt(2)
	v_fmac_f32_e32 v63, v54, v2
	v_cndmask_b32_e32 v7, 0, v24, vcc
	v_cvt_pk_bf16_f32 v12, v7, v6
	v_cvt_pk_bf16_f32 v6, v26, v27
	v_cmp_le_u32_e32 vcc, v59, v31
	v_mul_u32_u24_e32 v26, 0x110, v22
	v_cvt_pk_bf16_f32 v27, v41, s0
	v_cndmask_b32_e32 v7, 0, v6, vcc
	v_lshrrev_b32_e32 v6, 16, v6
	v_cmp_le_u32_e32 vcc, v76, v31
	v_add3_u32 v26, s15, v26, v33
	v_cvt_pk_bf16_f32 v2, v63, s0
	v_cndmask_b32_e32 v6, 0, v6, vcc
	v_perm_b32 v13, v6, v7, s19
	ds_write_b128 v0, v[10:13] offset:80
	v_or_b32_e32 v11, 62, v34
	v_or_b32_e32 v10, 63, v34
	v_lshlrev_b32_e32 v7, 2, v11
	global_load_dword v12, v7, s[16:17]
	global_load_dword v13, v7, s[20:21]
	v_lshlrev_b32_e32 v7, 2, v10
	global_load_dword v24, v7, s[16:17]
	global_load_dword v25, v7, s[20:21]
	v_cmp_gt_u32_e32 vcc, v31, v57
	s_waitcnt vmcnt(4)
	v_fmac_f32_e32 v65, v64, v3
	v_and_or_b32 v76, v30, 64, v32
	v_cndmask_b32_e32 v6, 0, v45, vcc
	v_cmp_le_u32_e32 vcc, v57, v31
	s_waitcnt vmcnt(2)
	v_fmac_f32_e32 v13, v5, v12
	v_cndmask_b32_e32 v7, 0, v44, vcc
	v_cvt_pk_bf16_f32 v6, v7, v6
	v_mul_u32_u24_e32 v7, 0x110, v23
	v_add3_u32 v7, s15, v7, v33
	ds_write_b16 v7, v27 offset:34816
	v_cvt_pk_bf16_f32 v7, v43, s0
	ds_write_b16 v26, v7 offset:34816
	v_cvt_pk_bf16_f32 v7, v46, v47
	v_cmp_le_u32_e32 vcc, v23, v31
	v_cvt_pk_bf16_f32 v5, v13, s0
	s_waitcnt vmcnt(0)
	v_fmac_f32_e32 v25, v4, v24
	v_cndmask_b32_e32 v23, 0, v7, vcc
	v_lshrrev_b32_e32 v7, 16, v7
	v_cmp_le_u32_e32 vcc, v22, v31
	s_nop 1
	v_cndmask_b32_e32 v7, 0, v7, vcc
	v_perm_b32 v7, v7, v23, s19
	v_cmp_gt_u32_e32 vcc, v31, v60
	ds_write_b64 v0, v[6:7] offset:96
	s_nop 0
	v_cndmask_b32_e32 v6, 0, v19, vcc
	v_cmp_le_u32_e32 vcc, v60, v31
	s_nop 1
	v_cndmask_b32_e32 v7, 0, v18, vcc
	v_cvt_pk_bf16_f32 v6, v7, v6
	v_mul_u32_u24_e32 v7, 0x110, v52
	v_add3_u32 v7, s15, v7, v33
	v_mul_u32_u24_e32 v18, 0x110, v48
	v_add3_u32 v18, s15, v18, v33
	ds_write_b16 v7, v9 offset:34816
	v_cvt_pk_bf16_f32 v7, v58, s0
	ds_write_b16 v18, v7 offset:34816
	v_cvt_pk_bf16_f32 v7, v20, v21
	v_cmp_le_u32_e32 vcc, v52, v31
	s_nop 1
	v_cndmask_b32_e32 v8, 0, v7, vcc
	v_lshrrev_b32_e32 v7, 16, v7
	v_cmp_le_u32_e32 vcc, v48, v31
	s_nop 1
	v_cndmask_b32_e32 v7, 0, v7, vcc
	v_perm_b32 v7, v7, v8, s19
	v_cmp_gt_u32_e32 vcc, v31, v29
	ds_write_b64 v0, v[6:7] offset:104
	v_mul_u32_u24_e32 v8, 0x110, v35
	v_cndmask_b32_e32 v6, 0, v37, vcc
	v_cmp_le_u32_e32 vcc, v29, v31
	v_add3_u32 v8, s15, v8, v33
	s_nop 0
	v_cndmask_b32_e32 v7, 0, v36, vcc
	v_cvt_pk_bf16_f32 v6, v7, v6
	v_mul_u32_u24_e32 v7, 0x110, v49
	v_add3_u32 v7, s15, v7, v33
	ds_write_b16 v7, v2 offset:34816
	v_cvt_pk_bf16_f32 v2, v65, s0
	ds_write_b16 v8, v2 offset:34816
	v_cvt_pk_bf16_f32 v2, v38, v39
	v_cmp_le_u32_e32 vcc, v49, v31
	s_nop 1
	v_cndmask_b32_e32 v3, 0, v2, vcc
	v_lshrrev_b32_e32 v2, 16, v2
	v_cmp_le_u32_e32 vcc, v35, v31
	s_nop 1
	v_cndmask_b32_e32 v2, 0, v2, vcc
	v_cmp_gt_u32_e32 vcc, v31, v28
	v_perm_b32 v7, v2, v3, s19
	ds_write_b64 v0, v[6:7] offset:112
	v_cndmask_b32_e32 v2, 0, v15, vcc
	v_cmp_le_u32_e32 vcc, v28, v31
	v_mul_u32_u24_e32 v6, 0x110, v10
	v_add3_u32 v6, s15, v6, v33
	v_cndmask_b32_e32 v3, 0, v14, vcc
	v_cvt_pk_bf16_f32 v2, v3, v2
	v_mul_u32_u24_e32 v3, 0x110, v11
	v_add3_u32 v3, s15, v3, v33
	ds_write_b16 v3, v5 offset:34816
	v_cvt_pk_bf16_f32 v3, v25, s0
	ds_write_b16 v6, v3 offset:34816
	v_cvt_pk_bf16_f32 v3, v16, v17
	v_cmp_le_u32_e32 vcc, v11, v31
	v_mul_u32_u24_e32 v7, 0x88, v76
	s_mov_b64 s[0:1], 0x1f000
	v_cndmask_b32_e32 v4, 0, v3, vcc
	v_lshrrev_b32_e32 v3, 16, v3
	v_cmp_le_u32_e32 vcc, v10, v31
	s_nop 1
	v_cndmask_b32_e32 v3, 0, v3, vcc
	v_perm_b32 v3, v3, v4, s19
	ds_write_b64 v0, v[2:3] offset:120
	v_bfe_u32 v0, v50, 4, 2
	v_and_b32_e32 v2, 0x4f, v50
	v_lshl_add_u32 v6, v0, 4, s15
	v_mul_u32_u24_e32 v2, 0x88, v2
	v_lshl_add_u32 v51, v2, 1, v6
	s_waitcnt lgkmcnt(0)
	s_barrier
	ds_read_b128 v[2:5], v51 offset:34816
	ds_read_b128 v[72:75], v51 offset:34880
	ds_read_b128 v[14:17], v51 offset:39168
	ds_read_b128 v[78:81], v51 offset:39232
	ds_read_b128 v[22:25], v51 offset:43520
	ds_read_b128 v[82:85], v51 offset:43584
	ds_read_b128 v[30:33], v51 offset:47872
	ds_read_b128 v[86:89], v51 offset:47936
	v_lshl_add_u32 v77, v7, 1, v6
	ds_read_b128 v[6:9], v77
	ds_read_b128 v[34:37], v77 offset:4352
	ds_read_b128 v[52:55], v77 offset:8704
	ds_read_b128 v[68:71], v77 offset:13056
	s_waitcnt lgkmcnt(3)
	v_mfma_f32_16x16x32_bf16 v[10:13], v[2:5], v[6:9], 0
	ds_read_b128 v[98:101], v51 offset:48000
	v_mfma_f32_16x16x32_bf16 v[18:21], v[14:17], v[6:9], 0
	v_mfma_f32_16x16x32_bf16 v[26:29], v[22:25], v[6:9], 0
	v_mfma_f32_16x16x32_bf16 v[6:9], v[30:33], v[6:9], 0
	s_waitcnt lgkmcnt(3)
	v_mfma_f32_16x16x32_bf16 v[38:41], v[2:5], v[34:37], 0
	v_mfma_f32_16x16x32_bf16 v[42:45], v[14:17], v[34:37], 0
	v_mfma_f32_16x16x32_bf16 v[46:49], v[22:25], v[34:37], 0
	v_mfma_f32_16x16x32_bf16 v[34:37], v[30:33], v[34:37], 0
	s_waitcnt lgkmcnt(2)
	v_mfma_f32_16x16x32_bf16 v[56:59], v[2:5], v[52:55], 0
	v_mfma_f32_16x16x32_bf16 v[60:63], v[14:17], v[52:55], 0
	v_mfma_f32_16x16x32_bf16 v[64:67], v[22:25], v[52:55], 0
	v_mfma_f32_16x16x32_bf16 v[52:55], v[30:33], v[52:55], 0
	s_waitcnt lgkmcnt(1)
	v_mfma_f32_16x16x32_bf16 v[2:5], v[2:5], v[68:71], 0
	v_mfma_f32_16x16x32_bf16 v[14:17], v[14:17], v[68:71], 0
	v_mfma_f32_16x16x32_bf16 v[22:25], v[22:25], v[68:71], 0
	v_mfma_f32_16x16x32_bf16 v[30:33], v[30:33], v[68:71], 0
	ds_read_b128 v[68:71], v77 offset:64
	s_waitcnt lgkmcnt(0)
	v_mfma_f32_16x16x32_bf16 v[10:13], v[72:75], v[68:71], v[10:13]
	v_mfma_f32_16x16x32_bf16 v[18:21], v[78:81], v[68:71], v[18:21]
	v_mfma_f32_16x16x32_bf16 v[26:29], v[82:85], v[68:71], v[26:29]
	v_mfma_f32_16x16x32_bf16 v[6:9], v[86:89], v[68:71], v[6:9]
	ds_read_b128 v[68:71], v77 offset:4416
	s_waitcnt lgkmcnt(0)
	v_mfma_f32_16x16x32_bf16 v[38:41], v[72:75], v[68:71], v[38:41]
	v_mfma_f32_16x16x32_bf16 v[42:45], v[78:81], v[68:71], v[42:45]
	v_mfma_f32_16x16x32_bf16 v[46:49], v[82:85], v[68:71], v[46:49]
	v_mfma_f32_16x16x32_bf16 v[34:37], v[86:89], v[68:71], v[34:37]
	ds_read_b128 v[68:71], v77 offset:8768
	s_waitcnt lgkmcnt(0)
	v_mfma_f32_16x16x32_bf16 v[90:93], v[78:81], v[68:71], v[60:63]
	s_nop 2
	ds_read_b128 v[60:63], v77 offset:13120
	v_mfma_f32_16x16x32_bf16 v[56:59], v[72:75], v[68:71], v[56:59]
	v_mfma_f32_16x16x32_bf16 v[94:97], v[82:85], v[68:71], v[64:67]
	v_mfma_f32_16x16x32_bf16 v[52:55], v[86:89], v[68:71], v[52:55]
	s_nop 1
	ds_read_b128 v[66:69], v51 offset:34944
	s_waitcnt lgkmcnt(1)
	v_mfma_f32_16x16x32_bf16 v[2:5], v[72:75], v[60:63], v[2:5]
	v_mfma_f32_16x16x32_bf16 v[70:73], v[86:89], v[60:63], v[30:33]
	s_nop 2
	ds_read_b128 v[30:33], v77 offset:128
	v_mfma_f32_16x16x32_bf16 v[14:17], v[78:81], v[60:63], v[14:17]
	s_waitcnt lgkmcnt(0)
	v_mfma_f32_16x16x32_bf16 v[78:81], v[66:69], v[30:33], v[10:13]
	s_nop 2
	ds_read_b128 v[10:13], v51 offset:39296
	v_mfma_f32_16x16x32_bf16 v[22:25], v[82:85], v[60:63], v[22:25]
	v_mfma_f32_16x16x32_bf16 v[102:105], v[98:101], v[30:33], v[6:9]
	s_nop 2
	ds_read_b128 v[6:9], v77 offset:4480
	s_waitcnt lgkmcnt(1)
	v_mfma_f32_16x16x32_bf16 v[82:85], v[10:13], v[30:33], v[18:21]
	s_nop 2
	ds_read_b128 v[18:21], v51 offset:43648
	s_waitcnt lgkmcnt(1)
	v_mfma_f32_16x16x32_bf16 v[106:109], v[66:69], v[6:9], v[38:41]
	v_mfma_f32_16x16x32_bf16 v[110:113], v[10:13], v[6:9], v[42:45]
	s_waitcnt lgkmcnt(0)
	v_mfma_f32_16x16x32_bf16 v[114:117], v[18:21], v[6:9], v[46:49]
	v_mfma_f32_16x16x32_bf16 v[62:65], v[98:101], v[6:9], v[34:37]
	ds_read_b128 v[6:9], v77 offset:8832
	s_waitcnt lgkmcnt(0)
	v_mfma_f32_16x16x32_bf16 v[42:45], v[98:101], v[6:9], v[52:55]
	s_nop 2
	ds_read_b128 v[52:55], v77 offset:13184
	v_mfma_f32_16x16x32_bf16 v[86:89], v[18:21], v[30:33], v[26:29]
	ds_read_b128 v[30:33], v51 offset:35008
	s_waitcnt lgkmcnt(1)
	v_mfma_f32_16x16x32_bf16 v[26:29], v[66:69], v[52:55], v[2:5]
	v_mfma_f32_16x16x32_bf16 v[2:5], v[18:21], v[52:55], v[22:25]
	s_nop 2
	v_and_b32_e32 v22, 64, v50
	v_mfma_f32_16x16x32_bf16 v[38:41], v[66:69], v[6:9], v[56:59]
	v_lshlrev_b32_e32 v66, 3, v0
	v_lshlrev_b32_e32 v0, 1, v22
	v_or_b32_e32 v24, s4, v76
	v_lshl_add_u64 v[22:23], s[6:7], 0, v[0:1]
	v_mov_b32_e32 v67, v1
	v_mfma_f32_16x16x32_bf16 v[34:37], v[10:13], v[6:9], v[90:93]
	v_lshl_add_u64 v[22:23], v[22:23], 0, v[66:67]
	v_lshlrev_b32_e32 v76, 2, v76
	s_mov_b32 s4, 0x3e000
	v_mfma_f32_16x16x32_bf16 v[46:49], v[18:21], v[6:9], v[94:97]
	v_mfma_f32_16x16x32_bf16 v[6:9], v[10:13], v[52:55], v[14:17]
	v_mfma_f32_16x16x32_bf16 v[10:13], v[98:101], v[52:55], v[70:73]
	ds_read_b128 v[52:55], v77 offset:192
	s_nop 0
	ds_read_b128 v[14:17], v51 offset:39360
	ds_read_b128 v[18:21], v51 offset:43712
	v_mul_u32_u24_e32 v72, 0x1f00, v24
	v_mov_b32_e32 v73, v1
	v_lshl_add_u64 v[68:69], v[22:23], 0, v[72:73]
	global_load_dwordx2 v[98:99], v[68:69], off
	global_load_dwordx2 v[100:101], v[68:69], off offset:32
	ds_read_b128 v[94:97], v77 offset:4544
	s_waitcnt lgkmcnt(0)
	v_mfma_f32_16x16x32_bf16 v[58:61], v[30:33], v[94:97], v[106:109]
	s_nop 2
	global_load_dword v106, v76, s[12:13]
	ds_read_b128 v[22:25], v51 offset:48064
	v_lshl_add_u64 v[72:73], s[46:47], 0, v[72:73]
	s_waitcnt lgkmcnt(0)
	v_mfma_f32_16x16x32_bf16 v[90:93], v[22:25], v[52:55], v[102:105]
	s_nop 2
	global_load_dwordx2 v[102:103], v[68:69], off offset:64
	global_load_dwordx2 v[104:105], v[68:69], off offset:96
	v_lshl_add_u64 v[72:73], v[72:73], 0, s[8:9]
	v_lshl_add_u64 v[72:73], v[72:73], 0, v[0:1]
	v_mfma_f32_16x16x32_bf16 v[78:81], v[30:33], v[52:55], v[78:81]
	v_lshl_add_u64 v[66:67], v[72:73], 0, v[66:67]
	v_add_co_u32_e32 v70, vcc, s2, v68
	v_mfma_f32_16x16x32_bf16 v[82:85], v[14:17], v[52:55], v[82:85]
	s_nop 0
	v_addc_co_u32_e32 v71, vcc, 0, v69, vcc
	s_waitcnt vmcnt(4)
	v_lshlrev_b32_e32 v107, 16, v98
	v_and_b32_e32 v98, 0xffff0000, v98
	v_mul_f32_e32 v75, v98, v98
	v_mul_f32_e32 v74, v107, v107
	v_fmamk_f32 v75, v75, 0xbdd2d3e7, v129
	v_fmamk_f32 v74, v74, 0xbdd2d3e7, v129
	v_mul_f32_e32 v75, v75, v98
	v_mul_f32_e32 v74, v74, v107
	v_exp_f32_e32 v108, v75
	v_exp_f32_e32 v74, v74
	s_waitcnt vmcnt(2)
	v_add_f32_e32 v79, v79, v106
	v_add_f32_e32 v78, v78, v106
	v_add_f32_e32 v108, 1.0, v108
	v_add_f32_e32 v74, 1.0, v74
	v_rcp_f32_e32 v108, v108
	v_rcp_f32_e32 v109, v74
	v_add_f32_e32 v80, v80, v106
	v_add_f32_e32 v81, v81, v106
	v_mul_f32_e32 v98, v108, v98
	v_mul_f32_e32 v107, v109, v107
	v_mul_f32_e32 v79, v98, v79
	v_lshlrev_b32_e32 v98, 16, v99
	v_and_b32_e32 v99, 0xffff0000, v99
	v_mul_f32_e32 v78, v107, v78
	v_mul_f32_e32 v107, v98, v98
	v_mul_f32_e32 v108, v99, v99
	v_fmamk_f32 v107, v107, 0xbdd2d3e7, v129
	v_fmamk_f32 v108, v108, 0xbdd2d3e7, v129
	v_mul_f32_e32 v107, v107, v98
	v_mul_f32_e32 v108, v108, v99
	v_exp_f32_e32 v107, v107
	v_exp_f32_e32 v108, v108
	v_cvt_pk_bf16_f32 v78, v78, v79
	v_lshlrev_b32_e32 v0, 16, v100
	v_add_f32_e32 v107, 1.0, v107
	v_add_f32_e32 v79, 1.0, v108
	v_rcp_f32_e32 v107, v107
	v_rcp_f32_e32 v79, v79
	v_mul_f32_e32 v72, v0, v0
	v_and_b32_e32 v73, 0xffff0000, v100
	v_mul_f32_e32 v98, v107, v98
	v_mul_f32_e32 v79, v79, v99
	v_mul_f32_e32 v80, v98, v80
	v_mul_f32_e32 v79, v79, v81
	v_cvt_pk_bf16_f32 v79, v80, v79
	v_fmamk_f32 v72, v72, 0xbdd2d3e7, v129
	v_mul_f32_e32 v80, v73, v73
	v_mul_f32_e32 v72, v72, v0
	v_fmamk_f32 v80, v80, 0xbdd2d3e7, v129
	v_mul_f32_e32 v80, v80, v73
	v_exp_f32_e32 v72, v72
	v_exp_f32_e32 v80, v80
	global_store_dwordx2 v[66:67], v[78:79], off
	v_add_f32_e32 v72, 1.0, v72
	v_rcp_f32_e32 v72, v72
	v_add_f32_e32 v78, 1.0, v80
	v_rcp_f32_e32 v78, v78
	v_and_b32_e32 v79, 0xffff0000, v101
	v_mul_f32_e32 v0, v72, v0
	v_add_f32_e32 v72, v82, v106
	v_mul_f32_e32 v0, v0, v72
	v_mul_f32_e32 v72, v78, v73
	v_add_f32_e32 v73, v83, v106
	v_mul_f32_e32 v72, v72, v73
	v_lshlrev_b32_e32 v73, 16, v101
	v_mul_f32_e32 v78, v73, v73
	v_fmamk_f32 v78, v78, 0xbdd2d3e7, v129
	v_mul_f32_e32 v80, v79, v79
	v_mul_f32_e32 v78, v78, v73
	v_fmamk_f32 v80, v80, 0xbdd2d3e7, v129
	v_mul_f32_e32 v80, v80, v79
	v_exp_f32_e32 v78, v78
	v_exp_f32_e32 v80, v80
	v_cvt_pk_bf16_f32 v72, v0, v72
	v_add_f32_e32 v78, 1.0, v78
	v_rcp_f32_e32 v78, v78
	v_add_f32_e32 v0, 1.0, v80
	v_rcp_f32_e32 v0, v0
	v_mfma_f32_16x16x32_bf16 v[86:89], v[18:21], v[52:55], v[86:89]
	v_mul_f32_e32 v73, v78, v73
	v_add_f32_e32 v78, v84, v106
	v_mul_f32_e32 v73, v73, v78
	v_mul_f32_e32 v0, v0, v79
	v_add_f32_e32 v78, v85, v106
	v_mul_f32_e32 v0, v0, v78
	v_cvt_pk_bf16_f32 v73, v73, v0
	s_waitcnt vmcnt(2)
	v_lshlrev_b32_e32 v0, 16, v102
	v_mul_f32_e32 v78, v0, v0
	v_and_b32_e32 v79, 0xffff0000, v102
	v_fmamk_f32 v78, v78, 0xbdd2d3e7, v129
	v_mul_f32_e32 v80, v79, v79
	v_mul_f32_e32 v78, v78, v0
	v_fmamk_f32 v80, v80, 0xbdd2d3e7, v129
	v_mul_f32_e32 v80, v80, v79
	v_exp_f32_e32 v78, v78
	v_exp_f32_e32 v80, v80
	global_store_dwordx2 v[66:67], v[72:73], off offset:32
	v_add_f32_e32 v78, 1.0, v78
	v_rcp_f32_e32 v78, v78
	v_add_f32_e32 v72, 1.0, v80
	v_rcp_f32_e32 v72, v72
	v_add_f32_e32 v73, v86, v106
	v_mul_f32_e32 v0, v78, v0
	v_mul_f32_e32 v0, v0, v73
	v_mul_f32_e32 v72, v72, v79
	v_add_f32_e32 v73, v87, v106
	v_mul_f32_e32 v72, v72, v73
	v_lshlrev_b32_e32 v73, 16, v103
	v_mul_f32_e32 v78, v73, v73
	v_and_b32_e32 v79, 0xffff0000, v103
	v_fmamk_f32 v78, v78, 0xbdd2d3e7, v129
	v_mul_f32_e32 v80, v79, v79
	v_mul_f32_e32 v78, v78, v73
	v_fmamk_f32 v80, v80, 0xbdd2d3e7, v129
	v_mul_f32_e32 v80, v80, v79
	v_exp_f32_e32 v78, v78
	v_exp_f32_e32 v80, v80
	v_cvt_pk_bf16_f32 v72, v0, v72
	v_add_f32_e32 v78, 1.0, v78
	v_rcp_f32_e32 v78, v78
	v_add_f32_e32 v0, 1.0, v80
	v_rcp_f32_e32 v0, v0
	global_load_dwordx2 v[74:75], v[70:71], off
	global_load_dwordx2 v[82:83], v[70:71], off offset:32
	v_mul_f32_e32 v73, v78, v73
	v_add_f32_e32 v78, v88, v106
	v_mul_f32_e32 v73, v73, v78
	v_mul_f32_e32 v0, v0, v79
	v_add_f32_e32 v78, v89, v106
	v_mul_f32_e32 v0, v0, v78
	v_cvt_pk_bf16_f32 v73, v73, v0
	s_waitcnt vmcnt(4)
	v_lshlrev_b32_e32 v0, 16, v104
	v_mul_f32_e32 v78, v0, v0
	v_and_b32_e32 v79, 0xffff0000, v104
	v_fmamk_f32 v78, v78, 0xbdd2d3e7, v129
	v_mul_f32_e32 v80, v79, v79
	v_mul_f32_e32 v78, v78, v0
	v_fmamk_f32 v80, v80, 0xbdd2d3e7, v129
	v_mul_f32_e32 v80, v80, v79
	v_exp_f32_e32 v78, v78
	v_exp_f32_e32 v80, v80
	global_store_dwordx2 v[66:67], v[72:73], off offset:64
	v_add_f32_e32 v78, 1.0, v78
	v_rcp_f32_e32 v78, v78
	v_add_f32_e32 v72, 1.0, v80
	v_rcp_f32_e32 v72, v72
	v_add_f32_e32 v73, v90, v106
	v_mul_f32_e32 v0, v78, v0
	v_mul_f32_e32 v0, v0, v73
	v_mul_f32_e32 v72, v72, v79
	v_add_f32_e32 v73, v91, v106
	v_mul_f32_e32 v72, v72, v73
	v_lshlrev_b32_e32 v73, 16, v105
	v_mul_f32_e32 v78, v73, v73
	v_and_b32_e32 v79, 0xffff0000, v105
	v_fmamk_f32 v78, v78, 0xbdd2d3e7, v129
	v_mul_f32_e32 v80, v79, v79
	v_mul_f32_e32 v78, v78, v73
	v_fmamk_f32 v80, v80, 0xbdd2d3e7, v129
	v_mul_f32_e32 v80, v80, v79
	v_exp_f32_e32 v78, v78
	v_exp_f32_e32 v80, v80
	v_cvt_pk_bf16_f32 v72, v0, v72
	v_add_f32_e32 v78, 1.0, v78
	v_rcp_f32_e32 v78, v78
	v_add_f32_e32 v0, 1.0, v80
	v_rcp_f32_e32 v0, v0
	v_mfma_f32_16x16x32_bf16 v[54:57], v[14:17], v[94:97], v[110:113]
	v_mul_f32_e32 v73, v78, v73
	v_add_f32_e32 v78, v92, v106
	v_mul_f32_e32 v73, v78, v73
	v_mul_f32_e32 v0, v0, v79
	v_add_f32_e32 v78, v93, v106
	v_mul_f32_e32 v0, v78, v0
	v_cvt_pk_bf16_f32 v73, v73, v0
	global_store_dwordx2 v[66:67], v[72:73], off offset:96
	global_load_dword v0, v76, s[12:13] offset:64
	ds_read_b128 v[78:81], v77 offset:8896
	global_load_dwordx2 v[84:85], v[70:71], off offset:64
	global_load_dwordx2 v[86:87], v[70:71], off offset:96
	v_add_co_u32_e32 v72, vcc, s4, v68
	v_mfma_f32_16x16x32_bf16 v[50:53], v[18:21], v[94:97], v[114:117]
	s_nop 0
	v_addc_co_u32_e32 v73, vcc, 0, v69, vcc
	s_waitcnt vmcnt(6)
	v_lshlrev_b32_e32 v88, 16, v74
	v_and_b32_e32 v74, 0xffff0000, v74
	v_mul_f32_e32 v71, v74, v74
	v_mul_f32_e32 v70, v88, v88
	v_fmamk_f32 v71, v71, 0xbdd2d3e7, v129
	v_fmamk_f32 v70, v70, 0xbdd2d3e7, v129
	v_mul_f32_e32 v71, v71, v74
	v_mul_f32_e32 v70, v70, v88
	v_exp_f32_e32 v89, v71
	v_exp_f32_e32 v70, v70
	v_mfma_f32_16x16x32_bf16 v[62:65], v[22:25], v[94:97], v[62:65]
	v_add_f32_e32 v89, 1.0, v89
	v_add_f32_e32 v70, 1.0, v70
	v_rcp_f32_e32 v89, v89
	v_rcp_f32_e32 v90, v70
	global_load_dwordx2 v[70:71], v[72:73], off
	s_waitcnt lgkmcnt(0)
	v_mfma_f32_16x16x32_bf16 v[38:41], v[30:33], v[78:81], v[38:41]
	v_mul_f32_e32 v74, v89, v74
	v_mul_f32_e32 v88, v90, v88
	s_waitcnt vmcnt(3)
	v_add_f32_e32 v59, v59, v0
	v_add_f32_e32 v58, v58, v0
	v_mul_f32_e32 v59, v74, v59
	v_lshlrev_b32_e32 v74, 16, v75
	v_mul_f32_e32 v58, v88, v58
	v_mul_f32_e32 v88, v74, v74
	v_fmamk_f32 v88, v88, 0xbdd2d3e7, v129
	v_mul_f32_e32 v88, v88, v74
	v_exp_f32_e32 v88, v88
	v_and_b32_e32 v75, 0xffff0000, v75
	v_mul_f32_e32 v89, v75, v75
	v_fmamk_f32 v89, v89, 0xbdd2d3e7, v129
	v_mul_f32_e32 v89, v89, v75
	v_add_f32_e32 v88, 1.0, v88
	v_rcp_f32_e32 v88, v88
	v_exp_f32_e32 v89, v89
	v_cvt_pk_bf16_f32 v58, v58, v59
	v_mul_f32_e32 v74, v88, v74
	v_lshlrev_b32_e32 v88, 16, v82
	v_and_b32_e32 v82, 0xffff0000, v82
	v_mul_f32_e32 v90, v82, v82
	v_add_f32_e32 v59, 1.0, v89
	v_mul_f32_e32 v89, v88, v88
	v_fmamk_f32 v90, v90, 0xbdd2d3e7, v129
	v_rcp_f32_e32 v59, v59
	v_fmamk_f32 v89, v89, 0xbdd2d3e7, v129
	v_mul_f32_e32 v90, v90, v82
	v_mul_f32_e32 v89, v89, v88
	v_exp_f32_e32 v90, v90
	v_add_f32_e32 v60, v60, v0
	v_mul_f32_e32 v59, v59, v75
	v_add_f32_e32 v61, v61, v0
	v_exp_f32_e32 v89, v89
	v_mul_f32_e32 v60, v74, v60
	v_mul_f32_e32 v59, v59, v61
	v_add_co_u32_e32 v74, vcc, s2, v66
	v_cvt_pk_bf16_f32 v59, v60, v59
	s_nop 0
	v_addc_co_u32_e32 v75, vcc, 0, v67, vcc
	global_store_dwordx2 v[74:75], v[58:59], off
	v_add_f32_e32 v58, 1.0, v90
	v_add_f32_e32 v89, 1.0, v89
	v_rcp_f32_e32 v58, v58
	v_rcp_f32_e32 v89, v89
	v_add_f32_e32 v55, v55, v0
	v_add_f32_e32 v54, v54, v0
	v_mul_f32_e32 v58, v58, v82
	v_mul_f32_e32 v59, v89, v88
	v_mul_f32_e32 v55, v58, v55
	v_lshlrev_b32_e32 v58, 16, v83
	v_and_b32_e32 v74, 0xffff0000, v83
	v_mul_f32_e32 v54, v59, v54
	v_mul_f32_e32 v59, v58, v58
	v_mul_f32_e32 v75, v74, v74
	v_fmamk_f32 v59, v59, 0xbdd2d3e7, v129
	v_fmamk_f32 v75, v75, 0xbdd2d3e7, v129
	v_mul_f32_e32 v59, v59, v58
	v_mul_f32_e32 v75, v75, v74
	v_exp_f32_e32 v59, v59
	v_exp_f32_e32 v75, v75
	v_cvt_pk_bf16_f32 v54, v54, v55
	v_add_f32_e32 v56, v56, v0
	v_add_f32_e32 v59, 1.0, v59
	v_add_f32_e32 v55, 1.0, v75
	v_rcp_f32_e32 v59, v59
	v_rcp_f32_e32 v55, v55
	v_add_f32_e32 v57, v57, v0
	v_lshl_add_u64 v[60:61], v[66:67], 0, s[0:1]
	v_mul_f32_e32 v58, v59, v58
	v_mul_f32_e32 v55, v55, v74
	v_mul_f32_e32 v56, v58, v56
	v_mul_f32_e32 v55, v55, v57
	s_waitcnt vmcnt(3)
	v_and_b32_e32 v58, 0xffff0000, v84
	v_cvt_pk_bf16_f32 v55, v56, v55
	v_lshlrev_b32_e32 v56, 16, v84
	v_mul_f32_e32 v59, v58, v58
	v_mul_f32_e32 v57, v56, v56
	v_fmamk_f32 v59, v59, 0xbdd2d3e7, v129
	v_fmamk_f32 v57, v57, 0xbdd2d3e7, v129
	v_mul_f32_e32 v59, v59, v58
	v_mul_f32_e32 v57, v57, v56
	v_exp_f32_e32 v59, v59
	v_exp_f32_e32 v57, v57
	global_store_dwordx2 v[60:61], v[54:55], off offset:32
	v_add_f32_e32 v51, v51, v0
	v_add_f32_e32 v54, 1.0, v59
	v_add_f32_e32 v57, 1.0, v57
	v_rcp_f32_e32 v54, v54
	v_rcp_f32_e32 v57, v57
	v_add_f32_e32 v50, v50, v0
	v_add_f32_e32 v52, v52, v0
	v_mul_f32_e32 v54, v54, v58
	v_mul_f32_e32 v55, v57, v56
	v_mul_f32_e32 v51, v54, v51
	v_lshlrev_b32_e32 v54, 16, v85
	v_and_b32_e32 v56, 0xffff0000, v85
	v_mul_f32_e32 v50, v55, v50
	v_mul_f32_e32 v55, v54, v54
	v_mul_f32_e32 v57, v56, v56
	v_fmamk_f32 v55, v55, 0xbdd2d3e7, v129
	v_fmamk_f32 v57, v57, 0xbdd2d3e7, v129
	v_mul_f32_e32 v55, v55, v54
	v_mul_f32_e32 v57, v57, v56
	v_exp_f32_e32 v55, v55
	v_exp_f32_e32 v57, v57
	v_cvt_pk_bf16_f32 v50, v50, v51
	v_add_f32_e32 v53, v53, v0
	v_add_f32_e32 v55, 1.0, v55
	v_add_f32_e32 v51, 1.0, v57
	v_rcp_f32_e32 v55, v55
	v_rcp_f32_e32 v51, v51
	s_mov_b32 s2, 0x5d000
	v_mfma_f32_16x16x32_bf16 v[34:37], v[14:17], v[78:81], v[34:37]
	v_mul_f32_e32 v54, v55, v54
	v_mul_f32_e32 v51, v51, v56
	v_mul_f32_e32 v52, v54, v52
	v_mul_f32_e32 v51, v51, v53
	v_cvt_pk_bf16_f32 v51, v52, v51
	s_waitcnt vmcnt(3)
	v_lshlrev_b32_e32 v52, 16, v86
	v_mul_f32_e32 v53, v52, v52
	v_and_b32_e32 v54, 0xffff0000, v86
	v_fmamk_f32 v53, v53, 0xbdd2d3e7, v129
	v_mul_f32_e32 v55, v54, v54
	v_mul_f32_e32 v53, v53, v52
	v_fmamk_f32 v55, v55, 0xbdd2d3e7, v129
	v_mul_f32_e32 v55, v55, v54
	v_exp_f32_e32 v53, v53
	v_exp_f32_e32 v55, v55
	global_store_dwordx2 v[60:61], v[50:51], off offset:64
	v_add_f32_e32 v53, 1.0, v53
	v_rcp_f32_e32 v53, v53
	v_add_f32_e32 v50, 1.0, v55
	v_rcp_f32_e32 v50, v50
	s_mov_b64 s[0:1], 0x3e000
	v_mul_f32_e32 v51, v53, v52
	v_add_f32_e32 v52, v62, v0
	v_mul_f32_e32 v51, v51, v52
	v_mul_f32_e32 v50, v50, v54
	v_add_f32_e32 v52, v63, v0
	v_mul_f32_e32 v50, v50, v52
	v_lshlrev_b32_e32 v52, 16, v87
	v_and_b32_e32 v54, 0xffff0000, v87
	v_mul_f32_e32 v53, v52, v52
	v_mul_f32_e32 v55, v54, v54
	v_fmamk_f32 v53, v53, 0xbdd2d3e7, v129
	v_fmamk_f32 v55, v55, 0xbdd2d3e7, v129
	v_mul_f32_e32 v53, v53, v52
	v_mul_f32_e32 v55, v55, v54
	v_exp_f32_e32 v53, v53
	v_exp_f32_e32 v55, v55
	v_cvt_pk_bf16_f32 v50, v51, v50
	v_mfma_f32_16x16x32_bf16 v[46:49], v[18:21], v[78:81], v[46:49]
	v_add_f32_e32 v53, 1.0, v53
	v_add_f32_e32 v51, 1.0, v55
	v_rcp_f32_e32 v53, v53
	v_rcp_f32_e32 v51, v51
	v_mfma_f32_16x16x32_bf16 v[42:45], v[22:25], v[78:81], v[42:45]
	v_mul_f32_e32 v52, v53, v52
	v_add_f32_e32 v53, v64, v0
	v_mul_f32_e32 v51, v51, v54
	v_add_f32_e32 v0, v65, v0
	v_mul_f32_e32 v52, v52, v53
	v_mul_f32_e32 v0, v51, v0
	v_cvt_pk_bf16_f32 v51, v52, v0
	global_store_dwordx2 v[60:61], v[50:51], off offset:96
	global_load_dword v0, v76, s[12:13] offset:128
	global_load_dwordx2 v[54:55], v[72:73], off offset:32
	ds_read_b128 v[50:53], v77 offset:13248
	global_load_dwordx2 v[56:57], v[72:73], off offset:64
	global_load_dwordx2 v[58:59], v[72:73], off offset:96
	s_waitcnt vmcnt(8)
	v_lshlrev_b32_e32 v60, 16, v70
	s_waitcnt lgkmcnt(0)
	v_mfma_f32_16x16x32_bf16 v[26:29], v[30:33], v[50:53], v[26:29]
	v_mul_f32_e32 v30, v60, v60
	v_and_b32_e32 v61, 0xffff0000, v70
	v_fmamk_f32 v30, v30, 0xbdd2d3e7, v129
	v_mul_f32_e32 v31, v61, v61
	v_mul_f32_e32 v30, v30, v60
	v_fmamk_f32 v31, v31, 0xbdd2d3e7, v129
	v_mul_f32_e32 v31, v31, v61
	v_exp_f32_e32 v30, v30
	v_exp_f32_e32 v62, v31
	v_add_co_u32_e32 v32, vcc, s2, v68
	v_add_f32_e32 v30, 1.0, v30
	v_rcp_f32_e32 v63, v30
	v_add_f32_e32 v62, 1.0, v62
	v_rcp_f32_e32 v62, v62
	v_addc_co_u32_e32 v33, vcc, 0, v69, vcc
	v_mul_f32_e32 v60, v63, v60
	global_load_dwordx2 v[30:31], v[32:33], off
	v_mfma_f32_16x16x32_bf16 v[6:9], v[14:17], v[50:53], v[6:9]
	global_load_dwordx2 v[14:15], v[32:33], off offset:32
	s_waitcnt vmcnt(5)
	v_add_f32_e32 v38, v38, v0
	v_mul_f32_e32 v38, v60, v38
	v_mul_f32_e32 v60, v62, v61
	v_and_b32_e32 v62, 0xffff0000, v71
	v_mul_f32_e32 v63, v62, v62
	v_fmamk_f32 v63, v63, 0xbdd2d3e7, v129
	v_mul_f32_e32 v63, v63, v62
	v_add_f32_e32 v39, v39, v0
	v_exp_f32_e32 v63, v63
	v_mul_f32_e32 v39, v60, v39
	v_lshlrev_b32_e32 v60, 16, v71
	v_mul_f32_e32 v61, v60, v60
	v_fmamk_f32 v61, v61, 0xbdd2d3e7, v129
	v_mul_f32_e32 v61, v61, v60
	v_cvt_pk_bf16_f32 v38, v38, v39
	v_add_f32_e32 v39, 1.0, v63
	v_rcp_f32_e32 v39, v39
	v_exp_f32_e32 v61, v61
	v_add_f32_e32 v40, v40, v0
	v_mul_f32_e32 v39, v39, v62
	s_waitcnt vmcnt(4)
	v_lshlrev_b32_e32 v62, 16, v54
	v_and_b32_e32 v54, 0xffff0000, v54
	v_mul_f32_e32 v64, v54, v54
	v_add_f32_e32 v61, 1.0, v61
	v_mul_f32_e32 v63, v62, v62
	v_fmamk_f32 v64, v64, 0xbdd2d3e7, v129
	v_rcp_f32_e32 v61, v61
	v_fmamk_f32 v63, v63, 0xbdd2d3e7, v129
	v_mul_f32_e32 v64, v64, v54
	v_mul_f32_e32 v63, v63, v62
	v_exp_f32_e32 v64, v64
	v_mul_f32_e32 v60, v61, v60
	v_add_f32_e32 v41, v41, v0
	v_exp_f32_e32 v63, v63
	v_mul_f32_e32 v40, v60, v40
	v_mul_f32_e32 v39, v39, v41
	v_add_co_u32_e32 v60, vcc, s4, v66
	v_cvt_pk_bf16_f32 v39, v40, v39
	s_nop 0
	v_addc_co_u32_e32 v61, vcc, 0, v67, vcc
	global_store_dwordx2 v[60:61], v[38:39], off
	v_add_f32_e32 v38, 1.0, v64
	v_add_f32_e32 v63, 1.0, v63
	v_rcp_f32_e32 v38, v38
	v_rcp_f32_e32 v63, v63
	v_add_f32_e32 v35, v35, v0
	v_add_f32_e32 v34, v34, v0
	v_mul_f32_e32 v38, v38, v54
	v_mul_f32_e32 v39, v63, v62
	v_mul_f32_e32 v35, v38, v35
	v_lshlrev_b32_e32 v38, 16, v55
	v_and_b32_e32 v54, 0xffff0000, v55
	v_mul_f32_e32 v34, v39, v34
	v_mul_f32_e32 v39, v38, v38
	v_mul_f32_e32 v55, v54, v54
	v_fmamk_f32 v39, v39, 0xbdd2d3e7, v129
	v_fmamk_f32 v55, v55, 0xbdd2d3e7, v129
	v_mul_f32_e32 v39, v39, v38
	v_mul_f32_e32 v55, v55, v54
	v_exp_f32_e32 v39, v39
	v_exp_f32_e32 v55, v55
	v_cvt_pk_bf16_f32 v34, v34, v35
	v_add_f32_e32 v36, v36, v0
	v_add_f32_e32 v39, 1.0, v39
	v_add_f32_e32 v35, 1.0, v55
	v_rcp_f32_e32 v39, v39
	v_rcp_f32_e32 v35, v35
	v_add_f32_e32 v37, v37, v0
	v_lshl_add_u64 v[40:41], v[66:67], 0, s[0:1]
	v_mul_f32_e32 v38, v39, v38
	v_mul_f32_e32 v35, v35, v54
	v_mul_f32_e32 v36, v38, v36
	v_mul_f32_e32 v35, v35, v37
	v_cvt_pk_bf16_f32 v35, v36, v35
	s_waitcnt vmcnt(4)
	v_lshlrev_b32_e32 v36, 16, v56
	v_mul_f32_e32 v37, v36, v36
	v_and_b32_e32 v38, 0xffff0000, v56
	v_fmamk_f32 v37, v37, 0xbdd2d3e7, v129
	v_mul_f32_e32 v39, v38, v38
	v_mul_f32_e32 v37, v37, v36
	v_fmamk_f32 v39, v39, 0xbdd2d3e7, v129
	v_mul_f32_e32 v39, v39, v38
	v_exp_f32_e32 v37, v37
	v_exp_f32_e32 v39, v39
	global_store_dwordx2 v[40:41], v[34:35], off offset:32
	v_add_f32_e32 v37, 1.0, v37
	v_rcp_f32_e32 v37, v37
	v_add_f32_e32 v34, 1.0, v39
	v_rcp_f32_e32 v34, v34
	v_mfma_f32_16x16x32_bf16 v[2:5], v[18:21], v[50:53], v[2:5]
	v_mul_f32_e32 v35, v37, v36
	v_add_f32_e32 v36, v46, v0
	v_mul_f32_e32 v35, v35, v36
	v_mul_f32_e32 v34, v34, v38
	v_add_f32_e32 v36, v47, v0
	v_mul_f32_e32 v34, v34, v36
	v_lshlrev_b32_e32 v36, 16, v57
	v_mul_f32_e32 v37, v36, v36
	v_and_b32_e32 v38, 0xffff0000, v57
	v_fmamk_f32 v37, v37, 0xbdd2d3e7, v129
	v_mul_f32_e32 v39, v38, v38
	v_mul_f32_e32 v37, v37, v36
	v_fmamk_f32 v39, v39, 0xbdd2d3e7, v129
	v_mul_f32_e32 v39, v39, v38
	v_exp_f32_e32 v37, v37
	v_exp_f32_e32 v39, v39
	v_cvt_pk_bf16_f32 v34, v35, v34
	v_add_f32_e32 v37, 1.0, v37
	v_rcp_f32_e32 v37, v37
	v_add_f32_e32 v35, 1.0, v39
	v_rcp_f32_e32 v35, v35
	s_waitcnt vmcnt(3)
	v_lshlrev_b32_e32 v20, 16, v30
	v_mul_f32_e32 v36, v37, v36
	v_add_f32_e32 v37, v48, v0
	v_mul_f32_e32 v36, v36, v37
	v_mul_f32_e32 v35, v35, v38
	v_add_f32_e32 v37, v49, v0
	v_mul_f32_e32 v35, v35, v37
	v_cvt_pk_bf16_f32 v35, v36, v35
	v_lshlrev_b32_e32 v36, 16, v58
	v_mul_f32_e32 v37, v36, v36
	v_and_b32_e32 v38, 0xffff0000, v58
	v_fmamk_f32 v37, v37, 0xbdd2d3e7, v129
	v_mul_f32_e32 v39, v38, v38
	v_mul_f32_e32 v37, v37, v36
	v_fmamk_f32 v39, v39, 0xbdd2d3e7, v129
	v_mul_f32_e32 v39, v39, v38
	v_exp_f32_e32 v37, v37
	v_exp_f32_e32 v39, v39
	global_store_dwordx2 v[40:41], v[34:35], off offset:64
	v_add_f32_e32 v37, 1.0, v37
	v_rcp_f32_e32 v37, v37
	v_add_f32_e32 v34, 1.0, v39
	v_rcp_f32_e32 v34, v34
	v_mul_f32_e32 v21, v20, v20
	v_mul_f32_e32 v35, v37, v36
	v_add_f32_e32 v36, v42, v0
	v_mul_f32_e32 v35, v35, v36
	v_mul_f32_e32 v34, v34, v38
	v_add_f32_e32 v36, v43, v0
	v_mul_f32_e32 v34, v34, v36
	v_lshlrev_b32_e32 v36, 16, v59
	v_and_b32_e32 v38, 0xffff0000, v59
	v_mul_f32_e32 v37, v36, v36
	v_mul_f32_e32 v39, v38, v38
	v_fmamk_f32 v37, v37, 0xbdd2d3e7, v129
	v_fmamk_f32 v39, v39, 0xbdd2d3e7, v129
	v_mul_f32_e32 v37, v37, v36
	v_mul_f32_e32 v39, v39, v38
	v_exp_f32_e32 v37, v37
	v_exp_f32_e32 v39, v39
	v_cvt_pk_bf16_f32 v34, v35, v34
	v_and_b32_e32 v30, 0xffff0000, v30
	v_add_f32_e32 v37, 1.0, v37
	v_add_f32_e32 v35, 1.0, v39
	v_rcp_f32_e32 v37, v37
	v_rcp_f32_e32 v35, v35
	v_fmamk_f32 v21, v21, 0xbdd2d3e7, v129
	v_mul_f32_e32 v21, v21, v20
	v_mul_f32_e32 v36, v37, v36
	v_add_f32_e32 v37, v44, v0
	v_mul_f32_e32 v35, v35, v38
	v_add_f32_e32 v0, v45, v0
	v_mul_f32_e32 v36, v36, v37
	v_mul_f32_e32 v0, v35, v0
	v_cvt_pk_bf16_f32 v35, v36, v0
	global_store_dwordx2 v[40:41], v[34:35], off offset:96
	global_load_dword v0, v76, s[12:13] offset:192
	global_load_dwordx2 v[16:17], v[32:33], off offset:64
	global_load_dwordx2 v[18:19], v[32:33], off offset:96
	v_mul_f32_e32 v32, v30, v30
	v_fmamk_f32 v32, v32, 0xbdd2d3e7, v129
	v_mul_f32_e32 v32, v32, v30
	v_exp_f32_e32 v21, v21
	v_exp_f32_e32 v32, v32
	v_mfma_f32_16x16x32_bf16 v[10:13], v[22:25], v[50:53], v[10:13]
	v_add_f32_e32 v21, 1.0, v21
	v_rcp_f32_e32 v21, v21
	v_add_f32_e32 v22, 1.0, v32
	v_rcp_f32_e32 v22, v22
	v_and_b32_e32 v24, 0xffff0000, v31
	v_mul_f32_e32 v20, v21, v20
	v_mul_f32_e32 v25, v24, v24
	v_fmamk_f32 v25, v25, 0xbdd2d3e7, v129
	v_mul_f32_e32 v25, v25, v24
	v_exp_f32_e32 v25, v25
	s_mov_b64 s[0:1], 0x5d000
	s_waitcnt vmcnt(2)
	v_add_f32_e32 v21, v26, v0
	v_mul_f32_e32 v20, v20, v21
	v_mul_f32_e32 v21, v22, v30
	v_add_f32_e32 v22, v27, v0
	v_mul_f32_e32 v21, v21, v22
	v_lshlrev_b32_e32 v22, 16, v31
	v_mul_f32_e32 v23, v22, v22
	v_fmamk_f32 v23, v23, 0xbdd2d3e7, v129
	v_mul_f32_e32 v23, v23, v22
	v_exp_f32_e32 v23, v23
	v_lshlrev_b32_e32 v26, 16, v14
	v_and_b32_e32 v14, 0xffff0000, v14
	v_cvt_pk_bf16_f32 v20, v20, v21
	v_add_f32_e32 v23, 1.0, v23
	v_rcp_f32_e32 v23, v23
	v_add_f32_e32 v21, 1.0, v25
	v_mul_f32_e32 v27, v26, v26
	v_rcp_f32_e32 v21, v21
	v_mul_f32_e32 v22, v23, v22
	v_add_f32_e32 v23, v28, v0
	v_mul_f32_e32 v28, v14, v14
	v_fmamk_f32 v28, v28, 0xbdd2d3e7, v129
	v_fmamk_f32 v27, v27, 0xbdd2d3e7, v129
	v_mul_f32_e32 v28, v28, v14
	v_mul_f32_e32 v27, v27, v26
	v_exp_f32_e32 v28, v28
	v_mul_f32_e32 v22, v22, v23
	v_mul_f32_e32 v21, v21, v24
	v_add_f32_e32 v23, v29, v0
	v_exp_f32_e32 v27, v27
	v_mul_f32_e32 v21, v21, v23
	v_add_co_u32_e32 v24, vcc, s2, v66
	v_cvt_pk_bf16_f32 v21, v22, v21
	s_nop 0
	v_addc_co_u32_e32 v25, vcc, 0, v67, vcc
	global_store_dwordx2 v[24:25], v[20:21], off
	v_add_f32_e32 v20, 1.0, v28
	v_add_f32_e32 v27, 1.0, v27
	v_rcp_f32_e32 v20, v20
	v_rcp_f32_e32 v27, v27
	v_add_f32_e32 v7, v7, v0
	v_add_f32_e32 v6, v6, v0
	v_mul_f32_e32 v14, v20, v14
	v_mul_f32_e32 v21, v27, v26
	v_mul_f32_e32 v7, v14, v7
	v_lshlrev_b32_e32 v14, 16, v15
	v_and_b32_e32 v15, 0xffff0000, v15
	v_mul_f32_e32 v6, v21, v6
	v_mul_f32_e32 v20, v14, v14
	v_mul_f32_e32 v21, v15, v15
	v_fmamk_f32 v20, v20, 0xbdd2d3e7, v129
	v_fmamk_f32 v21, v21, 0xbdd2d3e7, v129
	v_mul_f32_e32 v20, v20, v14
	v_mul_f32_e32 v21, v21, v15
	v_exp_f32_e32 v20, v20
	v_exp_f32_e32 v21, v21
	v_cvt_pk_bf16_f32 v6, v6, v7
	v_add_f32_e32 v8, v8, v0
	v_add_f32_e32 v20, 1.0, v20
	v_add_f32_e32 v7, 1.0, v21
	v_rcp_f32_e32 v20, v20
	v_rcp_f32_e32 v7, v7
	v_add_f32_e32 v9, v9, v0
	v_lshl_add_u64 v[22:23], v[66:67], 0, s[0:1]
	v_mul_f32_e32 v14, v20, v14
	v_mul_f32_e32 v7, v7, v15
	v_mul_f32_e32 v8, v14, v8
	v_mul_f32_e32 v7, v7, v9
	s_waitcnt vmcnt(2)
	v_and_b32_e32 v14, 0xffff0000, v16
	v_cvt_pk_bf16_f32 v7, v8, v7
	v_lshlrev_b32_e32 v8, 16, v16
	v_mul_f32_e32 v15, v14, v14
	v_mul_f32_e32 v9, v8, v8
	v_fmamk_f32 v15, v15, 0xbdd2d3e7, v129
	v_fmamk_f32 v9, v9, 0xbdd2d3e7, v129
	v_mul_f32_e32 v15, v15, v14
	v_mul_f32_e32 v9, v9, v8
	v_exp_f32_e32 v15, v15
	v_exp_f32_e32 v9, v9
	global_store_dwordx2 v[22:23], v[6:7], off offset:32
	v_add_f32_e32 v3, v3, v0
	v_add_f32_e32 v6, 1.0, v15
	v_add_f32_e32 v9, 1.0, v9
	v_rcp_f32_e32 v6, v6
	v_rcp_f32_e32 v9, v9
	v_add_f32_e32 v2, v2, v0
	v_add_f32_e32 v4, v4, v0
	v_mul_f32_e32 v6, v6, v14
	v_mul_f32_e32 v7, v9, v8
	v_mul_f32_e32 v3, v6, v3
	v_lshlrev_b32_e32 v6, 16, v17
	v_and_b32_e32 v8, 0xffff0000, v17
	v_mul_f32_e32 v2, v7, v2
	v_mul_f32_e32 v7, v6, v6
	v_mul_f32_e32 v9, v8, v8
	v_fmamk_f32 v7, v7, 0xbdd2d3e7, v129
	v_fmamk_f32 v9, v9, 0xbdd2d3e7, v129
	v_mul_f32_e32 v7, v7, v6
	v_mul_f32_e32 v9, v9, v8
	v_exp_f32_e32 v7, v7
	v_exp_f32_e32 v9, v9
	v_cvt_pk_bf16_f32 v2, v2, v3
	v_add_f32_e32 v5, v5, v0
	v_add_f32_e32 v7, 1.0, v7
	v_add_f32_e32 v3, 1.0, v9
	v_rcp_f32_e32 v7, v7
	v_rcp_f32_e32 v3, v3
	s_lshl_b32 s0, s38, 6
	s_and_b32 s2, s0, 0x3fc0
	v_mul_f32_e32 v6, v7, v6
	v_mul_f32_e32 v3, v3, v8
	v_mul_f32_e32 v4, v6, v4
	v_mul_f32_e32 v3, v3, v5
	v_cvt_pk_bf16_f32 v3, v4, v3
	s_waitcnt vmcnt(2)
	v_lshlrev_b32_e32 v4, 16, v18
	v_mul_f32_e32 v5, v4, v4
	v_and_b32_e32 v6, 0xffff0000, v18
	v_fmamk_f32 v5, v5, 0xbdd2d3e7, v129
	v_mul_f32_e32 v7, v6, v6
	v_mul_f32_e32 v5, v5, v4
	v_fmamk_f32 v7, v7, 0xbdd2d3e7, v129
	v_mul_f32_e32 v7, v7, v6
	v_exp_f32_e32 v5, v5
	v_exp_f32_e32 v7, v7
	global_store_dwordx2 v[22:23], v[2:3], off offset:64
	v_add_f32_e32 v5, 1.0, v5
	v_rcp_f32_e32 v5, v5
	v_add_f32_e32 v2, 1.0, v7
	v_rcp_f32_e32 v2, v2
	s_lshr_b32 s0, s38, 2
	v_mul_f32_e32 v3, v5, v4
	v_add_f32_e32 v4, v10, v0
	v_mul_f32_e32 v3, v3, v4
	v_mul_f32_e32 v2, v2, v6
	v_add_f32_e32 v4, v11, v0
	v_mul_f32_e32 v2, v2, v4
	v_lshlrev_b32_e32 v4, 16, v19
	v_and_b32_e32 v6, 0xffff0000, v19
	v_mul_f32_e32 v5, v4, v4
	v_mul_f32_e32 v7, v6, v6
	v_fmamk_f32 v5, v5, 0xbdd2d3e7, v129
	v_fmamk_f32 v7, v7, 0xbdd2d3e7, v129
	v_mul_f32_e32 v5, v5, v4
	v_mul_f32_e32 v7, v7, v6
	v_exp_f32_e32 v5, v5
	v_exp_f32_e32 v7, v7
	v_cvt_pk_bf16_f32 v2, v3, v2
	s_and_b32 s4, s0, 64
	v_add_f32_e32 v5, 1.0, v5
	v_add_f32_e32 v3, 1.0, v7
	v_rcp_f32_e32 v5, v5
	v_rcp_f32_e32 v3, v3
	s_lshl_b32 s88, s4, 1
	s_mov_b64 s[0:1], 0x1b00
	v_mul_f32_e32 v4, v5, v4
	v_add_f32_e32 v5, v12, v0
	v_mul_f32_e32 v3, v3, v6
	v_add_f32_e32 v0, v13, v0
	v_mul_f32_e32 v4, v4, v5
	v_mul_f32_e32 v0, v3, v0
	v_cvt_pk_bf16_f32 v3, v4, v0
	v_mov_b32_e32 v0, v194
	global_store_dwordx2 v[22:23], v[2:3], off offset:96
	s_barrier
	s_nop 0
	v_bfe_u32 v12, v0, 2, 6
	v_lshlrev_b32_e32 v0, 4, v0
	v_and_b32_e32 v10, 48, v0
	v_or_b32_e32 v0, s2, v12
	v_mul_u32_u24_e32 v0, 0xf80, v0
	v_lshlrev_b32_e32 v0, 1, v0
	v_lshl_add_u64 v[2:3], s[46:47], 0, v[0:1]
	v_lshl_add_u64 v[2:3], v[2:3], 0, s[88:89]
	v_lshlrev_b32_e32 v0, 1, v10
	v_lshl_add_u64 v[6:7], v[2:3], 0, v[0:1]
	v_add_co_u32_e32 v2, vcc, s68, v6
	v_mul_u32_u24_e32 v10, 0x48, v10
	s_nop 0
	v_addc_co_u32_e32 v3, vcc, 0, v7, vcc
	global_load_dwordx4 v[2:5], v[2:3], off offset:2816
	v_lshl_add_u64 v[6:7], v[6:7], 0, s[0:1]
	global_load_dwordx4 v[6:9], v[6:7], off offset:16
	v_lshlrev_b32_e32 v10, 1, v10
	v_lshlrev_b32_e32 v11, 1, v12
	v_add3_u32 v13, s15, v10, v11
	v_add3_u32 v10, s15, v11, v10
	s_lshl_b32 s88, s2, 1
	s_waitcnt vmcnt(1)
	ds_write_b16 v13, v2
	ds_write_b16_d16_hi v10, v2 offset:144
	ds_write_b16 v13, v3 offset:288
	ds_write_b16_d16_hi v10, v3 offset:432
	ds_write_b16 v13, v4 offset:576
	ds_write_b16_d16_hi v10, v4 offset:720
	ds_write_b16 v13, v5 offset:864
	ds_write_b16_d16_hi v10, v5 offset:1008
	s_waitcnt vmcnt(0)
	ds_write_b16 v13, v6 offset:1152
	ds_write_b16_d16_hi v10, v6 offset:1296
	ds_write_b16 v13, v7 offset:1440
	ds_write_b16_d16_hi v10, v7 offset:1584
	ds_write_b16 v13, v8 offset:1728
	ds_write_b16_d16_hi v10, v8 offset:1872
	ds_write_b16 v13, v9 offset:2016
	ds_write_b16_d16_hi v10, v9 offset:2160
	v_or_b32_e32 v2, s4, v12
	v_lshlrev_b32_e32 v2, 15, v2
	v_mov_b32_e32 v3, v1
	v_lshl_add_u64 v[10:11], s[48:49], 0, v[2:3]
	v_mul_u32_u24_e32 v2, 0x90, v12
	v_add3_u32 v6, s15, v2, v0
	s_waitcnt lgkmcnt(0)
	s_barrier
	ds_read_b128 v[2:5], v6
	ds_read_b128 v[6:9], v6 offset:16
	v_lshl_add_u64 v[10:11], v[10:11], 0, s[88:89]
	v_lshl_add_u64 v[10:11], v[10:11], 0, v[0:1]
	s_mov_b64 s[4:5], -1
	s_waitcnt lgkmcnt(1)
	global_store_dwordx4 v[10:11], v[2:5], off
	s_waitcnt lgkmcnt(0)
	global_store_dwordx4 v[10:11], v[6:9], off offset:16
	s_barrier
